# v38: v37 + tile-end store drain (vmcnt(0)) removed in G2/G3/G5 tile loops
# speedup vs baseline: 1.0494x; 1.0027x over previous
; DI float sigmoidf_(float x) { return __builtin_amdgcn_rcpf(1.0f + __expf(-x)); }
; DI float siluf_(float x) { return x * sigmoidf_(x); }
; template <class FL, class FS>
; DI void gemm8_tile(char* shmc, const bf16_t* __restrict__ A, const bf16_t* __restrict__ Bt, const int K, const int brow, const int bcol, FL fl, FS fs) {
;     ...
; #pragma unroll
;   for (int ai = 0; ai < 2; ++ai)
; #pragma unroll
;     for (int mh = 0; mh < 2; ++mh) {
;       decltype(fl(0, 0)) ld[2][2][2];
; #pragma unroll
;       for (int mm = 0; mm < 2; ++mm)
; #pragma unroll
;         for (int bj = 0; bj < 2; ++bj)
; #pragma unroll
;           for (int n = 0; n < 2; ++n) ld[mm][bj][n] = fl(brow + ai * HALF + wr * 64 + (2 * mh + mm) * 16 + fr, bcol + bj * HALF + wc * 32 + n * 16 + 4 * fq);
; #pragma unroll
;       for (int mm = 0; mm < 2; ++mm)
; #pragma unroll
;         for (int bj = 0; bj < 2; ++bj)
; #pragma unroll
;           for (int n = 0; n < 2; ++n) fs(brow + ai * HALF + wr * 64 + (2 * mh + mm) * 16 + fr, bcol + bj * HALF + wc * 32 + n * 16 + 4 * fq, acc[ai][bj][2 * mh + mm][n], ld[mm][bj][n]);
; DI void phase_g2(const Params& p, const Sub& s, char* lds_all) {
;     ...
;       [&](int row, int col) { const size_t o = (size_t)row * D + col; Ld2 r; const uint2 a = *(const uint2*)(A + o), b = *(const uint2*)(z + o);
;         r.a.x = __uint_as_float(a.x); r.a.y = __uint_as_float(a.y); r.a.z = __uint_as_float(b.x); r.a.w = __uint_as_float(b.y); r.b = *(const float4*)(p.s5_b_glu + col); return r; },
;       [&](int row, int col, f32x4 v, const Ld2& l2) {
;         uint4 ld; ld.x = __float_as_uint(l2.a.x); ld.y = __float_as_uint(l2.a.y); ld.z = __float_as_uint(l2.a.z); ld.w = __float_as_uint(l2.a.w);
;         const size_t o = (size_t)row * D + col;
;         const float y0 = __uint_as_float(ld.x << 16), y1 = __uint_as_float(ld.x & 0xffff0000u), y2_ = __uint_as_float(ld.y << 16), y3 = __uint_as_float(ld.y & 0xffff0000u);
;         const float z0 = __uint_as_float(ld.z << 16), z1 = __uint_as_float(ld.z & 0xffff0000u), z2 = __uint_as_float(ld.w << 16), z3 = __uint_as_float(ld.w & 0xffff0000u);
;         const float4 b4 = l2.b;
;         st_bf4(y2 + o, y0 * sigmoidf_(v[0] + b4.x) * siluf_(z0), y1 * sigmoidf_(v[1] + b4.y) * siluf_(z1),
;                y2_ * sigmoidf_(v[2] + b4.z) * siluf_(z2), y3 * sigmoidf_(v[3] + b4.w) * siluf_(z3));
;       });
.LBB0_683:
	s_or_b64 exec, exec, s[0:1]
	v_or_b32_e32 v108, s42, v147
	v_add_u32_e32 v148, v108, v148
	v_lshlrev_b32_e32 v108, 5, v145
	v_lshlrev_b32_e32 v109, 2, v146
	v_or3_b32 v146, v108, v109, s40
	v_ashrrev_i32_e32 v147, 31, v146
	v_lshl_add_u64 v[154:155], v[146:147], 2, s[8:9]
	global_load_dwordx4 v[128:131], v[154:155], off
	global_load_dwordx4 v[124:127], v[154:155], off offset:64
	v_ashrrev_i32_e32 v149, 31, v148
	v_lshlrev_b64 v[108:109], 10, v[148:149]
	v_lshl_add_u64 v[110:111], v[108:109], 0, v[146:147]
	v_lshlrev_b64 v[110:111], 1, v[110:111]
	v_lshl_add_u64 v[116:117], s[10:11], 0, v[110:111]
	v_lshl_add_u64 v[110:111], s[12:13], 0, v[110:111]
	global_load_dwordx2 v[186:187], v[116:117], off
	global_load_dwordx2 v[188:189], v[110:111], off
	v_or_b32_e32 v152, 16, v146
	v_ashrrev_i32_e32 v153, 31, v152
	v_lshlrev_b64 v[158:159], 11, v[148:149]
	v_lshl_add_u64 v[160:161], v[108:109], 0, v[152:153]
	v_or_b32_e32 v150, 0x80, v146
	v_or_b32_e32 v156, 0x90, v146
	v_lshlrev_b64 v[144:145], 1, v[146:147]
	v_lshl_add_u64 v[158:159], s[14:15], 0, v[158:159]
	v_lshlrev_b64 v[160:161], 1, v[160:161]
	v_ashrrev_i32_e32 v151, 31, v150
	v_ashrrev_i32_e32 v157, 31, v156
	v_lshl_add_u64 v[172:173], v[158:159], 0, v[144:145]
	v_lshl_add_u64 v[158:159], s[10:11], 0, v[160:161]
	v_lshl_add_u64 v[160:161], s[12:13], 0, v[160:161]
	v_lshl_add_u64 v[162:163], v[108:109], 0, v[150:151]
	v_lshl_add_u64 v[164:165], v[108:109], 0, v[156:157]
	global_load_dwordx4 v[116:119], v[154:155], off offset:512
	global_load_dwordx4 v[108:111], v[154:155], off offset:576
	global_load_dwordx2 v[190:191], v[158:159], off
	global_load_dwordx2 v[192:193], v[160:161], off
	v_lshlrev_b64 v[162:163], 1, v[162:163]
	v_lshl_add_u64 v[178:179], s[10:11], 0, v[162:163]
	v_lshl_add_u64 v[162:163], s[12:13], 0, v[162:163]
	global_load_dwordx2 v[194:195], v[178:179], off
	global_load_dwordx2 v[196:197], v[162:163], off
	v_or_b32_e32 v170, 16, v148
	v_ashrrev_i32_e32 v171, 31, v170
	v_lshlrev_b64 v[166:167], 10, v[170:171]
	v_lshlrev_b64 v[164:165], 1, v[164:165]
	v_lshl_add_u64 v[168:169], v[166:167], 0, v[146:147]
	v_lshl_add_u64 v[176:177], v[166:167], 0, v[150:151]
	v_lshl_add_u64 v[174:175], v[166:167], 0, v[152:153]
	v_lshl_add_u64 v[166:167], v[166:167], 0, v[156:157]
	v_lshl_add_u64 v[180:181], s[10:11], 0, v[164:165]
	v_lshl_add_u64 v[158:159], s[12:13], 0, v[164:165]
	v_lshlrev_b64 v[164:165], 1, v[168:169]
	v_lshlrev_b64 v[160:161], 1, v[176:177]
	v_lshlrev_b64 v[168:169], 1, v[174:175]
	v_lshlrev_b64 v[166:167], 1, v[166:167]
	v_lshl_add_u64 v[162:163], s[10:11], 0, v[164:165]
	v_lshl_add_u64 v[164:165], s[12:13], 0, v[164:165]
	v_lshl_add_u64 v[202:203], s[10:11], 0, v[160:161]
	v_lshl_add_u64 v[160:161], s[12:13], 0, v[160:161]
	v_lshl_add_u64 v[198:199], s[10:11], 0, v[168:169]
	v_lshl_add_u64 v[200:201], s[12:13], 0, v[168:169]
	v_lshl_add_u64 v[204:205], s[10:11], 0, v[166:167]
	v_lshl_add_u64 v[206:207], s[12:13], 0, v[166:167]
	global_load_dwordx2 v[180:181], v[180:181], off
	s_nop 0
	global_load_dwordx2 v[178:179], v[158:159], off
	global_load_dwordx2 v[176:177], v[162:163], off
	global_load_dwordx2 v[174:175], v[164:165], off
	global_load_dwordx2 v[168:169], v[198:199], off
	global_load_dwordx2 v[166:167], v[200:201], off
	s_nop 0
	global_load_dwordx2 v[164:165], v[202:203], off
	global_load_dwordx2 v[162:163], v[160:161], off
	s_nop 0
	global_load_dwordx2 v[160:161], v[204:205], off
	global_load_dwordx2 v[158:159], v[206:207], off
	v_readlane_b32 s0, v251, 1
	s_add_i32 s53, s53, s0
	s_cmpk_lt_i32 s53, 0x400
	v_readlane_b32 s1, v251, 2
	s_waitcnt vmcnt(19)
	v_add_f32_e32 v140, v140, v128
	v_add_f32_e32 v141, v141, v129
	v_mul_f32_e32 v140, 0xbfb8aa3b, v140
	v_mul_f32_e32 v141, 0xbfb8aa3b, v141
	v_exp_f32_e32 v149, v140
	v_exp_f32_e32 v185, v141
	v_add_f32_e32 v142, v142, v130
	v_add_f32_e32 v143, v143, v131
	v_add_f32_e32 v149, 1.0, v149
	s_waitcnt vmcnt(16)
	v_lshlrev_b32_e32 v198, 16, v188
	v_and_b32_e32 v199, 0xffff0000, v188
	v_mul_f32_e32 v201, 0xbfb8aa3b, v198
	v_add_f32_e32 v185, 1.0, v185
	v_rcp_f32_e32 v200, v149
	v_exp_f32_e32 v149, v201
	v_rcp_f32_e32 v201, v185
	v_mul_f32_e32 v185, 0xbfb8aa3b, v199
	v_exp_f32_e32 v185, v185
	v_add_f32_e32 v149, 1.0, v149
	v_lshlrev_b32_e32 v188, 16, v189
	v_rcp_f32_e32 v202, v149
	v_add_f32_e32 v149, 1.0, v185
	v_and_b32_e32 v189, 0xffff0000, v189
	v_rcp_f32_e32 v203, v149
	v_mul_f32_e32 v149, 0xbfb8aa3b, v188
	v_mul_f32_e32 v142, 0xbfb8aa3b, v142
	v_mul_f32_e32 v143, 0xbfb8aa3b, v143
	v_exp_f32_e32 v149, v149
	v_mul_f32_e32 v185, 0xbfb8aa3b, v189
	v_exp_f32_e32 v142, v142
	v_exp_f32_e32 v143, v143
	v_exp_f32_e32 v185, v185
	v_lshlrev_b32_e32 v140, 16, v186
	v_and_b32_e32 v141, 0xffff0000, v186
	v_add_f32_e32 v149, 1.0, v149
	v_pk_mul_f32 v[140:141], v[200:201], v[140:141]
	v_add_f32_e32 v142, 1.0, v142
	v_add_f32_e32 v143, 1.0, v143
	v_rcp_f32_e32 v200, v149
	v_add_f32_e32 v149, 1.0, v185
	v_rcp_f32_e32 v142, v142
	v_rcp_f32_e32 v143, v143
	v_rcp_f32_e32 v201, v149
	v_add_f32_e32 v136, v136, v124
	v_add_f32_e32 v137, v137, v125
	v_mul_f32_e32 v136, 0xbfb8aa3b, v136
	v_mul_f32_e32 v137, 0xbfb8aa3b, v137
	v_exp_f32_e32 v136, v136
	v_exp_f32_e32 v137, v137
	v_lshlrev_b32_e32 v186, 16, v187
	v_and_b32_e32 v187, 0xffff0000, v187
	v_pk_mul_f32 v[142:143], v[142:143], v[186:187]
	v_pk_mul_f32 v[186:187], v[200:201], v[188:189]
	v_add_f32_e32 v136, 1.0, v136
	v_pk_mul_f32 v[142:143], v[186:187], v[142:143]
	s_waitcnt vmcnt(12)
; DI float sigmoidf_(float x) { return __builtin_amdgcn_rcpf(1.0f + __expf(-x)); }
; DI float siluf_(float x) { return x * sigmoidf_(x); }
; DI void st_bf4(bf16_t* p, float a, float b, float c, float d) { uint2 v; v.x = pack2(a, b); v.y = pack2(c, d); *(uint2*)p = v; }
; DI void phase_g2(const Params& p, const Sub& s, char* lds_all) {
;     ...
;       [&](int row, int col) { const size_t o = (size_t)row * D + col; Ld2 r; const uint2 a = *(const uint2*)(A + o), b = *(const uint2*)(z + o);
;         r.a.x = __uint_as_float(a.x); r.a.y = __uint_as_float(a.y); r.a.z = __uint_as_float(b.x); r.a.w = __uint_as_float(b.y); r.b = *(const float4*)(p.s5_b_glu + col); return r; },
;       [&](int row, int col, f32x4 v, const Ld2& l2) {
;         uint4 ld; ld.x = __float_as_uint(l2.a.x); ld.y = __float_as_uint(l2.a.y); ld.z = __float_as_uint(l2.a.z); ld.w = __float_as_uint(l2.a.w);
;         const size_t o = (size_t)row * D + col;
;         const float y0 = __uint_as_float(ld.x << 16), y1 = __uint_as_float(ld.x & 0xffff0000u), y2_ = __uint_as_float(ld.y << 16), y3 = __uint_as_float(ld.y & 0xffff0000u);
;         const float z0 = __uint_as_float(ld.z << 16), z1 = __uint_as_float(ld.z & 0xffff0000u), z2 = __uint_as_float(ld.w << 16), z3 = __uint_as_float(ld.w & 0xffff0000u);
;         const float4 b4 = l2.b;
;         st_bf4(y2 + o, y0 * sigmoidf_(v[0] + b4.x) * siluf_(z0), y1 * sigmoidf_(v[1] + b4.y) * siluf_(z1),
;                y2_ * sigmoidf_(v[2] + b4.z) * siluf_(z2), y3 * sigmoidf_(v[3] + b4.w) * siluf_(z3));
;       });
	v_and_b32_e32 v187, 0xffff0000, v192
	v_add_f32_e32 v137, 1.0, v137
	v_mul_f32_e32 v185, 0xbfb8aa3b, v187
	v_pk_mul_f32 v[198:199], v[202:203], v[198:199]
	v_rcp_f32_e32 v136, v136
	v_rcp_f32_e32 v137, v137
	v_exp_f32_e32 v185, v185
	v_pk_mul_f32 v[140:141], v[198:199], v[140:141]
	v_lshlrev_b32_e32 v188, 16, v193
	v_cvt_pk_bf16_f32 v140, v140, v141
	v_cvt_pk_bf16_f32 v141, v142, v143
	global_store_dwordx2 v[172:173], v[140:141], off
	v_lshlrev_b32_e32 v140, 16, v190
	v_and_b32_e32 v141, 0xffff0000, v190
	v_and_b32_e32 v189, 0xffff0000, v193
	v_pk_mul_f32 v[136:137], v[136:137], v[140:141]
	v_add_f32_e32 v140, 1.0, v185
	v_add_f32_e32 v138, v138, v126
	v_add_f32_e32 v139, v139, v127
	v_lshlrev_b32_e32 v142, 16, v191
	v_and_b32_e32 v143, 0xffff0000, v191
	v_mul_f32_e32 v138, 0xbfb8aa3b, v138
	v_mul_f32_e32 v139, 0xbfb8aa3b, v139
	v_rcp_f32_e32 v191, v140
	v_mul_f32_e32 v140, 0xbfb8aa3b, v188
	v_mul_f32_e32 v141, 0xbfb8aa3b, v189
	v_exp_f32_e32 v138, v138
	v_exp_f32_e32 v139, v139
	v_exp_f32_e32 v140, v140
	v_exp_f32_e32 v141, v141
	v_lshlrev_b32_e32 v186, 16, v192
	v_mul_f32_e32 v149, 0xbfb8aa3b, v186
	v_exp_f32_e32 v149, v149
	v_add_f32_e32 v138, 1.0, v138
	v_add_f32_e32 v139, 1.0, v139
	v_add_f32_e32 v140, 1.0, v140
	v_add_f32_e32 v141, 1.0, v141
	v_rcp_f32_e32 v138, v138
	v_rcp_f32_e32 v139, v139
	v_rcp_f32_e32 v140, v140
	v_rcp_f32_e32 v141, v141
	v_add_f32_e32 v132, v132, v116
	v_add_f32_e32 v133, v133, v117
	v_mul_f32_e32 v132, 0xbfb8aa3b, v132
	v_mul_f32_e32 v133, 0xbfb8aa3b, v133
	v_add_f32_e32 v149, 1.0, v149
	v_exp_f32_e32 v132, v132
	v_exp_f32_e32 v133, v133
	v_rcp_f32_e32 v190, v149
	v_pk_mul_f32 v[138:139], v[138:139], v[142:143]
	v_pk_mul_f32 v[140:141], v[140:141], v[188:189]
	v_add_f32_e32 v132, 1.0, v132
	v_pk_mul_f32 v[138:139], v[140:141], v[138:139]
	s_waitcnt vmcnt(11)
	v_and_b32_e32 v141, 0xffff0000, v196
	v_add_f32_e32 v133, 1.0, v133
	v_mul_f32_e32 v185, 0xbfb8aa3b, v141
	v_pk_mul_f32 v[186:187], v[190:191], v[186:187]
	v_rcp_f32_e32 v132, v132
	v_rcp_f32_e32 v133, v133
	v_exp_f32_e32 v185, v185
	v_pk_mul_f32 v[136:137], v[186:187], v[136:137]
	v_lshlrev_b32_e32 v142, 16, v197
	v_cvt_pk_bf16_f32 v136, v136, v137
	v_cvt_pk_bf16_f32 v137, v138, v139
	global_store_dwordx2 v[172:173], v[136:137], off offset:32
	v_lshlrev_b32_e32 v136, 16, v194
	v_and_b32_e32 v137, 0xffff0000, v194
	v_and_b32_e32 v143, 0xffff0000, v197
	v_pk_mul_f32 v[132:133], v[132:133], v[136:137]
	v_add_f32_e32 v136, 1.0, v185
	v_add_f32_e32 v134, v134, v118
	v_add_f32_e32 v135, v135, v119
	v_lshlrev_b32_e32 v140, 16, v196
	v_mul_f32_e32 v134, 0xbfb8aa3b, v134
	v_mul_f32_e32 v135, 0xbfb8aa3b, v135
	v_rcp_f32_e32 v187, v136
	v_mul_f32_e32 v136, 0xbfb8aa3b, v142
	v_mul_f32_e32 v137, 0xbfb8aa3b, v143
	v_mul_f32_e32 v149, 0xbfb8aa3b, v140
	v_exp_f32_e32 v134, v134
	v_exp_f32_e32 v135, v135
	v_exp_f32_e32 v136, v136
	v_exp_f32_e32 v137, v137
	v_exp_f32_e32 v149, v149
	v_add_f32_e32 v134, 1.0, v134
	v_add_f32_e32 v135, 1.0, v135
	v_add_f32_e32 v136, 1.0, v136
	v_add_f32_e32 v137, 1.0, v137
	v_add_f32_e32 v149, 1.0, v149
	v_rcp_f32_e32 v134, v134
	v_rcp_f32_e32 v135, v135
	v_rcp_f32_e32 v136, v136
	v_rcp_f32_e32 v137, v137
	v_add_f32_e32 v120, v120, v108
	v_add_f32_e32 v121, v121, v109
	v_rcp_f32_e32 v186, v149
	v_mul_f32_e32 v120, 0xbfb8aa3b, v120
	v_mul_f32_e32 v121, 0xbfb8aa3b, v121
	v_exp_f32_e32 v120, v120
	v_exp_f32_e32 v121, v121
	v_lshlrev_b32_e32 v138, 16, v195
	v_and_b32_e32 v139, 0xffff0000, v195
	v_pk_mul_f32 v[134:135], v[134:135], v[138:139]
	v_pk_mul_f32 v[136:137], v[136:137], v[142:143]
	v_pk_mul_f32 v[140:141], v[186:187], v[140:141]
	v_pk_mul_f32 v[134:135], v[136:137], v[134:135]
	s_waitcnt vmcnt(10)
	v_and_b32_e32 v137, 0xffff0000, v178
	v_pk_mul_f32 v[132:133], v[140:141], v[132:133]
	v_add_f32_e32 v120, 1.0, v120
	v_add_f32_e32 v121, 1.0, v121
	v_mul_f32_e32 v141, 0xbfb8aa3b, v137
	v_rcp_f32_e32 v120, v120
	v_rcp_f32_e32 v121, v121
	v_exp_f32_e32 v141, v141
	v_cvt_pk_bf16_f32 v132, v132, v133
	v_cvt_pk_bf16_f32 v133, v134, v135
	global_store_dwordx2 v[172:173], v[132:133], off offset:256
	v_lshlrev_b32_e32 v132, 16, v180
	v_and_b32_e32 v133, 0xffff0000, v180
	v_lshlrev_b32_e32 v136, 16, v178
	v_lshlrev_b32_e32 v138, 16, v179
	v_and_b32_e32 v139, 0xffff0000, v179
	v_pk_mul_f32 v[120:121], v[120:121], v[132:133]
	v_add_f32_e32 v132, 1.0, v141
	v_add_f32_e32 v122, v122, v110
	v_add_f32_e32 v123, v123, v111
	v_mul_f32_e32 v140, 0xbfb8aa3b, v136
	v_mul_f32_e32 v122, 0xbfb8aa3b, v122
	v_mul_f32_e32 v123, 0xbfb8aa3b, v123
	v_rcp_f32_e32 v141, v132
	v_mul_f32_e32 v132, 0xbfb8aa3b, v138
	v_mul_f32_e32 v133, 0xbfb8aa3b, v139
	v_exp_f32_e32 v140, v140
	v_exp_f32_e32 v122, v122
	v_exp_f32_e32 v123, v123
	v_exp_f32_e32 v132, v132
	v_exp_f32_e32 v133, v133
	v_add_f32_e32 v140, 1.0, v140
	v_add_f32_e32 v122, 1.0, v122
	v_add_f32_e32 v123, 1.0, v123
	v_add_f32_e32 v132, 1.0, v132
	v_add_f32_e32 v133, 1.0, v133
	v_rcp_f32_e32 v140, v140
	v_rcp_f32_e32 v122, v122
	v_rcp_f32_e32 v123, v123
	v_rcp_f32_e32 v132, v132
	v_rcp_f32_e32 v133, v133
	v_add_f32_e32 v112, v112, v128
	v_mul_f32_e32 v112, 0xbfb8aa3b, v112
	v_lshlrev_b32_e32 v134, 16, v181
	v_and_b32_e32 v135, 0xffff0000, v181
	v_exp_f32_e32 v128, v112
	v_add_f32_e32 v112, v113, v129
	v_pk_mul_f32 v[136:137], v[140:141], v[136:137]
	v_pk_mul_f32 v[122:123], v[122:123], v[134:135]
	v_pk_mul_f32 v[132:133], v[132:133], v[138:139]
	v_mul_f32_e32 v112, 0xbfb8aa3b, v112
	v_pk_mul_f32 v[120:121], v[136:137], v[120:121]
	v_pk_mul_f32 v[122:123], v[132:133], v[122:123]
	v_exp_f32_e32 v129, v112
	v_cvt_pk_bf16_f32 v120, v120, v121
	v_cvt_pk_bf16_f32 v121, v122, v123
	global_store_dwordx2 v[172:173], v[120:121], off offset:288
	v_lshlrev_b64 v[120:121], 11, v[170:171]
	s_waitcnt vmcnt(10)
; DI float sigmoidf_(float x) { return __builtin_amdgcn_rcpf(1.0f + __expf(-x)); }
; DI float siluf_(float x) { return x * sigmoidf_(x); }
; DI void st_bf4(bf16_t* p, float a, float b, float c, float d) { uint2 v; v.x = pack2(a, b); v.y = pack2(c, d); *(uint2*)p = v; }
; DI void phase_g2(const Params& p, const Sub& s, char* lds_all) {
;     ...
;       [&](int row, int col) { const size_t o = (size_t)row * D + col; Ld2 r; const uint2 a = *(const uint2*)(A + o), b = *(const uint2*)(z + o);
;         r.a.x = __uint_as_float(a.x); r.a.y = __uint_as_float(a.y); r.a.z = __uint_as_float(b.x); r.a.w = __uint_as_float(b.y); r.b = *(const float4*)(p.s5_b_glu + col); return r; },
;       [&](int row, int col, f32x4 v, const Ld2& l2) {
;         uint4 ld; ld.x = __float_as_uint(l2.a.x); ld.y = __float_as_uint(l2.a.y); ld.z = __float_as_uint(l2.a.z); ld.w = __float_as_uint(l2.a.w);
;         const size_t o = (size_t)row * D + col;
;         const float y0 = __uint_as_float(ld.x << 16), y1 = __uint_as_float(ld.x & 0xffff0000u), y2_ = __uint_as_float(ld.y << 16), y3 = __uint_as_float(ld.y & 0xffff0000u);
;         const float z0 = __uint_as_float(ld.z << 16), z1 = __uint_as_float(ld.z & 0xffff0000u), z2 = __uint_as_float(ld.w << 16), z3 = __uint_as_float(ld.w & 0xffff0000u);
;         const float4 b4 = l2.b;
;         st_bf4(y2 + o, y0 * sigmoidf_(v[0] + b4.x) * siluf_(z0), y1 * sigmoidf_(v[1] + b4.y) * siluf_(z1),
;                y2_ * sigmoidf_(v[2] + b4.z) * siluf_(z2), y3 * sigmoidf_(v[3] + b4.w) * siluf_(z3));
;       });
	v_and_b32_e32 v135, 0xffff0000, v174
	v_lshl_add_u64 v[120:121], s[14:15], 0, v[120:121]
	v_lshl_add_u64 v[112:113], v[120:121], 0, v[144:145]
	v_add_f32_e32 v120, 1.0, v128
	v_add_f32_e32 v121, 1.0, v129
	v_mul_f32_e32 v129, 0xbfb8aa3b, v135
	v_rcp_f32_e32 v120, v120
	v_rcp_f32_e32 v121, v121
	v_exp_f32_e32 v129, v129
	v_lshlrev_b32_e32 v122, 16, v176
	v_and_b32_e32 v123, 0xffff0000, v176
	v_lshlrev_b32_e32 v136, 16, v175
	v_and_b32_e32 v137, 0xffff0000, v175
	v_pk_mul_f32 v[120:121], v[120:121], v[122:123]
	v_add_f32_e32 v122, 1.0, v129
	v_add_f32_e32 v114, v114, v130
	v_add_f32_e32 v115, v115, v131
	v_mul_f32_e32 v114, 0xbfb8aa3b, v114
	v_mul_f32_e32 v115, 0xbfb8aa3b, v115
	v_rcp_f32_e32 v129, v122
	v_mul_f32_e32 v122, 0xbfb8aa3b, v136
	v_mul_f32_e32 v123, 0xbfb8aa3b, v137
	v_exp_f32_e32 v114, v114
	v_exp_f32_e32 v115, v115
	v_exp_f32_e32 v122, v122
	v_exp_f32_e32 v123, v123
	v_lshlrev_b32_e32 v134, 16, v174
	v_mul_f32_e32 v128, 0xbfb8aa3b, v134
	v_exp_f32_e32 v128, v128
	v_add_f32_e32 v114, 1.0, v114
	v_add_f32_e32 v115, 1.0, v115
	v_add_f32_e32 v122, 1.0, v122
	v_add_f32_e32 v123, 1.0, v123
	v_rcp_f32_e32 v114, v114
	v_rcp_f32_e32 v115, v115
	v_rcp_f32_e32 v122, v122
	v_rcp_f32_e32 v123, v123
	v_add_f32_e32 v104, v104, v124
	v_add_f32_e32 v105, v105, v125
	v_mul_f32_e32 v104, 0xbfb8aa3b, v104
	v_mul_f32_e32 v105, 0xbfb8aa3b, v105
	v_exp_f32_e32 v104, v104
	v_exp_f32_e32 v105, v105
	v_lshlrev_b32_e32 v132, 16, v177
	v_and_b32_e32 v133, 0xffff0000, v177
	v_add_f32_e32 v128, 1.0, v128
	v_rcp_f32_e32 v128, v128
	v_pk_mul_f32 v[114:115], v[114:115], v[132:133]
	v_pk_mul_f32 v[122:123], v[122:123], v[136:137]
	v_add_f32_e32 v104, 1.0, v104
	v_pk_mul_f32 v[114:115], v[114:115], v[122:123]
	s_waitcnt vmcnt(8)
	v_and_b32_e32 v123, 0xffff0000, v166
	v_add_f32_e32 v105, 1.0, v105
	v_mul_f32_e32 v125, 0xbfb8aa3b, v123
	v_rcp_f32_e32 v104, v104
	v_rcp_f32_e32 v105, v105
	v_exp_f32_e32 v125, v125
	v_pk_mul_f32 v[128:129], v[128:129], v[134:135]
	v_add_f32_e32 v106, v106, v126
	v_pk_mul_f32 v[120:121], v[120:121], v[128:129]
	v_lshlrev_b32_e32 v128, 16, v167
	v_cvt_pk_bf16_f32 v120, v120, v121
	v_cvt_pk_bf16_f32 v121, v114, v115
	v_lshlrev_b32_e32 v114, 16, v168
	v_and_b32_e32 v115, 0xffff0000, v168
	v_and_b32_e32 v129, 0xffff0000, v167
	v_pk_mul_f32 v[104:105], v[104:105], v[114:115]
	v_add_f32_e32 v114, 1.0, v125
	v_add_f32_e32 v107, v107, v127
	v_mul_f32_e32 v106, 0xbfb8aa3b, v106
	v_mul_f32_e32 v107, 0xbfb8aa3b, v107
	v_rcp_f32_e32 v125, v114
	v_mul_f32_e32 v114, 0xbfb8aa3b, v128
	v_mul_f32_e32 v115, 0xbfb8aa3b, v129
	v_exp_f32_e32 v106, v106
	v_exp_f32_e32 v107, v107
	v_exp_f32_e32 v114, v114
	v_exp_f32_e32 v115, v115
	v_lshlrev_b32_e32 v122, 16, v166
	v_mul_f32_e32 v124, 0xbfb8aa3b, v122
	v_exp_f32_e32 v124, v124
	v_add_f32_e32 v106, 1.0, v106
	v_add_f32_e32 v107, 1.0, v107
	v_add_f32_e32 v114, 1.0, v114
	v_add_f32_e32 v115, 1.0, v115
	v_rcp_f32_e32 v106, v106
	v_rcp_f32_e32 v107, v107
	v_rcp_f32_e32 v114, v114
	v_rcp_f32_e32 v115, v115
	v_add_f32_e32 v100, v100, v116
	v_add_f32_e32 v101, v101, v117
	v_mul_f32_e32 v100, 0xbfb8aa3b, v100
	v_mul_f32_e32 v101, 0xbfb8aa3b, v101
	v_add_f32_e32 v124, 1.0, v124
	v_exp_f32_e32 v100, v100
	v_exp_f32_e32 v101, v101
	global_store_dwordx2 v[112:113], v[120:121], off
	v_lshlrev_b32_e32 v120, 16, v169
	v_and_b32_e32 v121, 0xffff0000, v169
	v_rcp_f32_e32 v124, v124
	v_pk_mul_f32 v[106:107], v[106:107], v[120:121]
	v_pk_mul_f32 v[114:115], v[114:115], v[128:129]
	v_add_f32_e32 v100, 1.0, v100
	v_pk_mul_f32 v[106:107], v[106:107], v[114:115]
	s_waitcnt vmcnt(7)
	v_and_b32_e32 v115, 0xffff0000, v162
	v_add_f32_e32 v101, 1.0, v101
	v_mul_f32_e32 v117, 0xbfb8aa3b, v115
	v_pk_mul_f32 v[122:123], v[124:125], v[122:123]
	v_rcp_f32_e32 v100, v100
	v_rcp_f32_e32 v101, v101
	v_exp_f32_e32 v117, v117
	v_pk_mul_f32 v[104:105], v[104:105], v[122:123]
	v_lshlrev_b32_e32 v120, 16, v163
	v_cvt_pk_bf16_f32 v104, v104, v105
	v_cvt_pk_bf16_f32 v105, v106, v107
	global_store_dwordx2 v[112:113], v[104:105], off offset:32
	v_lshlrev_b32_e32 v104, 16, v164
	v_and_b32_e32 v105, 0xffff0000, v164
	v_and_b32_e32 v121, 0xffff0000, v163
	v_pk_mul_f32 v[100:101], v[100:101], v[104:105]
	v_add_f32_e32 v104, 1.0, v117
	v_add_f32_e32 v102, v102, v118
	v_add_f32_e32 v103, v103, v119
	v_mul_f32_e32 v102, 0xbfb8aa3b, v102
	v_mul_f32_e32 v103, 0xbfb8aa3b, v103
	v_rcp_f32_e32 v117, v104
	v_mul_f32_e32 v104, 0xbfb8aa3b, v120
	v_mul_f32_e32 v105, 0xbfb8aa3b, v121
	v_exp_f32_e32 v102, v102
	v_exp_f32_e32 v103, v103
	v_exp_f32_e32 v104, v104
	v_exp_f32_e32 v105, v105
	v_lshlrev_b32_e32 v114, 16, v162
	v_mul_f32_e32 v116, 0xbfb8aa3b, v114
	v_exp_f32_e32 v116, v116
	v_add_f32_e32 v102, 1.0, v102
	v_add_f32_e32 v103, 1.0, v103
	v_add_f32_e32 v104, 1.0, v104
	v_add_f32_e32 v105, 1.0, v105
	v_rcp_f32_e32 v102, v102
	v_rcp_f32_e32 v103, v103
	v_rcp_f32_e32 v104, v104
	v_rcp_f32_e32 v105, v105
	v_add_f32_e32 v96, v96, v108
	v_add_f32_e32 v97, v97, v109
	v_mul_f32_e32 v96, 0xbfb8aa3b, v96
	v_mul_f32_e32 v97, 0xbfb8aa3b, v97
	v_add_f32_e32 v116, 1.0, v116
	v_exp_f32_e32 v96, v96
	v_exp_f32_e32 v97, v97
	v_lshlrev_b32_e32 v106, 16, v165
	v_and_b32_e32 v107, 0xffff0000, v165
	v_rcp_f32_e32 v116, v116
	v_pk_mul_f32 v[102:103], v[102:103], v[106:107]
	v_pk_mul_f32 v[104:105], v[104:105], v[120:121]
	v_add_f32_e32 v96, 1.0, v96
	v_pk_mul_f32 v[102:103], v[102:103], v[104:105]
	s_waitcnt vmcnt(6)
; DI float sigmoidf_(float x) { return __builtin_amdgcn_rcpf(1.0f + __expf(-x)); }
; DI float siluf_(float x) { return x * sigmoidf_(x); }
; DI void st_bf4(bf16_t* p, float a, float b, float c, float d) { uint2 v; v.x = pack2(a, b); v.y = pack2(c, d); *(uint2*)p = v; }
; template <class FL, class FS>
; DI void gemm8_tile(char* shmc, const bf16_t* __restrict__ A, const bf16_t* __restrict__ Bt, const int K, const int brow, const int bcol, FL fl, FS fs) {
;     ...
;       decltype(fl(0, 0)) ld[2][2][2];
; #pragma unroll
;       for (int mm = 0; mm < 2; ++mm)
; #pragma unroll
;         for (int bj = 0; bj < 2; ++bj)
; #pragma unroll
;           for (int n = 0; n < 2; ++n) ld[mm][bj][n] = fl(brow + ai * HALF + wr * 64 + (2 * mh + mm) * 16 + fr, bcol + bj * HALF + wc * 32 + n * 16 + 4 * fq);
; #pragma unroll
;       for (int mm = 0; mm < 2; ++mm)
; #pragma unroll
;         for (int bj = 0; bj < 2; ++bj)
; #pragma unroll
;           for (int n = 0; n < 2; ++n) fs(brow + ai * HALF + wr * 64 + (2 * mh + mm) * 16 + fr, bcol + bj * HALF + wc * 32 + n * 16 + 4 * fq, acc[ai][bj][2 * mh + mm][n], ld[mm][bj][n]);
; DI void phase_g2(const Params& p, const Sub& s, char* lds_all) {
;     ...
;       [&](int row, int col) { const size_t o = (size_t)row * D + col; Ld2 r; const uint2 a = *(const uint2*)(A + o), b = *(const uint2*)(z + o);
;         r.a.x = __uint_as_float(a.x); r.a.y = __uint_as_float(a.y); r.a.z = __uint_as_float(b.x); r.a.w = __uint_as_float(b.y); r.b = *(const float4*)(p.s5_b_glu + col); return r; },
;       [&](int row, int col, f32x4 v, const Ld2& l2) {
;         uint4 ld; ld.x = __float_as_uint(l2.a.x); ld.y = __float_as_uint(l2.a.y); ld.z = __float_as_uint(l2.a.z); ld.w = __float_as_uint(l2.a.w);
;         const size_t o = (size_t)row * D + col;
;         const float y0 = __uint_as_float(ld.x << 16), y1 = __uint_as_float(ld.x & 0xffff0000u), y2_ = __uint_as_float(ld.y << 16), y3 = __uint_as_float(ld.y & 0xffff0000u);
;         const float z0 = __uint_as_float(ld.z << 16), z1 = __uint_as_float(ld.z & 0xffff0000u), z2 = __uint_as_float(ld.w << 16), z3 = __uint_as_float(ld.w & 0xffff0000u);
;         const float4 b4 = l2.b;
;         st_bf4(y2 + o, y0 * sigmoidf_(v[0] + b4.x) * siluf_(z0), y1 * sigmoidf_(v[1] + b4.y) * siluf_(z1),
;                y2_ * sigmoidf_(v[2] + b4.z) * siluf_(z2), y3 * sigmoidf_(v[3] + b4.w) * siluf_(z3));
;       });
	v_and_b32_e32 v105, 0xffff0000, v158
	v_add_f32_e32 v97, 1.0, v97
	v_mul_f32_e32 v109, 0xbfb8aa3b, v105
	v_pk_mul_f32 v[114:115], v[116:117], v[114:115]
	v_rcp_f32_e32 v96, v96
	v_rcp_f32_e32 v97, v97
	v_exp_f32_e32 v109, v109
	v_pk_mul_f32 v[100:101], v[100:101], v[114:115]
	v_lshlrev_b32_e32 v104, 16, v158
	v_cvt_pk_bf16_f32 v100, v100, v101
	v_cvt_pk_bf16_f32 v101, v102, v103
	global_store_dwordx2 v[112:113], v[100:101], off offset:256
	v_lshlrev_b32_e32 v100, 16, v160
	v_and_b32_e32 v101, 0xffff0000, v160
	v_lshlrev_b32_e32 v106, 16, v159
	v_and_b32_e32 v107, 0xffff0000, v159
	v_pk_mul_f32 v[96:97], v[96:97], v[100:101]
	v_add_f32_e32 v100, 1.0, v109
	v_add_f32_e32 v98, v98, v110
	v_add_f32_e32 v99, v99, v111
	v_mul_f32_e32 v108, 0xbfb8aa3b, v104
	v_mul_f32_e32 v98, 0xbfb8aa3b, v98
	v_mul_f32_e32 v99, 0xbfb8aa3b, v99
	v_rcp_f32_e32 v109, v100
	v_mul_f32_e32 v100, 0xbfb8aa3b, v106
	v_mul_f32_e32 v101, 0xbfb8aa3b, v107
	v_exp_f32_e32 v108, v108
	v_exp_f32_e32 v98, v98
	v_exp_f32_e32 v99, v99
	v_exp_f32_e32 v100, v100
	v_exp_f32_e32 v101, v101
	v_add_f32_e32 v108, 1.0, v108
	v_add_f32_e32 v98, 1.0, v98
	v_add_f32_e32 v99, 1.0, v99
	v_add_f32_e32 v100, 1.0, v100
	v_add_f32_e32 v101, 1.0, v101
	v_rcp_f32_e32 v108, v108
	v_rcp_f32_e32 v98, v98
	v_rcp_f32_e32 v99, v99
	v_rcp_f32_e32 v100, v100
	v_rcp_f32_e32 v101, v101
	v_lshlrev_b32_e32 v102, 16, v161
	v_and_b32_e32 v103, 0xffff0000, v161
	v_pk_mul_f32 v[104:105], v[108:109], v[104:105]
	v_pk_mul_f32 v[98:99], v[98:99], v[102:103]
	v_pk_mul_f32 v[100:101], v[100:101], v[106:107]
	v_pk_mul_f32 v[96:97], v[96:97], v[104:105]
	v_pk_mul_f32 v[98:99], v[98:99], v[100:101]
	v_or_b32_e32 v134, 32, v148
	v_cvt_pk_bf16_f32 v96, v96, v97
	v_cvt_pk_bf16_f32 v97, v98, v99
	v_ashrrev_i32_e32 v135, 31, v134
	global_store_dwordx2 v[112:113], v[96:97], off offset:288
	v_lshlrev_b64 v[96:97], 10, v[134:135]
	v_lshl_add_u64 v[98:99], v[96:97], 0, v[146:147]
	v_lshlrev_b64 v[98:99], 1, v[98:99]
	v_lshl_add_u64 v[100:101], s[10:11], 0, v[98:99]
	v_lshl_add_u64 v[98:99], s[12:13], 0, v[98:99]
	global_load_dwordx2 v[136:137], v[100:101], off
	global_load_dwordx2 v[138:139], v[98:99], off
	global_load_dwordx4 v[108:111], v[154:155], off
	v_lshl_add_u64 v[98:99], v[96:97], 0, v[152:153]
	v_lshlrev_b64 v[98:99], 1, v[98:99]
	v_lshl_add_u64 v[100:101], s[10:11], 0, v[98:99]
	v_lshl_add_u64 v[98:99], s[12:13], 0, v[98:99]
	global_load_dwordx2 v[140:141], v[100:101], off
	global_load_dwordx2 v[142:143], v[98:99], off
	global_load_dwordx4 v[104:107], v[154:155], off offset:64
	v_lshl_add_u64 v[98:99], v[96:97], 0, v[150:151]
	v_lshl_add_u64 v[96:97], v[96:97], 0, v[156:157]
	v_lshlrev_b64 v[98:99], 1, v[98:99]
	v_lshlrev_b64 v[96:97], 1, v[96:97]
	v_lshl_add_u64 v[100:101], s[10:11], 0, v[98:99]
	v_lshl_add_u64 v[98:99], s[12:13], 0, v[98:99]
	v_lshl_add_u64 v[102:103], s[10:11], 0, v[96:97]
	v_lshl_add_u64 v[96:97], s[12:13], 0, v[96:97]
	global_load_dwordx2 v[158:159], v[100:101], off
	global_load_dwordx2 v[160:161], v[98:99], off
	global_load_dwordx2 v[132:133], v[102:103], off
	global_load_dwordx2 v[130:131], v[96:97], off
	s_nop 0
	global_load_dwordx4 v[100:103], v[154:155], off offset:512
	global_load_dwordx4 v[96:99], v[154:155], off offset:576
	v_or_b32_e32 v124, 48, v148
	v_ashrrev_i32_e32 v125, 31, v124
	v_lshlrev_b64 v[112:113], 10, v[124:125]
	v_lshl_add_u64 v[114:115], v[112:113], 0, v[146:147]
	v_lshl_add_u64 v[118:119], v[112:113], 0, v[152:153]
	v_lshlrev_b64 v[114:115], 1, v[114:115]
	v_lshlrev_b64 v[118:119], 1, v[118:119]
	v_lshlrev_b64 v[134:135], 11, v[134:135]
	v_lshl_add_u64 v[116:117], s[10:11], 0, v[114:115]
	v_lshl_add_u64 v[120:121], s[10:11], 0, v[118:119]
	v_lshl_add_u64 v[134:135], s[14:15], 0, v[134:135]
	v_lshl_add_u64 v[114:115], s[12:13], 0, v[114:115]
	v_lshl_add_u64 v[118:119], s[12:13], 0, v[118:119]
	global_load_dwordx2 v[128:129], v[116:117], off
	global_load_dwordx2 v[126:127], v[114:115], off
	global_load_dwordx2 v[122:123], v[120:121], off
	s_nop 0
	global_load_dwordx2 v[120:121], v[118:119], off
	v_lshl_add_u64 v[114:115], v[112:113], 0, v[150:151]
	v_lshl_add_u64 v[112:113], v[112:113], 0, v[156:157]
	v_lshlrev_b64 v[114:115], 1, v[114:115]
	v_lshlrev_b64 v[112:113], 1, v[112:113]
	v_lshl_add_u64 v[116:117], s[10:11], 0, v[114:115]
	v_lshl_add_u64 v[114:115], s[12:13], 0, v[114:115]
	v_lshl_add_u64 v[162:163], s[10:11], 0, v[112:113]
	v_lshl_add_u64 v[112:113], s[12:13], 0, v[112:113]
	global_load_dwordx2 v[118:119], v[116:117], off
	s_nop 0
	global_load_dwordx2 v[116:117], v[114:115], off
	s_nop 0
	global_load_dwordx2 v[114:115], v[162:163], off
	s_nop 0
	global_load_dwordx2 v[112:113], v[112:113], off
	s_waitcnt vmcnt(18)
	v_lshlrev_b32_e32 v164, 16, v138
	s_waitcnt vmcnt(17)
	v_add_f32_e32 v92, v92, v108
	v_mul_f32_e32 v92, 0xbfb8aa3b, v92
	v_exp_f32_e32 v149, v92
	v_add_f32_e32 v92, v93, v109
	v_mul_f32_e32 v92, 0xbfb8aa3b, v92
	v_exp_f32_e32 v166, v92
	v_and_b32_e32 v165, 0xffff0000, v138
	v_lshl_add_u64 v[92:93], v[134:135], 0, v[144:145]
	v_add_f32_e32 v134, 1.0, v149
	v_mul_f32_e32 v149, 0xbfb8aa3b, v164
	v_add_f32_e32 v135, 1.0, v166
	v_exp_f32_e32 v149, v149
	v_mul_f32_e32 v166, 0xbfb8aa3b, v165
	v_exp_f32_e32 v167, v166
	v_rcp_f32_e32 v134, v134
	v_rcp_f32_e32 v135, v135
	v_add_f32_e32 v149, 1.0, v149
	v_lshlrev_b32_e32 v138, 16, v139
	v_rcp_f32_e32 v166, v149
	v_add_f32_e32 v149, 1.0, v167
	v_lshlrev_b32_e32 v162, 16, v136
	v_and_b32_e32 v163, 0xffff0000, v136
	v_and_b32_e32 v139, 0xffff0000, v139
	v_add_f32_e32 v94, v94, v110
	v_add_f32_e32 v95, v95, v111
	v_rcp_f32_e32 v167, v149
	v_mul_f32_e32 v149, 0xbfb8aa3b, v138
	v_pk_mul_f32 v[134:135], v[134:135], v[162:163]
	v_mul_f32_e32 v94, 0xbfb8aa3b, v94
	v_mul_f32_e32 v95, 0xbfb8aa3b, v95
	v_exp_f32_e32 v149, v149
	v_mul_f32_e32 v162, 0xbfb8aa3b, v139
	v_exp_f32_e32 v94, v94
	v_exp_f32_e32 v95, v95
	v_exp_f32_e32 v163, v162
	v_add_f32_e32 v149, 1.0, v149
	v_add_f32_e32 v94, 1.0, v94
	v_add_f32_e32 v95, 1.0, v95
	v_rcp_f32_e32 v162, v149
	v_add_f32_e32 v149, 1.0, v163
	v_rcp_f32_e32 v94, v94
	v_rcp_f32_e32 v95, v95
	v_rcp_f32_e32 v163, v149
	s_waitcnt vmcnt(14)
; DI float sigmoidf_(float x) { return __builtin_amdgcn_rcpf(1.0f + __expf(-x)); }
; DI float siluf_(float x) { return x * sigmoidf_(x); }
; DI void st_bf4(bf16_t* p, float a, float b, float c, float d) { uint2 v; v.x = pack2(a, b); v.y = pack2(c, d); *(uint2*)p = v; }
; DI void phase_g2(const Params& p, const Sub& s, char* lds_all) {
;     ...
;       [&](int row, int col) { const size_t o = (size_t)row * D + col; Ld2 r; const uint2 a = *(const uint2*)(A + o), b = *(const uint2*)(z + o);
;         r.a.x = __uint_as_float(a.x); r.a.y = __uint_as_float(a.y); r.a.z = __uint_as_float(b.x); r.a.w = __uint_as_float(b.y); r.b = *(const float4*)(p.s5_b_glu + col); return r; },
;       [&](int row, int col, f32x4 v, const Ld2& l2) {
;         uint4 ld; ld.x = __float_as_uint(l2.a.x); ld.y = __float_as_uint(l2.a.y); ld.z = __float_as_uint(l2.a.z); ld.w = __float_as_uint(l2.a.w);
;         const size_t o = (size_t)row * D + col;
;         const float y0 = __uint_as_float(ld.x << 16), y1 = __uint_as_float(ld.x & 0xffff0000u), y2_ = __uint_as_float(ld.y << 16), y3 = __uint_as_float(ld.y & 0xffff0000u);
;         const float z0 = __uint_as_float(ld.z << 16), z1 = __uint_as_float(ld.z & 0xffff0000u), z2 = __uint_as_float(ld.w << 16), z3 = __uint_as_float(ld.w & 0xffff0000u);
;         const float4 b4 = l2.b;
;         st_bf4(y2 + o, y0 * sigmoidf_(v[0] + b4.x) * siluf_(z0), y1 * sigmoidf_(v[1] + b4.y) * siluf_(z1),
;                y2_ * sigmoidf_(v[2] + b4.z) * siluf_(z2), y3 * sigmoidf_(v[3] + b4.w) * siluf_(z3));
	v_add_f32_e32 v88, v88, v104
	v_add_f32_e32 v89, v89, v105
	v_mul_f32_e32 v88, 0xbfb8aa3b, v88
	v_mul_f32_e32 v89, 0xbfb8aa3b, v89
	v_lshlrev_b32_e32 v136, 16, v137
	v_and_b32_e32 v137, 0xffff0000, v137
	v_exp_f32_e32 v88, v88
	v_exp_f32_e32 v89, v89
	v_pk_mul_f32 v[164:165], v[166:167], v[164:165]
	v_pk_mul_f32 v[94:95], v[94:95], v[136:137]
	v_pk_mul_f32 v[136:137], v[162:163], v[138:139]
	v_pk_mul_f32 v[134:135], v[164:165], v[134:135]
	v_pk_mul_f32 v[94:95], v[136:137], v[94:95]
	v_cvt_pk_bf16_f32 v134, v134, v135
	v_cvt_pk_bf16_f32 v135, v94, v95
	v_and_b32_e32 v137, 0xffff0000, v142
	global_store_dwordx2 v[92:93], v[134:135], off
	v_lshlrev_b32_e32 v134, 16, v141
	v_and_b32_e32 v135, 0xffff0000, v141
	v_add_f32_e32 v88, 1.0, v88
	v_add_f32_e32 v89, 1.0, v89
	v_mul_f32_e32 v141, 0xbfb8aa3b, v137
	v_rcp_f32_e32 v88, v88
	v_rcp_f32_e32 v89, v89
	v_exp_f32_e32 v141, v141
	v_lshlrev_b32_e32 v94, 16, v140
	v_and_b32_e32 v95, 0xffff0000, v140
	v_lshlrev_b32_e32 v138, 16, v143
	v_and_b32_e32 v139, 0xffff0000, v143
	v_pk_mul_f32 v[88:89], v[88:89], v[94:95]
	v_add_f32_e32 v94, 1.0, v141
	v_add_f32_e32 v90, v90, v106
	v_add_f32_e32 v91, v91, v107
	v_lshlrev_b32_e32 v136, 16, v142
	v_mul_f32_e32 v90, 0xbfb8aa3b, v90
	v_mul_f32_e32 v91, 0xbfb8aa3b, v91
	v_rcp_f32_e32 v141, v94
	v_mul_f32_e32 v94, 0xbfb8aa3b, v138
	v_mul_f32_e32 v95, 0xbfb8aa3b, v139
	v_mul_f32_e32 v140, 0xbfb8aa3b, v136
	v_exp_f32_e32 v90, v90
	v_exp_f32_e32 v91, v91
	v_exp_f32_e32 v94, v94
	v_exp_f32_e32 v95, v95
	v_exp_f32_e32 v140, v140
	v_add_f32_e32 v90, 1.0, v90
	v_add_f32_e32 v91, 1.0, v91
	v_add_f32_e32 v94, 1.0, v94
	v_add_f32_e32 v95, 1.0, v95
	v_add_f32_e32 v140, 1.0, v140
	v_rcp_f32_e32 v90, v90
	v_rcp_f32_e32 v91, v91
	v_rcp_f32_e32 v94, v94
	v_rcp_f32_e32 v95, v95
	s_waitcnt vmcnt(10)
	v_add_f32_e32 v84, v84, v100
	v_add_f32_e32 v85, v85, v101
	v_rcp_f32_e32 v140, v140
	v_mul_f32_e32 v84, 0xbfb8aa3b, v84
	v_mul_f32_e32 v85, 0xbfb8aa3b, v85
	v_exp_f32_e32 v84, v84
	v_exp_f32_e32 v85, v85
	v_pk_mul_f32 v[90:91], v[90:91], v[134:135]
	v_pk_mul_f32 v[94:95], v[94:95], v[138:139]
	v_pk_mul_f32 v[136:137], v[140:141], v[136:137]
	v_pk_mul_f32 v[90:91], v[94:95], v[90:91]
	v_and_b32_e32 v95, 0xffff0000, v160
	v_pk_mul_f32 v[88:89], v[136:137], v[88:89]
	v_add_f32_e32 v84, 1.0, v84
	v_add_f32_e32 v85, 1.0, v85
	v_mul_f32_e32 v137, 0xbfb8aa3b, v95
	v_rcp_f32_e32 v84, v84
	v_rcp_f32_e32 v85, v85
	v_exp_f32_e32 v137, v137
	v_cvt_pk_bf16_f32 v88, v88, v89
	v_cvt_pk_bf16_f32 v89, v90, v91
	global_store_dwordx2 v[92:93], v[88:89], off offset:32
	v_lshlrev_b32_e32 v88, 16, v158
	v_and_b32_e32 v89, 0xffff0000, v158
	v_lshlrev_b32_e32 v134, 16, v161
	v_and_b32_e32 v135, 0xffff0000, v161
	v_pk_mul_f32 v[84:85], v[84:85], v[88:89]
	v_add_f32_e32 v88, 1.0, v137
	v_add_f32_e32 v86, v86, v102
	v_add_f32_e32 v87, v87, v103
	v_lshlrev_b32_e32 v94, 16, v160
	v_mul_f32_e32 v86, 0xbfb8aa3b, v86
	v_mul_f32_e32 v87, 0xbfb8aa3b, v87
	v_rcp_f32_e32 v137, v88
	v_mul_f32_e32 v88, 0xbfb8aa3b, v134
	v_mul_f32_e32 v89, 0xbfb8aa3b, v135
	v_mul_f32_e32 v136, 0xbfb8aa3b, v94
	v_exp_f32_e32 v86, v86
	v_exp_f32_e32 v87, v87
	v_exp_f32_e32 v88, v88
	v_exp_f32_e32 v89, v89
	v_exp_f32_e32 v136, v136
	v_add_f32_e32 v86, 1.0, v86
	v_add_f32_e32 v87, 1.0, v87
	v_add_f32_e32 v88, 1.0, v88
	v_add_f32_e32 v89, 1.0, v89
	v_add_f32_e32 v136, 1.0, v136
	v_rcp_f32_e32 v86, v86
	v_rcp_f32_e32 v87, v87
	v_rcp_f32_e32 v88, v88
	v_rcp_f32_e32 v89, v89
	s_waitcnt vmcnt(10)
	v_add_f32_e32 v80, v80, v96
	v_add_f32_e32 v81, v81, v97
	v_rcp_f32_e32 v136, v136
	v_mul_f32_e32 v80, 0xbfb8aa3b, v80
	v_mul_f32_e32 v81, 0xbfb8aa3b, v81
	v_exp_f32_e32 v80, v80
	v_exp_f32_e32 v81, v81
	v_lshlrev_b32_e32 v90, 16, v159
	v_and_b32_e32 v91, 0xffff0000, v159
	v_pk_mul_f32 v[86:87], v[86:87], v[90:91]
	v_pk_mul_f32 v[88:89], v[88:89], v[134:135]
	v_pk_mul_f32 v[94:95], v[136:137], v[94:95]
	v_pk_mul_f32 v[86:87], v[88:89], v[86:87]
	v_and_b32_e32 v89, 0xffff0000, v130
	v_pk_mul_f32 v[84:85], v[94:95], v[84:85]
	v_add_f32_e32 v80, 1.0, v80
	v_add_f32_e32 v81, 1.0, v81
	v_mul_f32_e32 v95, 0xbfb8aa3b, v89
	v_rcp_f32_e32 v80, v80
	v_rcp_f32_e32 v81, v81
	v_exp_f32_e32 v95, v95
	v_cvt_pk_bf16_f32 v84, v84, v85
	v_cvt_pk_bf16_f32 v85, v86, v87
	global_store_dwordx2 v[92:93], v[84:85], off offset:256
	v_lshlrev_b32_e32 v84, 16, v132
	v_and_b32_e32 v85, 0xffff0000, v132
	v_lshlrev_b32_e32 v90, 16, v131
	v_and_b32_e32 v91, 0xffff0000, v131
	v_pk_mul_f32 v[80:81], v[80:81], v[84:85]
	v_add_f32_e32 v84, 1.0, v95
	v_lshlrev_b32_e32 v88, 16, v130
	v_add_f32_e32 v82, v82, v98
	v_add_f32_e32 v83, v83, v99
	v_rcp_f32_e32 v95, v84
	v_mul_f32_e32 v84, 0xbfb8aa3b, v90
	v_mul_f32_e32 v85, 0xbfb8aa3b, v91
	v_mul_f32_e32 v94, 0xbfb8aa3b, v88
	v_mul_f32_e32 v82, 0xbfb8aa3b, v82
	v_mul_f32_e32 v83, 0xbfb8aa3b, v83
	v_exp_f32_e32 v84, v84
	v_exp_f32_e32 v85, v85
	v_exp_f32_e32 v94, v94
	v_exp_f32_e32 v82, v82
	v_exp_f32_e32 v83, v83
	v_add_f32_e32 v84, 1.0, v84
	v_add_f32_e32 v85, 1.0, v85
	v_add_f32_e32 v94, 1.0, v94
	v_add_f32_e32 v82, 1.0, v82
	v_add_f32_e32 v83, 1.0, v83
	v_rcp_f32_e32 v84, v84
	v_rcp_f32_e32 v85, v85
	v_rcp_f32_e32 v94, v94
	v_rcp_f32_e32 v82, v82
	v_rcp_f32_e32 v83, v83
	v_add_f32_e32 v76, v76, v108
	v_mul_f32_e32 v76, 0xbfb8aa3b, v76
	v_lshlrev_b32_e32 v86, 16, v133
	v_and_b32_e32 v87, 0xffff0000, v133
	v_pk_mul_f32 v[84:85], v[84:85], v[90:91]
	v_exp_f32_e32 v90, v76
	v_add_f32_e32 v76, v77, v109
	v_pk_mul_f32 v[88:89], v[94:95], v[88:89]
	v_pk_mul_f32 v[82:83], v[82:83], v[86:87]
	v_mul_f32_e32 v76, 0xbfb8aa3b, v76
	v_pk_mul_f32 v[80:81], v[88:89], v[80:81]
	v_pk_mul_f32 v[82:83], v[84:85], v[82:83]
	v_exp_f32_e32 v91, v76
	v_cvt_pk_bf16_f32 v80, v80, v81
	v_cvt_pk_bf16_f32 v81, v82, v83
	global_store_dwordx2 v[92:93], v[80:81], off offset:288
	v_lshlrev_b64 v[80:81], 11, v[124:125]
	s_waitcnt vmcnt(10)
; DI float sigmoidf_(float x) { return __builtin_amdgcn_rcpf(1.0f + __expf(-x)); }
; DI float siluf_(float x) { return x * sigmoidf_(x); }
; DI void st_bf4(bf16_t* p, float a, float b, float c, float d) { uint2 v; v.x = pack2(a, b); v.y = pack2(c, d); *(uint2*)p = v; }
; DI void phase_g2(const Params& p, const Sub& s, char* lds_all) {
;     ...
;       [&](int row, int col) { const size_t o = (size_t)row * D + col; Ld2 r; const uint2 a = *(const uint2*)(A + o), b = *(const uint2*)(z + o);
;         r.a.x = __uint_as_float(a.x); r.a.y = __uint_as_float(a.y); r.a.z = __uint_as_float(b.x); r.a.w = __uint_as_float(b.y); r.b = *(const float4*)(p.s5_b_glu + col); return r; },
;       [&](int row, int col, f32x4 v, const Ld2& l2) {
;         uint4 ld; ld.x = __float_as_uint(l2.a.x); ld.y = __float_as_uint(l2.a.y); ld.z = __float_as_uint(l2.a.z); ld.w = __float_as_uint(l2.a.w);
;         const size_t o = (size_t)row * D + col;
;         const float y0 = __uint_as_float(ld.x << 16), y1 = __uint_as_float(ld.x & 0xffff0000u), y2_ = __uint_as_float(ld.y << 16), y3 = __uint_as_float(ld.y & 0xffff0000u);
;         const float z0 = __uint_as_float(ld.z << 16), z1 = __uint_as_float(ld.z & 0xffff0000u), z2 = __uint_as_float(ld.w << 16), z3 = __uint_as_float(ld.w & 0xffff0000u);
;         const float4 b4 = l2.b;
;         st_bf4(y2 + o, y0 * sigmoidf_(v[0] + b4.x) * siluf_(z0), y1 * sigmoidf_(v[1] + b4.y) * siluf_(z1),
;                y2_ * sigmoidf_(v[2] + b4.z) * siluf_(z2), y3 * sigmoidf_(v[3] + b4.w) * siluf_(z3));
	v_and_b32_e32 v87, 0xffff0000, v126
	v_lshl_add_u64 v[80:81], s[14:15], 0, v[80:81]
	v_lshl_add_u64 v[76:77], v[80:81], 0, v[144:145]
	v_add_f32_e32 v80, 1.0, v90
	v_add_f32_e32 v81, 1.0, v91
	v_mul_f32_e32 v91, 0xbfb8aa3b, v87
	v_rcp_f32_e32 v80, v80
	v_rcp_f32_e32 v81, v81
	v_exp_f32_e32 v91, v91
	v_lshlrev_b32_e32 v82, 16, v128
	v_and_b32_e32 v83, 0xffff0000, v128
	v_lshlrev_b32_e32 v88, 16, v127
	v_and_b32_e32 v89, 0xffff0000, v127
	v_pk_mul_f32 v[80:81], v[80:81], v[82:83]
	v_add_f32_e32 v82, 1.0, v91
	v_add_f32_e32 v78, v78, v110
	v_add_f32_e32 v79, v79, v111
	v_lshlrev_b32_e32 v86, 16, v126
	v_mul_f32_e32 v78, 0xbfb8aa3b, v78
	v_mul_f32_e32 v79, 0xbfb8aa3b, v79
	v_rcp_f32_e32 v91, v82
	v_mul_f32_e32 v82, 0xbfb8aa3b, v88
	v_mul_f32_e32 v83, 0xbfb8aa3b, v89
	v_mul_f32_e32 v90, 0xbfb8aa3b, v86
	v_exp_f32_e32 v78, v78
	v_exp_f32_e32 v79, v79
	v_exp_f32_e32 v82, v82
	v_exp_f32_e32 v83, v83
	v_exp_f32_e32 v90, v90
	v_add_f32_e32 v78, 1.0, v78
	v_add_f32_e32 v79, 1.0, v79
	v_add_f32_e32 v82, 1.0, v82
	v_add_f32_e32 v83, 1.0, v83
	v_add_f32_e32 v90, 1.0, v90
	v_rcp_f32_e32 v78, v78
	v_rcp_f32_e32 v79, v79
	v_rcp_f32_e32 v82, v82
	v_rcp_f32_e32 v83, v83
	v_add_f32_e32 v72, v72, v104
	v_add_f32_e32 v73, v73, v105
	v_rcp_f32_e32 v90, v90
	v_mul_f32_e32 v72, 0xbfb8aa3b, v72
	v_mul_f32_e32 v73, 0xbfb8aa3b, v73
	v_exp_f32_e32 v72, v72
	v_exp_f32_e32 v73, v73
	v_lshlrev_b32_e32 v84, 16, v129
	v_and_b32_e32 v85, 0xffff0000, v129
	v_pk_mul_f32 v[78:79], v[78:79], v[84:85]
	v_pk_mul_f32 v[82:83], v[82:83], v[88:89]
	v_pk_mul_f32 v[86:87], v[90:91], v[86:87]
	v_pk_mul_f32 v[78:79], v[78:79], v[82:83]
	s_waitcnt vmcnt(8)
	v_and_b32_e32 v83, 0xffff0000, v120
	v_pk_mul_f32 v[80:81], v[80:81], v[86:87]
	v_add_f32_e32 v72, 1.0, v72
	v_add_f32_e32 v73, 1.0, v73
	v_mul_f32_e32 v87, 0xbfb8aa3b, v83
	v_rcp_f32_e32 v72, v72
	v_rcp_f32_e32 v73, v73
	v_exp_f32_e32 v87, v87
	v_cvt_pk_bf16_f32 v80, v80, v81
	v_cvt_pk_bf16_f32 v81, v78, v79
	v_lshlrev_b32_e32 v78, 16, v122
	v_and_b32_e32 v79, 0xffff0000, v122
	v_lshlrev_b32_e32 v84, 16, v121
	v_and_b32_e32 v85, 0xffff0000, v121
	v_pk_mul_f32 v[72:73], v[72:73], v[78:79]
	v_add_f32_e32 v78, 1.0, v87
	v_add_f32_e32 v74, v74, v106
	v_add_f32_e32 v75, v75, v107
	v_lshlrev_b32_e32 v82, 16, v120
	v_mul_f32_e32 v74, 0xbfb8aa3b, v74
	v_mul_f32_e32 v75, 0xbfb8aa3b, v75
	v_rcp_f32_e32 v87, v78
	v_mul_f32_e32 v78, 0xbfb8aa3b, v84
	v_mul_f32_e32 v79, 0xbfb8aa3b, v85
	v_mul_f32_e32 v86, 0xbfb8aa3b, v82
	v_exp_f32_e32 v74, v74
	v_exp_f32_e32 v75, v75
	v_exp_f32_e32 v78, v78
	v_exp_f32_e32 v79, v79
	v_exp_f32_e32 v86, v86
	v_add_f32_e32 v74, 1.0, v74
	v_add_f32_e32 v75, 1.0, v75
	v_add_f32_e32 v78, 1.0, v78
	v_add_f32_e32 v79, 1.0, v79
	v_add_f32_e32 v86, 1.0, v86
	v_rcp_f32_e32 v74, v74
	v_rcp_f32_e32 v75, v75
	v_rcp_f32_e32 v78, v78
	v_rcp_f32_e32 v79, v79
	v_add_f32_e32 v68, v68, v100
	v_add_f32_e32 v69, v69, v101
	v_rcp_f32_e32 v86, v86
	v_mul_f32_e32 v68, 0xbfb8aa3b, v68
	v_mul_f32_e32 v69, 0xbfb8aa3b, v69
	v_exp_f32_e32 v68, v68
	v_exp_f32_e32 v69, v69
	global_store_dwordx2 v[76:77], v[80:81], off
	v_lshlrev_b32_e32 v80, 16, v123
	v_and_b32_e32 v81, 0xffff0000, v123
	v_pk_mul_f32 v[74:75], v[74:75], v[80:81]
	v_pk_mul_f32 v[78:79], v[78:79], v[84:85]
	v_pk_mul_f32 v[82:83], v[86:87], v[82:83]
	v_pk_mul_f32 v[74:75], v[74:75], v[78:79]
	s_waitcnt vmcnt(7)
	v_and_b32_e32 v79, 0xffff0000, v116
	v_pk_mul_f32 v[72:73], v[72:73], v[82:83]
	v_add_f32_e32 v68, 1.0, v68
	v_add_f32_e32 v69, 1.0, v69
	v_mul_f32_e32 v83, 0xbfb8aa3b, v79
	v_rcp_f32_e32 v68, v68
	v_rcp_f32_e32 v69, v69
	v_exp_f32_e32 v83, v83
	v_cvt_pk_bf16_f32 v72, v72, v73
	v_cvt_pk_bf16_f32 v73, v74, v75
	global_store_dwordx2 v[76:77], v[72:73], off offset:32
	v_lshlrev_b32_e32 v72, 16, v118
	v_and_b32_e32 v73, 0xffff0000, v118
	v_lshlrev_b32_e32 v80, 16, v117
	v_and_b32_e32 v81, 0xffff0000, v117
	v_pk_mul_f32 v[68:69], v[68:69], v[72:73]
	v_add_f32_e32 v72, 1.0, v83
	v_add_f32_e32 v70, v70, v102
	v_add_f32_e32 v71, v71, v103
	v_lshlrev_b32_e32 v78, 16, v116
	v_mul_f32_e32 v70, 0xbfb8aa3b, v70
	v_mul_f32_e32 v71, 0xbfb8aa3b, v71
	v_rcp_f32_e32 v83, v72
	v_mul_f32_e32 v72, 0xbfb8aa3b, v80
	v_mul_f32_e32 v73, 0xbfb8aa3b, v81
	v_mul_f32_e32 v82, 0xbfb8aa3b, v78
	v_exp_f32_e32 v70, v70
	v_exp_f32_e32 v71, v71
	v_exp_f32_e32 v72, v72
	v_exp_f32_e32 v73, v73
	v_exp_f32_e32 v82, v82
	v_add_f32_e32 v70, 1.0, v70
	v_add_f32_e32 v71, 1.0, v71
	v_add_f32_e32 v72, 1.0, v72
	v_add_f32_e32 v73, 1.0, v73
	v_add_f32_e32 v82, 1.0, v82
	v_rcp_f32_e32 v70, v70
	v_rcp_f32_e32 v71, v71
	v_rcp_f32_e32 v72, v72
	v_rcp_f32_e32 v73, v73
	v_add_f32_e32 v64, v64, v96
	v_add_f32_e32 v65, v65, v97
	v_rcp_f32_e32 v82, v82
	v_mul_f32_e32 v64, 0xbfb8aa3b, v64
	v_mul_f32_e32 v65, 0xbfb8aa3b, v65
	v_exp_f32_e32 v64, v64
	v_exp_f32_e32 v65, v65
	v_lshlrev_b32_e32 v74, 16, v119
	v_and_b32_e32 v75, 0xffff0000, v119
	v_pk_mul_f32 v[70:71], v[70:71], v[74:75]
	v_pk_mul_f32 v[72:73], v[72:73], v[80:81]
	v_pk_mul_f32 v[78:79], v[82:83], v[78:79]
	v_pk_mul_f32 v[70:71], v[70:71], v[72:73]
	s_waitcnt vmcnt(6)
; DI float sigmoidf_(float x) { return __builtin_amdgcn_rcpf(1.0f + __expf(-x)); }
; DI float siluf_(float x) { return x * sigmoidf_(x); }
; DI void st_bf4(bf16_t* p, float a, float b, float c, float d) { uint2 v; v.x = pack2(a, b); v.y = pack2(c, d); *(uint2*)p = v; }
; DI void phase_g2(const Params& p, const Sub& s, char* lds_all) {
;     ...
;       [&](int row, int col) { const size_t o = (size_t)row * D + col; Ld2 r; const uint2 a = *(const uint2*)(A + o), b = *(const uint2*)(z + o);
;         r.a.x = __uint_as_float(a.x); r.a.y = __uint_as_float(a.y); r.a.z = __uint_as_float(b.x); r.a.w = __uint_as_float(b.y); r.b = *(const float4*)(p.s5_b_glu + col); return r; },
;       [&](int row, int col, f32x4 v, const Ld2& l2) {
;         uint4 ld; ld.x = __float_as_uint(l2.a.x); ld.y = __float_as_uint(l2.a.y); ld.z = __float_as_uint(l2.a.z); ld.w = __float_as_uint(l2.a.w);
;         const size_t o = (size_t)row * D + col;
;         const float y0 = __uint_as_float(ld.x << 16), y1 = __uint_as_float(ld.x & 0xffff0000u), y2_ = __uint_as_float(ld.y << 16), y3 = __uint_as_float(ld.y & 0xffff0000u);
;         const float z0 = __uint_as_float(ld.z << 16), z1 = __uint_as_float(ld.z & 0xffff0000u), z2 = __uint_as_float(ld.w << 16), z3 = __uint_as_float(ld.w & 0xffff0000u);
;         const float4 b4 = l2.b;
;         st_bf4(y2 + o, y0 * sigmoidf_(v[0] + b4.x) * siluf_(z0), y1 * sigmoidf_(v[1] + b4.y) * siluf_(z1),
;                y2_ * sigmoidf_(v[2] + b4.z) * siluf_(z2), y3 * sigmoidf_(v[3] + b4.w) * siluf_(z3));
	v_and_b32_e32 v73, 0xffff0000, v112
	v_pk_mul_f32 v[68:69], v[68:69], v[78:79]
	v_add_f32_e32 v64, 1.0, v64
	v_add_f32_e32 v65, 1.0, v65
	v_mul_f32_e32 v79, 0xbfb8aa3b, v73
	v_rcp_f32_e32 v64, v64
	v_rcp_f32_e32 v65, v65
	v_exp_f32_e32 v79, v79
	v_cvt_pk_bf16_f32 v68, v68, v69
	v_cvt_pk_bf16_f32 v69, v70, v71
	global_store_dwordx2 v[76:77], v[68:69], off offset:256
	v_lshlrev_b32_e32 v68, 16, v114
	v_and_b32_e32 v69, 0xffff0000, v114
	v_lshlrev_b32_e32 v72, 16, v112
	v_lshlrev_b32_e32 v74, 16, v113
	v_and_b32_e32 v75, 0xffff0000, v113
	v_pk_mul_f32 v[64:65], v[64:65], v[68:69]
	v_add_f32_e32 v68, 1.0, v79
	v_add_f32_e32 v66, v66, v98
	v_add_f32_e32 v67, v67, v99
	v_mul_f32_e32 v78, 0xbfb8aa3b, v72
	v_mul_f32_e32 v66, 0xbfb8aa3b, v66
	v_mul_f32_e32 v67, 0xbfb8aa3b, v67
	v_rcp_f32_e32 v79, v68
	v_mul_f32_e32 v68, 0xbfb8aa3b, v74
	v_mul_f32_e32 v69, 0xbfb8aa3b, v75
	v_exp_f32_e32 v78, v78
	v_exp_f32_e32 v66, v66
	v_exp_f32_e32 v67, v67
	v_exp_f32_e32 v68, v68
	v_exp_f32_e32 v69, v69
	v_add_f32_e32 v78, 1.0, v78
	v_add_f32_e32 v66, 1.0, v66
	v_add_f32_e32 v67, 1.0, v67
	v_add_f32_e32 v68, 1.0, v68
	v_add_f32_e32 v69, 1.0, v69
	v_rcp_f32_e32 v78, v78
	v_rcp_f32_e32 v66, v66
	v_rcp_f32_e32 v67, v67
	v_rcp_f32_e32 v68, v68
	v_rcp_f32_e32 v69, v69
	v_lshlrev_b32_e32 v70, 16, v115
	v_and_b32_e32 v71, 0xffff0000, v115
	v_pk_mul_f32 v[72:73], v[78:79], v[72:73]
	v_pk_mul_f32 v[66:67], v[66:67], v[70:71]
	v_pk_mul_f32 v[68:69], v[68:69], v[74:75]
	v_pk_mul_f32 v[64:65], v[64:65], v[72:73]
	v_pk_mul_f32 v[66:67], v[66:67], v[68:69]
	v_add_u32_e32 v102, 0x80, v148
	v_cvt_pk_bf16_f32 v64, v64, v65
	v_cvt_pk_bf16_f32 v65, v66, v67
	v_ashrrev_i32_e32 v103, 31, v102
	global_store_dwordx2 v[76:77], v[64:65], off offset:288
	v_lshlrev_b64 v[64:65], 10, v[102:103]
	v_lshl_add_u64 v[66:67], v[64:65], 0, v[146:147]
	v_lshlrev_b64 v[66:67], 1, v[66:67]
	v_lshl_add_u64 v[68:69], s[10:11], 0, v[66:67]
	v_lshl_add_u64 v[66:67], s[12:13], 0, v[66:67]
	global_load_dwordx2 v[104:105], v[68:69], off
	global_load_dwordx2 v[106:107], v[66:67], off
	global_load_dwordx4 v[76:79], v[154:155], off
	v_lshl_add_u64 v[66:67], v[64:65], 0, v[152:153]
	v_lshlrev_b64 v[66:67], 1, v[66:67]
	v_lshl_add_u64 v[68:69], s[10:11], 0, v[66:67]
	v_lshl_add_u64 v[66:67], s[12:13], 0, v[66:67]
	global_load_dwordx2 v[108:109], v[68:69], off
	global_load_dwordx2 v[110:111], v[66:67], off
	global_load_dwordx4 v[72:75], v[154:155], off offset:64
	v_lshl_add_u64 v[66:67], v[64:65], 0, v[150:151]
	v_lshl_add_u64 v[64:65], v[64:65], 0, v[156:157]
	v_lshlrev_b64 v[66:67], 1, v[66:67]
	v_lshlrev_b64 v[64:65], 1, v[64:65]
	v_lshl_add_u64 v[68:69], s[10:11], 0, v[66:67]
	v_lshl_add_u64 v[66:67], s[12:13], 0, v[66:67]
	v_lshl_add_u64 v[70:71], s[10:11], 0, v[64:65]
	v_lshl_add_u64 v[64:65], s[12:13], 0, v[64:65]
	global_load_dwordx2 v[112:113], v[68:69], off
	global_load_dwordx2 v[114:115], v[66:67], off
	global_load_dwordx2 v[100:101], v[70:71], off
	global_load_dwordx2 v[98:99], v[64:65], off
	s_nop 0
	global_load_dwordx4 v[68:71], v[154:155], off offset:512
	global_load_dwordx4 v[64:67], v[154:155], off offset:576
	v_add_u32_e32 v92, 0x90, v148
	v_ashrrev_i32_e32 v93, 31, v92
	v_lshlrev_b64 v[80:81], 10, v[92:93]
	v_lshl_add_u64 v[82:83], v[80:81], 0, v[146:147]
	v_lshl_add_u64 v[86:87], v[80:81], 0, v[152:153]
	v_lshlrev_b64 v[82:83], 1, v[82:83]
	v_lshlrev_b64 v[86:87], 1, v[86:87]
	v_lshl_add_u64 v[84:85], s[10:11], 0, v[82:83]
	v_lshl_add_u64 v[88:89], s[10:11], 0, v[86:87]
	v_lshl_add_u64 v[82:83], s[12:13], 0, v[82:83]
	v_lshl_add_u64 v[86:87], s[12:13], 0, v[86:87]
	global_load_dwordx2 v[96:97], v[84:85], off
	global_load_dwordx2 v[94:95], v[82:83], off
	global_load_dwordx2 v[90:91], v[88:89], off
	s_nop 0
	global_load_dwordx2 v[88:89], v[86:87], off
	v_lshlrev_b64 v[102:103], 11, v[102:103]
	v_lshl_add_u64 v[102:103], s[14:15], 0, v[102:103]
	v_lshl_add_u64 v[82:83], v[80:81], 0, v[150:151]
	v_lshl_add_u64 v[80:81], v[80:81], 0, v[156:157]
	v_lshlrev_b64 v[82:83], 1, v[82:83]
	v_lshlrev_b64 v[80:81], 1, v[80:81]
	v_lshl_add_u64 v[84:85], s[10:11], 0, v[82:83]
	v_lshl_add_u64 v[82:83], s[12:13], 0, v[82:83]
	v_lshl_add_u64 v[116:117], s[10:11], 0, v[80:81]
	v_lshl_add_u64 v[80:81], s[12:13], 0, v[80:81]
	global_load_dwordx2 v[86:87], v[84:85], off
	s_nop 0
	global_load_dwordx2 v[84:85], v[82:83], off
	s_nop 0
	global_load_dwordx2 v[82:83], v[116:117], off
	s_nop 0
	global_load_dwordx2 v[80:81], v[80:81], off
	s_waitcnt vmcnt(18)
	v_and_b32_e32 v119, 0xffff0000, v106
	s_waitcnt vmcnt(17)
	v_add_f32_e32 v60, v60, v76
	v_mul_f32_e32 v60, 0xbfb8aa3b, v60
	v_exp_f32_e32 v120, v60
	v_add_f32_e32 v60, v61, v77
	v_mul_f32_e32 v60, 0xbfb8aa3b, v60
	v_exp_f32_e32 v121, v60
	v_lshl_add_u64 v[60:61], v[102:103], 0, v[144:145]
	v_add_f32_e32 v102, 1.0, v120
	v_rcp_f32_e32 v102, v102
	v_add_f32_e32 v103, 1.0, v121
	v_mul_f32_e32 v121, 0xbfb8aa3b, v119
	v_rcp_f32_e32 v103, v103
	v_exp_f32_e32 v121, v121
	v_lshlrev_b32_e32 v116, 16, v104
	v_and_b32_e32 v117, 0xffff0000, v104
	v_lshlrev_b32_e32 v118, 16, v106
	v_lshlrev_b32_e32 v106, 16, v107
	v_and_b32_e32 v107, 0xffff0000, v107
	v_pk_mul_f32 v[102:103], v[102:103], v[116:117]
	v_add_f32_e32 v116, 1.0, v121
	v_add_f32_e32 v62, v62, v78
	v_add_f32_e32 v63, v63, v79
	v_mul_f32_e32 v120, 0xbfb8aa3b, v118
	v_mul_f32_e32 v62, 0xbfb8aa3b, v62
	v_mul_f32_e32 v63, 0xbfb8aa3b, v63
	v_rcp_f32_e32 v121, v116
	v_mul_f32_e32 v116, 0xbfb8aa3b, v106
	v_mul_f32_e32 v117, 0xbfb8aa3b, v107
	v_exp_f32_e32 v120, v120
	v_exp_f32_e32 v62, v62
	v_exp_f32_e32 v63, v63
	v_exp_f32_e32 v116, v116
	v_exp_f32_e32 v117, v117
	v_add_f32_e32 v120, 1.0, v120
	v_add_f32_e32 v62, 1.0, v62
	v_add_f32_e32 v63, 1.0, v63
	v_add_f32_e32 v116, 1.0, v116
	v_add_f32_e32 v117, 1.0, v117
	v_rcp_f32_e32 v120, v120
	v_rcp_f32_e32 v62, v62
	v_rcp_f32_e32 v63, v63
	v_rcp_f32_e32 v116, v116
	v_rcp_f32_e32 v117, v117
	s_waitcnt vmcnt(14)
; DI float sigmoidf_(float x) { return __builtin_amdgcn_rcpf(1.0f + __expf(-x)); }
; DI float siluf_(float x) { return x * sigmoidf_(x); }
; DI void st_bf4(bf16_t* p, float a, float b, float c, float d) { uint2 v; v.x = pack2(a, b); v.y = pack2(c, d); *(uint2*)p = v; }
; DI void phase_g2(const Params& p, const Sub& s, char* lds_all) {
;     ...
;       [&](int row, int col) { const size_t o = (size_t)row * D + col; Ld2 r; const uint2 a = *(const uint2*)(A + o), b = *(const uint2*)(z + o);
;         r.a.x = __uint_as_float(a.x); r.a.y = __uint_as_float(a.y); r.a.z = __uint_as_float(b.x); r.a.w = __uint_as_float(b.y); r.b = *(const float4*)(p.s5_b_glu + col); return r; },
;       [&](int row, int col, f32x4 v, const Ld2& l2) {
;         uint4 ld; ld.x = __float_as_uint(l2.a.x); ld.y = __float_as_uint(l2.a.y); ld.z = __float_as_uint(l2.a.z); ld.w = __float_as_uint(l2.a.w);
;         const size_t o = (size_t)row * D + col;
;         const float y0 = __uint_as_float(ld.x << 16), y1 = __uint_as_float(ld.x & 0xffff0000u), y2_ = __uint_as_float(ld.y << 16), y3 = __uint_as_float(ld.y & 0xffff0000u);
;         const float z0 = __uint_as_float(ld.z << 16), z1 = __uint_as_float(ld.z & 0xffff0000u), z2 = __uint_as_float(ld.w << 16), z3 = __uint_as_float(ld.w & 0xffff0000u);
;         const float4 b4 = l2.b;
;         st_bf4(y2 + o, y0 * sigmoidf_(v[0] + b4.x) * siluf_(z0), y1 * sigmoidf_(v[1] + b4.y) * siluf_(z1),
;                y2_ * sigmoidf_(v[2] + b4.z) * siluf_(z2), y3 * sigmoidf_(v[3] + b4.w) * siluf_(z3));
	v_add_f32_e32 v56, v56, v72
	v_add_f32_e32 v57, v57, v73
	v_mul_f32_e32 v56, 0xbfb8aa3b, v56
	v_mul_f32_e32 v57, 0xbfb8aa3b, v57
	v_lshlrev_b32_e32 v104, 16, v105
	v_and_b32_e32 v105, 0xffff0000, v105
	v_exp_f32_e32 v56, v56
	v_exp_f32_e32 v57, v57
	v_pk_mul_f32 v[118:119], v[120:121], v[118:119]
	v_pk_mul_f32 v[62:63], v[62:63], v[104:105]
	v_pk_mul_f32 v[104:105], v[116:117], v[106:107]
	v_pk_mul_f32 v[102:103], v[118:119], v[102:103]
	v_pk_mul_f32 v[62:63], v[104:105], v[62:63]
	v_cvt_pk_bf16_f32 v102, v102, v103
	v_cvt_pk_bf16_f32 v103, v62, v63
	v_and_b32_e32 v105, 0xffff0000, v110
	global_store_dwordx2 v[60:61], v[102:103], off
	v_lshlrev_b32_e32 v102, 16, v109
	v_and_b32_e32 v103, 0xffff0000, v109
	v_add_f32_e32 v56, 1.0, v56
	v_add_f32_e32 v57, 1.0, v57
	v_mul_f32_e32 v109, 0xbfb8aa3b, v105
	v_rcp_f32_e32 v56, v56
	v_rcp_f32_e32 v57, v57
	v_exp_f32_e32 v109, v109
	v_lshlrev_b32_e32 v62, 16, v108
	v_and_b32_e32 v63, 0xffff0000, v108
	v_lshlrev_b32_e32 v106, 16, v111
	v_and_b32_e32 v107, 0xffff0000, v111
	v_pk_mul_f32 v[56:57], v[56:57], v[62:63]
	v_add_f32_e32 v62, 1.0, v109
	v_add_f32_e32 v58, v58, v74
	v_add_f32_e32 v59, v59, v75
	v_lshlrev_b32_e32 v104, 16, v110
	v_mul_f32_e32 v58, 0xbfb8aa3b, v58
	v_mul_f32_e32 v59, 0xbfb8aa3b, v59
	v_rcp_f32_e32 v109, v62
	v_mul_f32_e32 v62, 0xbfb8aa3b, v106
	v_mul_f32_e32 v63, 0xbfb8aa3b, v107
	v_mul_f32_e32 v108, 0xbfb8aa3b, v104
	v_exp_f32_e32 v58, v58
	v_exp_f32_e32 v59, v59
	v_exp_f32_e32 v62, v62
	v_exp_f32_e32 v63, v63
	v_exp_f32_e32 v108, v108
	v_add_f32_e32 v58, 1.0, v58
	v_add_f32_e32 v59, 1.0, v59
	v_add_f32_e32 v62, 1.0, v62
	v_add_f32_e32 v63, 1.0, v63
	v_add_f32_e32 v108, 1.0, v108
	v_rcp_f32_e32 v58, v58
	v_rcp_f32_e32 v59, v59
	v_rcp_f32_e32 v62, v62
	v_rcp_f32_e32 v63, v63
	s_waitcnt vmcnt(10)
	v_add_f32_e32 v52, v52, v68
	v_add_f32_e32 v53, v53, v69
	v_rcp_f32_e32 v108, v108
	v_mul_f32_e32 v52, 0xbfb8aa3b, v52
	v_mul_f32_e32 v53, 0xbfb8aa3b, v53
	v_exp_f32_e32 v52, v52
	v_exp_f32_e32 v53, v53
	v_pk_mul_f32 v[58:59], v[58:59], v[102:103]
	v_pk_mul_f32 v[62:63], v[62:63], v[106:107]
	v_pk_mul_f32 v[104:105], v[108:109], v[104:105]
	v_pk_mul_f32 v[58:59], v[62:63], v[58:59]
	v_and_b32_e32 v63, 0xffff0000, v114
	v_pk_mul_f32 v[56:57], v[104:105], v[56:57]
	v_add_f32_e32 v52, 1.0, v52
	v_add_f32_e32 v53, 1.0, v53
	v_mul_f32_e32 v105, 0xbfb8aa3b, v63
	v_rcp_f32_e32 v52, v52
	v_rcp_f32_e32 v53, v53
	v_exp_f32_e32 v105, v105
	v_cvt_pk_bf16_f32 v56, v56, v57
	v_cvt_pk_bf16_f32 v57, v58, v59
	global_store_dwordx2 v[60:61], v[56:57], off offset:32
	v_lshlrev_b32_e32 v56, 16, v112
	v_and_b32_e32 v57, 0xffff0000, v112
	v_lshlrev_b32_e32 v102, 16, v115
	v_and_b32_e32 v103, 0xffff0000, v115
	v_pk_mul_f32 v[52:53], v[52:53], v[56:57]
	v_add_f32_e32 v56, 1.0, v105
	v_add_f32_e32 v54, v54, v70
	v_add_f32_e32 v55, v55, v71
	v_lshlrev_b32_e32 v62, 16, v114
	v_mul_f32_e32 v54, 0xbfb8aa3b, v54
	v_mul_f32_e32 v55, 0xbfb8aa3b, v55
	v_rcp_f32_e32 v105, v56
	v_mul_f32_e32 v56, 0xbfb8aa3b, v102
	v_mul_f32_e32 v57, 0xbfb8aa3b, v103
	v_mul_f32_e32 v104, 0xbfb8aa3b, v62
	v_exp_f32_e32 v54, v54
	v_exp_f32_e32 v55, v55
	v_exp_f32_e32 v56, v56
	v_exp_f32_e32 v57, v57
	v_exp_f32_e32 v104, v104
	v_add_f32_e32 v54, 1.0, v54
	v_add_f32_e32 v55, 1.0, v55
	v_add_f32_e32 v56, 1.0, v56
	v_add_f32_e32 v57, 1.0, v57
	v_add_f32_e32 v104, 1.0, v104
	v_rcp_f32_e32 v54, v54
	v_rcp_f32_e32 v55, v55
	v_rcp_f32_e32 v56, v56
	v_rcp_f32_e32 v57, v57
	s_waitcnt vmcnt(10)
	v_add_f32_e32 v48, v48, v64
	v_add_f32_e32 v49, v49, v65
	v_rcp_f32_e32 v104, v104
	v_mul_f32_e32 v48, 0xbfb8aa3b, v48
	v_mul_f32_e32 v49, 0xbfb8aa3b, v49
	v_exp_f32_e32 v48, v48
	v_exp_f32_e32 v49, v49
	v_lshlrev_b32_e32 v58, 16, v113
	v_and_b32_e32 v59, 0xffff0000, v113
	v_pk_mul_f32 v[54:55], v[54:55], v[58:59]
	v_pk_mul_f32 v[56:57], v[56:57], v[102:103]
	v_pk_mul_f32 v[62:63], v[104:105], v[62:63]
	v_pk_mul_f32 v[54:55], v[56:57], v[54:55]
	v_and_b32_e32 v57, 0xffff0000, v98
	v_pk_mul_f32 v[52:53], v[62:63], v[52:53]
	v_add_f32_e32 v48, 1.0, v48
	v_add_f32_e32 v49, 1.0, v49
	v_mul_f32_e32 v63, 0xbfb8aa3b, v57
	v_rcp_f32_e32 v48, v48
	v_rcp_f32_e32 v49, v49
	v_exp_f32_e32 v63, v63
	v_cvt_pk_bf16_f32 v52, v52, v53
	v_cvt_pk_bf16_f32 v53, v54, v55
	global_store_dwordx2 v[60:61], v[52:53], off offset:256
	v_lshlrev_b32_e32 v52, 16, v100
	v_and_b32_e32 v53, 0xffff0000, v100
	v_lshlrev_b32_e32 v58, 16, v99
	v_and_b32_e32 v59, 0xffff0000, v99
	v_pk_mul_f32 v[48:49], v[48:49], v[52:53]
	v_add_f32_e32 v52, 1.0, v63
	v_lshlrev_b32_e32 v56, 16, v98
	v_add_f32_e32 v50, v50, v66
	v_add_f32_e32 v51, v51, v67
	v_rcp_f32_e32 v63, v52
	v_mul_f32_e32 v52, 0xbfb8aa3b, v58
	v_mul_f32_e32 v53, 0xbfb8aa3b, v59
	v_mul_f32_e32 v62, 0xbfb8aa3b, v56
	v_mul_f32_e32 v50, 0xbfb8aa3b, v50
	v_mul_f32_e32 v51, 0xbfb8aa3b, v51
	v_exp_f32_e32 v52, v52
	v_exp_f32_e32 v53, v53
	v_exp_f32_e32 v62, v62
	v_exp_f32_e32 v50, v50
	v_exp_f32_e32 v51, v51
	v_add_f32_e32 v52, 1.0, v52
	v_add_f32_e32 v53, 1.0, v53
	v_add_f32_e32 v62, 1.0, v62
	v_add_f32_e32 v50, 1.0, v50
	v_add_f32_e32 v51, 1.0, v51
	v_rcp_f32_e32 v52, v52
	v_rcp_f32_e32 v53, v53
	v_rcp_f32_e32 v62, v62
	v_rcp_f32_e32 v50, v50
	v_rcp_f32_e32 v51, v51
	v_add_f32_e32 v44, v44, v76
	v_mul_f32_e32 v44, 0xbfb8aa3b, v44
	v_lshlrev_b32_e32 v54, 16, v101
	v_and_b32_e32 v55, 0xffff0000, v101
	v_pk_mul_f32 v[52:53], v[52:53], v[58:59]
	v_exp_f32_e32 v58, v44
	v_add_f32_e32 v44, v45, v77
	v_pk_mul_f32 v[56:57], v[62:63], v[56:57]
	v_pk_mul_f32 v[50:51], v[50:51], v[54:55]
	v_mul_f32_e32 v44, 0xbfb8aa3b, v44
	v_pk_mul_f32 v[48:49], v[56:57], v[48:49]
	v_pk_mul_f32 v[50:51], v[52:53], v[50:51]
	v_exp_f32_e32 v59, v44
	v_cvt_pk_bf16_f32 v48, v48, v49
	v_cvt_pk_bf16_f32 v49, v50, v51
	global_store_dwordx2 v[60:61], v[48:49], off offset:288
	v_lshlrev_b64 v[48:49], 11, v[92:93]
	s_waitcnt vmcnt(10)
; DI float sigmoidf_(float x) { return __builtin_amdgcn_rcpf(1.0f + __expf(-x)); }
; DI float siluf_(float x) { return x * sigmoidf_(x); }
; DI void st_bf4(bf16_t* p, float a, float b, float c, float d) { uint2 v; v.x = pack2(a, b); v.y = pack2(c, d); *(uint2*)p = v; }
; DI void phase_g2(const Params& p, const Sub& s, char* lds_all) {
;     ...
;       [&](int row, int col) { const size_t o = (size_t)row * D + col; Ld2 r; const uint2 a = *(const uint2*)(A + o), b = *(const uint2*)(z + o);
;         r.a.x = __uint_as_float(a.x); r.a.y = __uint_as_float(a.y); r.a.z = __uint_as_float(b.x); r.a.w = __uint_as_float(b.y); r.b = *(const float4*)(p.s5_b_glu + col); return r; },
;       [&](int row, int col, f32x4 v, const Ld2& l2) {
;         uint4 ld; ld.x = __float_as_uint(l2.a.x); ld.y = __float_as_uint(l2.a.y); ld.z = __float_as_uint(l2.a.z); ld.w = __float_as_uint(l2.a.w);
;         const size_t o = (size_t)row * D + col;
;         const float y0 = __uint_as_float(ld.x << 16), y1 = __uint_as_float(ld.x & 0xffff0000u), y2_ = __uint_as_float(ld.y << 16), y3 = __uint_as_float(ld.y & 0xffff0000u);
;         const float z0 = __uint_as_float(ld.z << 16), z1 = __uint_as_float(ld.z & 0xffff0000u), z2 = __uint_as_float(ld.w << 16), z3 = __uint_as_float(ld.w & 0xffff0000u);
;         const float4 b4 = l2.b;
;         st_bf4(y2 + o, y0 * sigmoidf_(v[0] + b4.x) * siluf_(z0), y1 * sigmoidf_(v[1] + b4.y) * siluf_(z1),
;                y2_ * sigmoidf_(v[2] + b4.z) * siluf_(z2), y3 * sigmoidf_(v[3] + b4.w) * siluf_(z3));
	v_and_b32_e32 v55, 0xffff0000, v94
	v_lshl_add_u64 v[48:49], s[14:15], 0, v[48:49]
	v_lshl_add_u64 v[44:45], v[48:49], 0, v[144:145]
	v_add_f32_e32 v48, 1.0, v58
	v_add_f32_e32 v49, 1.0, v59
	v_mul_f32_e32 v59, 0xbfb8aa3b, v55
	v_rcp_f32_e32 v48, v48
	v_rcp_f32_e32 v49, v49
	v_exp_f32_e32 v59, v59
	v_lshlrev_b32_e32 v50, 16, v96
	v_and_b32_e32 v51, 0xffff0000, v96
	v_lshlrev_b32_e32 v56, 16, v95
	v_and_b32_e32 v57, 0xffff0000, v95
	v_pk_mul_f32 v[48:49], v[48:49], v[50:51]
	v_add_f32_e32 v50, 1.0, v59
	v_add_f32_e32 v46, v46, v78
	v_add_f32_e32 v47, v47, v79
	v_lshlrev_b32_e32 v54, 16, v94
	v_mul_f32_e32 v46, 0xbfb8aa3b, v46
	v_mul_f32_e32 v47, 0xbfb8aa3b, v47
	v_rcp_f32_e32 v59, v50
	v_mul_f32_e32 v50, 0xbfb8aa3b, v56
	v_mul_f32_e32 v51, 0xbfb8aa3b, v57
	v_mul_f32_e32 v58, 0xbfb8aa3b, v54
	v_exp_f32_e32 v46, v46
	v_exp_f32_e32 v47, v47
	v_exp_f32_e32 v50, v50
	v_exp_f32_e32 v51, v51
	v_exp_f32_e32 v58, v58
	v_add_f32_e32 v46, 1.0, v46
	v_add_f32_e32 v47, 1.0, v47
	v_add_f32_e32 v50, 1.0, v50
	v_add_f32_e32 v51, 1.0, v51
	v_add_f32_e32 v58, 1.0, v58
	v_rcp_f32_e32 v46, v46
	v_rcp_f32_e32 v47, v47
	v_rcp_f32_e32 v50, v50
	v_rcp_f32_e32 v51, v51
	v_add_f32_e32 v40, v40, v72
	v_add_f32_e32 v41, v41, v73
	v_rcp_f32_e32 v58, v58
	v_mul_f32_e32 v40, 0xbfb8aa3b, v40
	v_mul_f32_e32 v41, 0xbfb8aa3b, v41
	v_exp_f32_e32 v40, v40
	v_exp_f32_e32 v41, v41
	v_lshlrev_b32_e32 v52, 16, v97
	v_and_b32_e32 v53, 0xffff0000, v97
	v_pk_mul_f32 v[46:47], v[46:47], v[52:53]
	v_pk_mul_f32 v[50:51], v[50:51], v[56:57]
	v_pk_mul_f32 v[54:55], v[58:59], v[54:55]
	v_pk_mul_f32 v[46:47], v[46:47], v[50:51]
	s_waitcnt vmcnt(8)
	v_and_b32_e32 v51, 0xffff0000, v88
	v_pk_mul_f32 v[48:49], v[48:49], v[54:55]
	v_add_f32_e32 v40, 1.0, v40
	v_add_f32_e32 v41, 1.0, v41
	v_mul_f32_e32 v55, 0xbfb8aa3b, v51
	v_rcp_f32_e32 v40, v40
	v_rcp_f32_e32 v41, v41
	v_exp_f32_e32 v55, v55
	v_cvt_pk_bf16_f32 v48, v48, v49
	v_cvt_pk_bf16_f32 v49, v46, v47
	v_lshlrev_b32_e32 v46, 16, v90
	v_and_b32_e32 v47, 0xffff0000, v90
	v_lshlrev_b32_e32 v52, 16, v89
	v_and_b32_e32 v53, 0xffff0000, v89
	v_pk_mul_f32 v[40:41], v[40:41], v[46:47]
	v_add_f32_e32 v46, 1.0, v55
	v_add_f32_e32 v42, v42, v74
	v_add_f32_e32 v43, v43, v75
	v_lshlrev_b32_e32 v50, 16, v88
	v_mul_f32_e32 v42, 0xbfb8aa3b, v42
	v_mul_f32_e32 v43, 0xbfb8aa3b, v43
	v_rcp_f32_e32 v55, v46
	v_mul_f32_e32 v46, 0xbfb8aa3b, v52
	v_mul_f32_e32 v47, 0xbfb8aa3b, v53
	v_mul_f32_e32 v54, 0xbfb8aa3b, v50
	v_exp_f32_e32 v42, v42
	v_exp_f32_e32 v43, v43
	v_exp_f32_e32 v46, v46
	v_exp_f32_e32 v47, v47
	v_exp_f32_e32 v54, v54
	v_add_f32_e32 v42, 1.0, v42
	v_add_f32_e32 v43, 1.0, v43
	v_add_f32_e32 v46, 1.0, v46
	v_add_f32_e32 v47, 1.0, v47
	v_add_f32_e32 v54, 1.0, v54
	v_rcp_f32_e32 v42, v42
	v_rcp_f32_e32 v43, v43
	v_rcp_f32_e32 v46, v46
	v_rcp_f32_e32 v47, v47
	v_add_f32_e32 v36, v36, v68
	v_add_f32_e32 v37, v37, v69
	v_rcp_f32_e32 v54, v54
	v_mul_f32_e32 v36, 0xbfb8aa3b, v36
	v_mul_f32_e32 v37, 0xbfb8aa3b, v37
	v_exp_f32_e32 v36, v36
	v_exp_f32_e32 v37, v37
	global_store_dwordx2 v[44:45], v[48:49], off
	v_lshlrev_b32_e32 v48, 16, v91
	v_and_b32_e32 v49, 0xffff0000, v91
	v_pk_mul_f32 v[42:43], v[42:43], v[48:49]
	v_pk_mul_f32 v[46:47], v[46:47], v[52:53]
	v_pk_mul_f32 v[50:51], v[54:55], v[50:51]
	v_pk_mul_f32 v[42:43], v[42:43], v[46:47]
	s_waitcnt vmcnt(7)
	v_and_b32_e32 v47, 0xffff0000, v84
	v_pk_mul_f32 v[40:41], v[40:41], v[50:51]
	v_add_f32_e32 v36, 1.0, v36
	v_add_f32_e32 v37, 1.0, v37
	v_mul_f32_e32 v51, 0xbfb8aa3b, v47
	v_rcp_f32_e32 v36, v36
	v_rcp_f32_e32 v37, v37
	v_exp_f32_e32 v51, v51
	v_cvt_pk_bf16_f32 v40, v40, v41
	v_cvt_pk_bf16_f32 v41, v42, v43
	global_store_dwordx2 v[44:45], v[40:41], off offset:32
	v_lshlrev_b32_e32 v40, 16, v86
	v_and_b32_e32 v41, 0xffff0000, v86
	v_lshlrev_b32_e32 v48, 16, v85
	v_and_b32_e32 v49, 0xffff0000, v85
	v_pk_mul_f32 v[36:37], v[36:37], v[40:41]
	v_add_f32_e32 v40, 1.0, v51
	v_add_f32_e32 v38, v38, v70
	v_add_f32_e32 v39, v39, v71
	v_lshlrev_b32_e32 v46, 16, v84
	v_mul_f32_e32 v38, 0xbfb8aa3b, v38
	v_mul_f32_e32 v39, 0xbfb8aa3b, v39
	v_rcp_f32_e32 v51, v40
	v_mul_f32_e32 v40, 0xbfb8aa3b, v48
	v_mul_f32_e32 v41, 0xbfb8aa3b, v49
	v_mul_f32_e32 v50, 0xbfb8aa3b, v46
	v_exp_f32_e32 v38, v38
	v_exp_f32_e32 v39, v39
	v_exp_f32_e32 v40, v40
	v_exp_f32_e32 v41, v41
	v_exp_f32_e32 v50, v50
	v_add_f32_e32 v38, 1.0, v38
	v_add_f32_e32 v39, 1.0, v39
	v_add_f32_e32 v40, 1.0, v40
	v_add_f32_e32 v41, 1.0, v41
	v_add_f32_e32 v50, 1.0, v50
	v_rcp_f32_e32 v38, v38
	v_rcp_f32_e32 v39, v39
	v_rcp_f32_e32 v40, v40
	v_rcp_f32_e32 v41, v41
	v_add_f32_e32 v32, v32, v64
	v_add_f32_e32 v33, v33, v65
	v_rcp_f32_e32 v50, v50
	v_mul_f32_e32 v32, 0xbfb8aa3b, v32
	v_mul_f32_e32 v33, 0xbfb8aa3b, v33
	v_exp_f32_e32 v32, v32
	v_exp_f32_e32 v33, v33
	v_lshlrev_b32_e32 v42, 16, v87
	v_and_b32_e32 v43, 0xffff0000, v87
	v_pk_mul_f32 v[38:39], v[38:39], v[42:43]
	v_pk_mul_f32 v[40:41], v[40:41], v[48:49]
	v_pk_mul_f32 v[46:47], v[50:51], v[46:47]
	v_pk_mul_f32 v[38:39], v[38:39], v[40:41]
	s_waitcnt vmcnt(6)
; DI float sigmoidf_(float x) { return __builtin_amdgcn_rcpf(1.0f + __expf(-x)); }
; DI float siluf_(float x) { return x * sigmoidf_(x); }
; DI void st_bf4(bf16_t* p, float a, float b, float c, float d) { uint2 v; v.x = pack2(a, b); v.y = pack2(c, d); *(uint2*)p = v; }
; DI void phase_g2(const Params& p, const Sub& s, char* lds_all) {
;     ...
;       [&](int row, int col) { const size_t o = (size_t)row * D + col; Ld2 r; const uint2 a = *(const uint2*)(A + o), b = *(const uint2*)(z + o);
;         r.a.x = __uint_as_float(a.x); r.a.y = __uint_as_float(a.y); r.a.z = __uint_as_float(b.x); r.a.w = __uint_as_float(b.y); r.b = *(const float4*)(p.s5_b_glu + col); return r; },
;       [&](int row, int col, f32x4 v, const Ld2& l2) {
;         uint4 ld; ld.x = __float_as_uint(l2.a.x); ld.y = __float_as_uint(l2.a.y); ld.z = __float_as_uint(l2.a.z); ld.w = __float_as_uint(l2.a.w);
;         const size_t o = (size_t)row * D + col;
;         const float y0 = __uint_as_float(ld.x << 16), y1 = __uint_as_float(ld.x & 0xffff0000u), y2_ = __uint_as_float(ld.y << 16), y3 = __uint_as_float(ld.y & 0xffff0000u);
;         const float z0 = __uint_as_float(ld.z << 16), z1 = __uint_as_float(ld.z & 0xffff0000u), z2 = __uint_as_float(ld.w << 16), z3 = __uint_as_float(ld.w & 0xffff0000u);
;         const float4 b4 = l2.b;
;         st_bf4(y2 + o, y0 * sigmoidf_(v[0] + b4.x) * siluf_(z0), y1 * sigmoidf_(v[1] + b4.y) * siluf_(z1),
;                y2_ * sigmoidf_(v[2] + b4.z) * siluf_(z2), y3 * sigmoidf_(v[3] + b4.w) * siluf_(z3));
	v_and_b32_e32 v41, 0xffff0000, v80
	v_pk_mul_f32 v[36:37], v[36:37], v[46:47]
	v_add_f32_e32 v32, 1.0, v32
	v_add_f32_e32 v33, 1.0, v33
	v_mul_f32_e32 v47, 0xbfb8aa3b, v41
	v_rcp_f32_e32 v32, v32
	v_rcp_f32_e32 v33, v33
	v_exp_f32_e32 v47, v47
	v_cvt_pk_bf16_f32 v36, v36, v37
	v_cvt_pk_bf16_f32 v37, v38, v39
	global_store_dwordx2 v[44:45], v[36:37], off offset:256
	v_lshlrev_b32_e32 v36, 16, v82
	v_and_b32_e32 v37, 0xffff0000, v82
	v_lshlrev_b32_e32 v40, 16, v80
	v_lshlrev_b32_e32 v42, 16, v81
	v_and_b32_e32 v43, 0xffff0000, v81
	v_pk_mul_f32 v[32:33], v[32:33], v[36:37]
	v_add_f32_e32 v36, 1.0, v47
	v_add_f32_e32 v34, v34, v66
	v_add_f32_e32 v35, v35, v67
	v_mul_f32_e32 v46, 0xbfb8aa3b, v40
	v_mul_f32_e32 v34, 0xbfb8aa3b, v34
	v_mul_f32_e32 v35, 0xbfb8aa3b, v35
	v_rcp_f32_e32 v47, v36
	v_mul_f32_e32 v36, 0xbfb8aa3b, v42
	v_mul_f32_e32 v37, 0xbfb8aa3b, v43
	v_exp_f32_e32 v46, v46
	v_exp_f32_e32 v34, v34
	v_exp_f32_e32 v35, v35
	v_exp_f32_e32 v36, v36
	v_exp_f32_e32 v37, v37
	v_add_f32_e32 v46, 1.0, v46
	v_add_f32_e32 v34, 1.0, v34
	v_add_f32_e32 v35, 1.0, v35
	v_add_f32_e32 v36, 1.0, v36
	v_add_f32_e32 v37, 1.0, v37
	v_rcp_f32_e32 v46, v46
	v_rcp_f32_e32 v34, v34
	v_rcp_f32_e32 v35, v35
	v_rcp_f32_e32 v36, v36
	v_rcp_f32_e32 v37, v37
	v_lshlrev_b32_e32 v38, 16, v83
	v_and_b32_e32 v39, 0xffff0000, v83
	v_pk_mul_f32 v[40:41], v[46:47], v[40:41]
	v_pk_mul_f32 v[34:35], v[34:35], v[38:39]
	v_pk_mul_f32 v[36:37], v[36:37], v[42:43]
	v_pk_mul_f32 v[32:33], v[32:33], v[40:41]
	v_pk_mul_f32 v[34:35], v[34:35], v[36:37]
	v_add_u32_e32 v70, 0xa0, v148
	v_cvt_pk_bf16_f32 v32, v32, v33
	v_cvt_pk_bf16_f32 v33, v34, v35
	v_ashrrev_i32_e32 v71, 31, v70
	global_store_dwordx2 v[44:45], v[32:33], off offset:288
	v_lshlrev_b64 v[32:33], 10, v[70:71]
	v_lshl_add_u64 v[34:35], v[32:33], 0, v[146:147]
	v_lshlrev_b64 v[34:35], 1, v[34:35]
	v_lshl_add_u64 v[36:37], s[10:11], 0, v[34:35]
	v_lshl_add_u64 v[34:35], s[12:13], 0, v[34:35]
	global_load_dwordx2 v[72:73], v[36:37], off
	global_load_dwordx2 v[74:75], v[34:35], off
	global_load_dwordx4 v[44:47], v[154:155], off
	v_lshl_add_u64 v[34:35], v[32:33], 0, v[152:153]
	v_lshlrev_b64 v[34:35], 1, v[34:35]
	v_lshl_add_u64 v[36:37], s[10:11], 0, v[34:35]
	v_lshl_add_u64 v[34:35], s[12:13], 0, v[34:35]
	global_load_dwordx2 v[76:77], v[36:37], off
	global_load_dwordx2 v[78:79], v[34:35], off
	global_load_dwordx4 v[40:43], v[154:155], off offset:64
	v_lshl_add_u64 v[34:35], v[32:33], 0, v[150:151]
	v_lshl_add_u64 v[32:33], v[32:33], 0, v[156:157]
	v_lshlrev_b64 v[34:35], 1, v[34:35]
	v_lshlrev_b64 v[32:33], 1, v[32:33]
	v_lshl_add_u64 v[36:37], s[10:11], 0, v[34:35]
	v_lshl_add_u64 v[34:35], s[12:13], 0, v[34:35]
	v_lshl_add_u64 v[38:39], s[10:11], 0, v[32:33]
	v_lshl_add_u64 v[32:33], s[12:13], 0, v[32:33]
	global_load_dwordx2 v[80:81], v[36:37], off
	global_load_dwordx2 v[82:83], v[34:35], off
	global_load_dwordx2 v[68:69], v[38:39], off
	global_load_dwordx2 v[66:67], v[32:33], off
	s_nop 0
	global_load_dwordx4 v[36:39], v[154:155], off offset:512
	global_load_dwordx4 v[32:35], v[154:155], off offset:576
	v_add_u32_e32 v60, 0xb0, v148
	v_ashrrev_i32_e32 v61, 31, v60
	v_lshlrev_b64 v[48:49], 10, v[60:61]
	v_lshl_add_u64 v[50:51], v[48:49], 0, v[146:147]
	v_lshl_add_u64 v[54:55], v[48:49], 0, v[152:153]
	v_lshlrev_b64 v[50:51], 1, v[50:51]
	v_lshlrev_b64 v[54:55], 1, v[54:55]
	v_lshl_add_u64 v[52:53], s[10:11], 0, v[50:51]
	v_lshl_add_u64 v[56:57], s[10:11], 0, v[54:55]
	v_lshl_add_u64 v[50:51], s[12:13], 0, v[50:51]
	v_lshl_add_u64 v[54:55], s[12:13], 0, v[54:55]
	global_load_dwordx2 v[64:65], v[52:53], off
	global_load_dwordx2 v[62:63], v[50:51], off
	global_load_dwordx2 v[58:59], v[56:57], off
	s_nop 0
	global_load_dwordx2 v[56:57], v[54:55], off
	v_lshlrev_b64 v[70:71], 11, v[70:71]
	v_lshl_add_u64 v[70:71], s[14:15], 0, v[70:71]
	v_lshl_add_u64 v[50:51], v[48:49], 0, v[150:151]
	v_lshl_add_u64 v[48:49], v[48:49], 0, v[156:157]
	v_lshlrev_b64 v[50:51], 1, v[50:51]
	v_lshlrev_b64 v[48:49], 1, v[48:49]
	v_lshl_add_u64 v[52:53], s[10:11], 0, v[50:51]
	v_lshl_add_u64 v[50:51], s[12:13], 0, v[50:51]
	v_lshl_add_u64 v[84:85], s[10:11], 0, v[48:49]
	v_lshl_add_u64 v[48:49], s[12:13], 0, v[48:49]
	global_load_dwordx2 v[54:55], v[52:53], off
	s_nop 0
	global_load_dwordx2 v[52:53], v[50:51], off
	s_nop 0
	global_load_dwordx2 v[50:51], v[84:85], off
	s_nop 0
	global_load_dwordx2 v[48:49], v[48:49], off
	s_waitcnt vmcnt(18)
	v_and_b32_e32 v87, 0xffff0000, v74
	s_waitcnt vmcnt(17)
	v_add_f32_e32 v28, v28, v44
	v_mul_f32_e32 v28, 0xbfb8aa3b, v28
	v_exp_f32_e32 v88, v28
	v_add_f32_e32 v28, v29, v45
	v_mul_f32_e32 v28, 0xbfb8aa3b, v28
	v_exp_f32_e32 v89, v28
	v_lshl_add_u64 v[28:29], v[70:71], 0, v[144:145]
	v_add_f32_e32 v70, 1.0, v88
	v_rcp_f32_e32 v70, v70
	v_add_f32_e32 v71, 1.0, v89
	v_mul_f32_e32 v89, 0xbfb8aa3b, v87
	v_rcp_f32_e32 v71, v71
	v_exp_f32_e32 v89, v89
	v_lshlrev_b32_e32 v84, 16, v72
	v_and_b32_e32 v85, 0xffff0000, v72
	v_lshlrev_b32_e32 v86, 16, v74
	v_lshlrev_b32_e32 v74, 16, v75
	v_and_b32_e32 v75, 0xffff0000, v75
	v_pk_mul_f32 v[70:71], v[70:71], v[84:85]
	v_add_f32_e32 v84, 1.0, v89
	v_add_f32_e32 v30, v30, v46
	v_add_f32_e32 v31, v31, v47
	v_mul_f32_e32 v88, 0xbfb8aa3b, v86
	v_mul_f32_e32 v30, 0xbfb8aa3b, v30
	v_mul_f32_e32 v31, 0xbfb8aa3b, v31
	v_rcp_f32_e32 v89, v84
	v_mul_f32_e32 v84, 0xbfb8aa3b, v74
	v_mul_f32_e32 v85, 0xbfb8aa3b, v75
	v_exp_f32_e32 v88, v88
	v_exp_f32_e32 v30, v30
	v_exp_f32_e32 v31, v31
	v_exp_f32_e32 v84, v84
	v_exp_f32_e32 v85, v85
	v_add_f32_e32 v88, 1.0, v88
	v_add_f32_e32 v30, 1.0, v30
	v_add_f32_e32 v31, 1.0, v31
	v_add_f32_e32 v84, 1.0, v84
	v_add_f32_e32 v85, 1.0, v85
	v_rcp_f32_e32 v88, v88
	v_rcp_f32_e32 v30, v30
	v_rcp_f32_e32 v31, v31
	v_rcp_f32_e32 v84, v84
	v_rcp_f32_e32 v85, v85
	s_waitcnt vmcnt(14)
; DI float sigmoidf_(float x) { return __builtin_amdgcn_rcpf(1.0f + __expf(-x)); }
; DI float siluf_(float x) { return x * sigmoidf_(x); }
; DI void st_bf4(bf16_t* p, float a, float b, float c, float d) { uint2 v; v.x = pack2(a, b); v.y = pack2(c, d); *(uint2*)p = v; }
; DI void phase_g2(const Params& p, const Sub& s, char* lds_all) {
;     ...
;       [&](int row, int col) { const size_t o = (size_t)row * D + col; Ld2 r; const uint2 a = *(const uint2*)(A + o), b = *(const uint2*)(z + o);
;         r.a.x = __uint_as_float(a.x); r.a.y = __uint_as_float(a.y); r.a.z = __uint_as_float(b.x); r.a.w = __uint_as_float(b.y); r.b = *(const float4*)(p.s5_b_glu + col); return r; },
;       [&](int row, int col, f32x4 v, const Ld2& l2) {
;         uint4 ld; ld.x = __float_as_uint(l2.a.x); ld.y = __float_as_uint(l2.a.y); ld.z = __float_as_uint(l2.a.z); ld.w = __float_as_uint(l2.a.w);
;         const size_t o = (size_t)row * D + col;
;         const float y0 = __uint_as_float(ld.x << 16), y1 = __uint_as_float(ld.x & 0xffff0000u), y2_ = __uint_as_float(ld.y << 16), y3 = __uint_as_float(ld.y & 0xffff0000u);
;         const float z0 = __uint_as_float(ld.z << 16), z1 = __uint_as_float(ld.z & 0xffff0000u), z2 = __uint_as_float(ld.w << 16), z3 = __uint_as_float(ld.w & 0xffff0000u);
;         const float4 b4 = l2.b;
;         st_bf4(y2 + o, y0 * sigmoidf_(v[0] + b4.x) * siluf_(z0), y1 * sigmoidf_(v[1] + b4.y) * siluf_(z1),
;                y2_ * sigmoidf_(v[2] + b4.z) * siluf_(z2), y3 * sigmoidf_(v[3] + b4.w) * siluf_(z3));
	v_add_f32_e32 v24, v24, v40
	v_add_f32_e32 v25, v25, v41
	v_mul_f32_e32 v24, 0xbfb8aa3b, v24
	v_mul_f32_e32 v25, 0xbfb8aa3b, v25
	v_lshlrev_b32_e32 v72, 16, v73
	v_and_b32_e32 v73, 0xffff0000, v73
	v_exp_f32_e32 v24, v24
	v_exp_f32_e32 v25, v25
	v_pk_mul_f32 v[86:87], v[88:89], v[86:87]
	v_pk_mul_f32 v[30:31], v[30:31], v[72:73]
	v_pk_mul_f32 v[72:73], v[84:85], v[74:75]
	v_pk_mul_f32 v[70:71], v[86:87], v[70:71]
	v_pk_mul_f32 v[30:31], v[72:73], v[30:31]
	v_cvt_pk_bf16_f32 v70, v70, v71
	v_cvt_pk_bf16_f32 v71, v30, v31
	v_and_b32_e32 v73, 0xffff0000, v78
	global_store_dwordx2 v[28:29], v[70:71], off
	v_lshlrev_b32_e32 v70, 16, v77
	v_and_b32_e32 v71, 0xffff0000, v77
	v_add_f32_e32 v24, 1.0, v24
	v_add_f32_e32 v25, 1.0, v25
	v_mul_f32_e32 v77, 0xbfb8aa3b, v73
	v_rcp_f32_e32 v24, v24
	v_rcp_f32_e32 v25, v25
	v_exp_f32_e32 v77, v77
	v_lshlrev_b32_e32 v30, 16, v76
	v_and_b32_e32 v31, 0xffff0000, v76
	v_lshlrev_b32_e32 v74, 16, v79
	v_and_b32_e32 v75, 0xffff0000, v79
	v_pk_mul_f32 v[24:25], v[24:25], v[30:31]
	v_add_f32_e32 v30, 1.0, v77
	v_add_f32_e32 v26, v26, v42
	v_add_f32_e32 v27, v27, v43
	v_lshlrev_b32_e32 v72, 16, v78
	v_mul_f32_e32 v26, 0xbfb8aa3b, v26
	v_mul_f32_e32 v27, 0xbfb8aa3b, v27
	v_rcp_f32_e32 v77, v30
	v_mul_f32_e32 v30, 0xbfb8aa3b, v74
	v_mul_f32_e32 v31, 0xbfb8aa3b, v75
	v_mul_f32_e32 v76, 0xbfb8aa3b, v72
	v_exp_f32_e32 v26, v26
	v_exp_f32_e32 v27, v27
	v_exp_f32_e32 v30, v30
	v_exp_f32_e32 v31, v31
	v_exp_f32_e32 v76, v76
	v_add_f32_e32 v26, 1.0, v26
	v_add_f32_e32 v27, 1.0, v27
	v_add_f32_e32 v30, 1.0, v30
	v_add_f32_e32 v31, 1.0, v31
	v_add_f32_e32 v76, 1.0, v76
	v_rcp_f32_e32 v26, v26
	v_rcp_f32_e32 v27, v27
	v_rcp_f32_e32 v30, v30
	v_rcp_f32_e32 v31, v31
	s_waitcnt vmcnt(10)
	v_add_f32_e32 v20, v20, v36
	v_add_f32_e32 v21, v21, v37
	v_rcp_f32_e32 v76, v76
	v_mul_f32_e32 v20, 0xbfb8aa3b, v20
	v_mul_f32_e32 v21, 0xbfb8aa3b, v21
	v_exp_f32_e32 v20, v20
	v_exp_f32_e32 v21, v21
	v_pk_mul_f32 v[26:27], v[26:27], v[70:71]
	v_pk_mul_f32 v[30:31], v[30:31], v[74:75]
	v_pk_mul_f32 v[72:73], v[76:77], v[72:73]
	v_pk_mul_f32 v[26:27], v[30:31], v[26:27]
	v_and_b32_e32 v31, 0xffff0000, v82
	v_pk_mul_f32 v[24:25], v[72:73], v[24:25]
	v_add_f32_e32 v20, 1.0, v20
	v_add_f32_e32 v21, 1.0, v21
	v_mul_f32_e32 v73, 0xbfb8aa3b, v31
	v_rcp_f32_e32 v20, v20
	v_rcp_f32_e32 v21, v21
	v_exp_f32_e32 v73, v73
	v_cvt_pk_bf16_f32 v24, v24, v25
	v_cvt_pk_bf16_f32 v25, v26, v27
	global_store_dwordx2 v[28:29], v[24:25], off offset:32
	v_lshlrev_b32_e32 v24, 16, v80
	v_and_b32_e32 v25, 0xffff0000, v80
	v_lshlrev_b32_e32 v70, 16, v83
	v_and_b32_e32 v71, 0xffff0000, v83
	v_pk_mul_f32 v[20:21], v[20:21], v[24:25]
	v_add_f32_e32 v24, 1.0, v73
	v_add_f32_e32 v22, v22, v38
	v_add_f32_e32 v23, v23, v39
	v_lshlrev_b32_e32 v30, 16, v82
	v_mul_f32_e32 v22, 0xbfb8aa3b, v22
	v_mul_f32_e32 v23, 0xbfb8aa3b, v23
	v_rcp_f32_e32 v73, v24
	v_mul_f32_e32 v24, 0xbfb8aa3b, v70
	v_mul_f32_e32 v25, 0xbfb8aa3b, v71
	v_mul_f32_e32 v72, 0xbfb8aa3b, v30
	v_exp_f32_e32 v22, v22
	v_exp_f32_e32 v23, v23
	v_exp_f32_e32 v24, v24
	v_exp_f32_e32 v25, v25
	v_exp_f32_e32 v72, v72
	v_add_f32_e32 v22, 1.0, v22
	v_add_f32_e32 v23, 1.0, v23
	v_add_f32_e32 v24, 1.0, v24
	v_add_f32_e32 v25, 1.0, v25
	v_add_f32_e32 v72, 1.0, v72
	v_rcp_f32_e32 v22, v22
	v_rcp_f32_e32 v23, v23
	v_rcp_f32_e32 v24, v24
	v_rcp_f32_e32 v25, v25
	s_waitcnt vmcnt(10)
	v_add_f32_e32 v16, v16, v32
	v_add_f32_e32 v17, v17, v33
	v_rcp_f32_e32 v72, v72
	v_mul_f32_e32 v16, 0xbfb8aa3b, v16
	v_mul_f32_e32 v17, 0xbfb8aa3b, v17
	v_exp_f32_e32 v16, v16
	v_exp_f32_e32 v17, v17
	v_lshlrev_b32_e32 v26, 16, v81
	v_and_b32_e32 v27, 0xffff0000, v81
	v_pk_mul_f32 v[22:23], v[22:23], v[26:27]
	v_pk_mul_f32 v[24:25], v[24:25], v[70:71]
	v_pk_mul_f32 v[30:31], v[72:73], v[30:31]
	v_pk_mul_f32 v[22:23], v[24:25], v[22:23]
	v_and_b32_e32 v25, 0xffff0000, v66
	v_pk_mul_f32 v[20:21], v[30:31], v[20:21]
	v_add_f32_e32 v16, 1.0, v16
	v_add_f32_e32 v17, 1.0, v17
	v_mul_f32_e32 v31, 0xbfb8aa3b, v25
	v_rcp_f32_e32 v16, v16
	v_rcp_f32_e32 v17, v17
	v_exp_f32_e32 v31, v31
	v_cvt_pk_bf16_f32 v20, v20, v21
	v_cvt_pk_bf16_f32 v21, v22, v23
	global_store_dwordx2 v[28:29], v[20:21], off offset:256
	v_lshlrev_b32_e32 v20, 16, v68
	v_and_b32_e32 v21, 0xffff0000, v68
	v_lshlrev_b32_e32 v26, 16, v67
	v_and_b32_e32 v27, 0xffff0000, v67
	v_pk_mul_f32 v[16:17], v[16:17], v[20:21]
	v_add_f32_e32 v20, 1.0, v31
	v_lshlrev_b32_e32 v24, 16, v66
	v_add_f32_e32 v18, v18, v34
	v_add_f32_e32 v19, v19, v35
	v_rcp_f32_e32 v31, v20
	v_mul_f32_e32 v20, 0xbfb8aa3b, v26
	v_mul_f32_e32 v21, 0xbfb8aa3b, v27
	v_mul_f32_e32 v30, 0xbfb8aa3b, v24
	v_mul_f32_e32 v18, 0xbfb8aa3b, v18
	v_mul_f32_e32 v19, 0xbfb8aa3b, v19
	v_exp_f32_e32 v20, v20
	v_exp_f32_e32 v21, v21
	v_exp_f32_e32 v30, v30
	v_exp_f32_e32 v18, v18
	v_exp_f32_e32 v19, v19
	v_add_f32_e32 v20, 1.0, v20
	v_add_f32_e32 v21, 1.0, v21
	v_add_f32_e32 v30, 1.0, v30
	v_add_f32_e32 v18, 1.0, v18
	v_add_f32_e32 v19, 1.0, v19
	v_rcp_f32_e32 v20, v20
	v_rcp_f32_e32 v21, v21
	v_rcp_f32_e32 v30, v30
	v_rcp_f32_e32 v18, v18
	v_rcp_f32_e32 v19, v19
	v_add_f32_e32 v12, v12, v44
	v_mul_f32_e32 v12, 0xbfb8aa3b, v12
	v_lshlrev_b32_e32 v22, 16, v69
	v_and_b32_e32 v23, 0xffff0000, v69
	v_pk_mul_f32 v[20:21], v[20:21], v[26:27]
	v_exp_f32_e32 v26, v12
	v_add_f32_e32 v12, v13, v45
	v_pk_mul_f32 v[24:25], v[30:31], v[24:25]
	v_pk_mul_f32 v[18:19], v[18:19], v[22:23]
	v_mul_f32_e32 v12, 0xbfb8aa3b, v12
	v_pk_mul_f32 v[16:17], v[24:25], v[16:17]
	v_pk_mul_f32 v[18:19], v[20:21], v[18:19]
	v_exp_f32_e32 v27, v12
	v_cvt_pk_bf16_f32 v16, v16, v17
	v_cvt_pk_bf16_f32 v17, v18, v19
	global_store_dwordx2 v[28:29], v[16:17], off offset:288
	v_lshlrev_b64 v[16:17], 11, v[60:61]
	s_waitcnt vmcnt(10)
; DI float sigmoidf_(float x) { return __builtin_amdgcn_rcpf(1.0f + __expf(-x)); }
; DI float siluf_(float x) { return x * sigmoidf_(x); }
; DI void st_bf4(bf16_t* p, float a, float b, float c, float d) { uint2 v; v.x = pack2(a, b); v.y = pack2(c, d); *(uint2*)p = v; }
; template <class FL, class FS>
; DI void gemm8_tile(char* shmc, const bf16_t* __restrict__ A, const bf16_t* __restrict__ Bt, const int K, const int brow, const int bcol, FL fl, FS fs) {
;     ...
;   asm volatile("s_waitcnt vmcnt(0)" ::: "memory");
;   __syncthreads();
; DI void phase_g2(const Params& p, const Sub& s, char* lds_all) {
;     ...
;       [&](int row, int col) { const size_t o = (size_t)row * D + col; Ld2 r; const uint2 a = *(const uint2*)(A + o), b = *(const uint2*)(z + o);
;         r.a.x = __uint_as_float(a.x); r.a.y = __uint_as_float(a.y); r.a.z = __uint_as_float(b.x); r.a.w = __uint_as_float(b.y); r.b = *(const float4*)(p.s5_b_glu + col); return r; },
;       [&](int row, int col, f32x4 v, const Ld2& l2) {
;         uint4 ld; ld.x = __float_as_uint(l2.a.x); ld.y = __float_as_uint(l2.a.y); ld.z = __float_as_uint(l2.a.z); ld.w = __float_as_uint(l2.a.w);
;         const size_t o = (size_t)row * D + col;
;         const float y0 = __uint_as_float(ld.x << 16), y1 = __uint_as_float(ld.x & 0xffff0000u), y2_ = __uint_as_float(ld.y << 16), y3 = __uint_as_float(ld.y & 0xffff0000u);
;         const float z0 = __uint_as_float(ld.z << 16), z1 = __uint_as_float(ld.z & 0xffff0000u), z2 = __uint_as_float(ld.w << 16), z3 = __uint_as_float(ld.w & 0xffff0000u);
;         const float4 b4 = l2.b;
;         st_bf4(y2 + o, y0 * sigmoidf_(v[0] + b4.x) * siluf_(z0), y1 * sigmoidf_(v[1] + b4.y) * siluf_(z1),
;                y2_ * sigmoidf_(v[2] + b4.z) * siluf_(z2), y3 * sigmoidf_(v[3] + b4.w) * siluf_(z3));
	v_and_b32_e32 v23, 0xffff0000, v62
	v_lshl_add_u64 v[16:17], s[14:15], 0, v[16:17]
	v_lshl_add_u64 v[12:13], v[16:17], 0, v[144:145]
	v_add_f32_e32 v16, 1.0, v26
	v_add_f32_e32 v17, 1.0, v27
	v_mul_f32_e32 v27, 0xbfb8aa3b, v23
	v_rcp_f32_e32 v16, v16
	v_rcp_f32_e32 v17, v17
	v_exp_f32_e32 v27, v27
	v_lshlrev_b32_e32 v18, 16, v64
	v_and_b32_e32 v19, 0xffff0000, v64
	v_lshlrev_b32_e32 v24, 16, v63
	v_and_b32_e32 v25, 0xffff0000, v63
	v_pk_mul_f32 v[16:17], v[16:17], v[18:19]
	v_add_f32_e32 v18, 1.0, v27
	v_add_f32_e32 v14, v14, v46
	v_add_f32_e32 v15, v15, v47
	v_lshlrev_b32_e32 v22, 16, v62
	v_mul_f32_e32 v14, 0xbfb8aa3b, v14
	v_mul_f32_e32 v15, 0xbfb8aa3b, v15
	v_rcp_f32_e32 v27, v18
	v_mul_f32_e32 v18, 0xbfb8aa3b, v24
	v_mul_f32_e32 v19, 0xbfb8aa3b, v25
	v_mul_f32_e32 v26, 0xbfb8aa3b, v22
	v_exp_f32_e32 v14, v14
	v_exp_f32_e32 v15, v15
	v_exp_f32_e32 v18, v18
	v_exp_f32_e32 v19, v19
	v_exp_f32_e32 v26, v26
	v_add_f32_e32 v14, 1.0, v14
	v_add_f32_e32 v15, 1.0, v15
	v_add_f32_e32 v18, 1.0, v18
	v_add_f32_e32 v19, 1.0, v19
	v_add_f32_e32 v26, 1.0, v26
	v_rcp_f32_e32 v14, v14
	v_rcp_f32_e32 v15, v15
	v_rcp_f32_e32 v18, v18
	v_rcp_f32_e32 v19, v19
	v_add_f32_e32 v8, v8, v40
	v_add_f32_e32 v9, v9, v41
	v_rcp_f32_e32 v26, v26
	v_mul_f32_e32 v8, 0xbfb8aa3b, v8
	v_mul_f32_e32 v9, 0xbfb8aa3b, v9
	v_exp_f32_e32 v8, v8
	v_exp_f32_e32 v9, v9
	v_lshlrev_b32_e32 v20, 16, v65
	v_and_b32_e32 v21, 0xffff0000, v65
	v_pk_mul_f32 v[14:15], v[14:15], v[20:21]
	v_pk_mul_f32 v[18:19], v[18:19], v[24:25]
	v_pk_mul_f32 v[22:23], v[26:27], v[22:23]
	v_pk_mul_f32 v[14:15], v[14:15], v[18:19]
	s_waitcnt vmcnt(8)
	v_and_b32_e32 v19, 0xffff0000, v56
	v_pk_mul_f32 v[16:17], v[16:17], v[22:23]
	v_add_f32_e32 v8, 1.0, v8
	v_add_f32_e32 v9, 1.0, v9
	v_mul_f32_e32 v23, 0xbfb8aa3b, v19
	v_rcp_f32_e32 v8, v8
	v_rcp_f32_e32 v9, v9
	v_exp_f32_e32 v23, v23
	v_cvt_pk_bf16_f32 v16, v16, v17
	v_cvt_pk_bf16_f32 v17, v14, v15
	v_lshlrev_b32_e32 v14, 16, v58
	v_and_b32_e32 v15, 0xffff0000, v58
	v_lshlrev_b32_e32 v20, 16, v57
	v_and_b32_e32 v21, 0xffff0000, v57
	v_pk_mul_f32 v[8:9], v[8:9], v[14:15]
	v_add_f32_e32 v14, 1.0, v23
	v_add_f32_e32 v10, v10, v42
	v_add_f32_e32 v11, v11, v43
	v_lshlrev_b32_e32 v18, 16, v56
	v_mul_f32_e32 v10, 0xbfb8aa3b, v10
	v_mul_f32_e32 v11, 0xbfb8aa3b, v11
	v_rcp_f32_e32 v23, v14
	v_mul_f32_e32 v14, 0xbfb8aa3b, v20
	v_mul_f32_e32 v15, 0xbfb8aa3b, v21
	v_mul_f32_e32 v22, 0xbfb8aa3b, v18
	v_exp_f32_e32 v10, v10
	v_exp_f32_e32 v11, v11
	v_exp_f32_e32 v14, v14
	v_exp_f32_e32 v15, v15
	v_exp_f32_e32 v22, v22
	v_add_f32_e32 v10, 1.0, v10
	v_add_f32_e32 v11, 1.0, v11
	v_add_f32_e32 v14, 1.0, v14
	v_add_f32_e32 v15, 1.0, v15
	v_add_f32_e32 v22, 1.0, v22
	v_rcp_f32_e32 v10, v10
	v_rcp_f32_e32 v11, v11
	v_rcp_f32_e32 v14, v14
	v_rcp_f32_e32 v15, v15
	v_add_f32_e32 v4, v4, v36
	v_add_f32_e32 v5, v5, v37
	v_rcp_f32_e32 v22, v22
	v_mul_f32_e32 v4, 0xbfb8aa3b, v4
	v_mul_f32_e32 v5, 0xbfb8aa3b, v5
	v_exp_f32_e32 v4, v4
	v_exp_f32_e32 v5, v5
	global_store_dwordx2 v[12:13], v[16:17], off
	v_lshlrev_b32_e32 v16, 16, v59
	v_and_b32_e32 v17, 0xffff0000, v59
	v_pk_mul_f32 v[10:11], v[10:11], v[16:17]
	v_pk_mul_f32 v[14:15], v[14:15], v[20:21]
	v_pk_mul_f32 v[18:19], v[22:23], v[18:19]
	v_pk_mul_f32 v[10:11], v[10:11], v[14:15]
	s_waitcnt vmcnt(7)
	v_and_b32_e32 v15, 0xffff0000, v52
	v_pk_mul_f32 v[8:9], v[8:9], v[18:19]
	v_add_f32_e32 v4, 1.0, v4
	v_add_f32_e32 v5, 1.0, v5
	v_mul_f32_e32 v19, 0xbfb8aa3b, v15
	v_rcp_f32_e32 v4, v4
	v_rcp_f32_e32 v5, v5
	v_exp_f32_e32 v19, v19
	v_cvt_pk_bf16_f32 v8, v8, v9
	v_cvt_pk_bf16_f32 v9, v10, v11
	global_store_dwordx2 v[12:13], v[8:9], off offset:32
	v_lshlrev_b32_e32 v8, 16, v54
	v_and_b32_e32 v9, 0xffff0000, v54
	v_lshlrev_b32_e32 v16, 16, v53
	v_and_b32_e32 v17, 0xffff0000, v53
	v_pk_mul_f32 v[4:5], v[4:5], v[8:9]
	v_add_f32_e32 v8, 1.0, v19
	v_add_f32_e32 v6, v6, v38
	v_add_f32_e32 v7, v7, v39
	v_lshlrev_b32_e32 v14, 16, v52
	v_mul_f32_e32 v6, 0xbfb8aa3b, v6
	v_mul_f32_e32 v7, 0xbfb8aa3b, v7
	v_rcp_f32_e32 v19, v8
	v_mul_f32_e32 v8, 0xbfb8aa3b, v16
	v_mul_f32_e32 v9, 0xbfb8aa3b, v17
	v_mul_f32_e32 v18, 0xbfb8aa3b, v14
	v_exp_f32_e32 v6, v6
	v_exp_f32_e32 v7, v7
	v_exp_f32_e32 v8, v8
	v_exp_f32_e32 v9, v9
	v_exp_f32_e32 v18, v18
	v_add_f32_e32 v6, 1.0, v6
	v_add_f32_e32 v7, 1.0, v7
	v_add_f32_e32 v8, 1.0, v8
	v_add_f32_e32 v9, 1.0, v9
	v_add_f32_e32 v18, 1.0, v18
	v_rcp_f32_e32 v6, v6
	v_rcp_f32_e32 v7, v7
	v_rcp_f32_e32 v8, v8
	v_rcp_f32_e32 v9, v9
	v_add_f32_e32 v0, v0, v32
	v_add_f32_e32 v1, v1, v33
	v_rcp_f32_e32 v18, v18
	v_mul_f32_e32 v0, 0xbfb8aa3b, v0
	v_mul_f32_e32 v1, 0xbfb8aa3b, v1
	v_exp_f32_e32 v0, v0
	v_exp_f32_e32 v1, v1
	v_lshlrev_b32_e32 v10, 16, v55
	v_and_b32_e32 v11, 0xffff0000, v55
	v_pk_mul_f32 v[6:7], v[6:7], v[10:11]
	v_pk_mul_f32 v[8:9], v[8:9], v[16:17]
	v_pk_mul_f32 v[14:15], v[18:19], v[14:15]
	v_pk_mul_f32 v[6:7], v[6:7], v[8:9]
	s_waitcnt vmcnt(6)
	v_and_b32_e32 v9, 0xffff0000, v48
	v_pk_mul_f32 v[4:5], v[4:5], v[14:15]
	v_add_f32_e32 v0, 1.0, v0
	v_add_f32_e32 v1, 1.0, v1
	v_mul_f32_e32 v15, 0xbfb8aa3b, v9
	v_rcp_f32_e32 v0, v0
	v_rcp_f32_e32 v1, v1
	v_exp_f32_e32 v15, v15
	v_cvt_pk_bf16_f32 v4, v4, v5
	v_cvt_pk_bf16_f32 v5, v6, v7
	global_store_dwordx2 v[12:13], v[4:5], off offset:256
	v_lshlrev_b32_e32 v4, 16, v50
	v_and_b32_e32 v5, 0xffff0000, v50
	v_lshlrev_b32_e32 v8, 16, v48
	v_lshlrev_b32_e32 v10, 16, v49
	v_and_b32_e32 v11, 0xffff0000, v49
	v_pk_mul_f32 v[0:1], v[0:1], v[4:5]
	v_add_f32_e32 v4, 1.0, v15
	v_add_f32_e32 v2, v2, v34
	v_add_f32_e32 v3, v3, v35
	v_mul_f32_e32 v14, 0xbfb8aa3b, v8
	v_mul_f32_e32 v2, 0xbfb8aa3b, v2
	v_mul_f32_e32 v3, 0xbfb8aa3b, v3
	v_rcp_f32_e32 v15, v4
	v_mul_f32_e32 v4, 0xbfb8aa3b, v10
	v_mul_f32_e32 v5, 0xbfb8aa3b, v11
	v_exp_f32_e32 v14, v14
	v_exp_f32_e32 v2, v2
	v_exp_f32_e32 v3, v3
	v_exp_f32_e32 v4, v4
	v_exp_f32_e32 v5, v5
	v_add_f32_e32 v14, 1.0, v14
	v_add_f32_e32 v2, 1.0, v2
	v_add_f32_e32 v3, 1.0, v3
	v_add_f32_e32 v4, 1.0, v4
	v_add_f32_e32 v5, 1.0, v5
	v_rcp_f32_e32 v14, v14
	v_rcp_f32_e32 v2, v2
	v_rcp_f32_e32 v3, v3
	v_rcp_f32_e32 v4, v4
	v_rcp_f32_e32 v5, v5
	v_lshlrev_b32_e32 v6, 16, v51
	v_and_b32_e32 v7, 0xffff0000, v51
	v_pk_mul_f32 v[8:9], v[14:15], v[8:9]
	v_pk_mul_f32 v[2:3], v[2:3], v[6:7]
	v_pk_mul_f32 v[4:5], v[4:5], v[10:11]
	v_pk_mul_f32 v[0:1], v[0:1], v[8:9]
	v_pk_mul_f32 v[2:3], v[2:3], v[4:5]
	v_cvt_pk_bf16_f32 v0, v0, v1
	v_cvt_pk_bf16_f32 v1, v2, v3
	global_store_dwordx2 v[12:13], v[0:1], off offset:288
	s_barrier
	s_cbranch_scc0 .LBB0_690

; DI float4 ldnt4(const float* p) { const f32x4 v = __builtin_nontemporal_load((const f32x4*)p); float4 r; r.x = v[0]; r.y = v[1]; r.z = v[2]; r.w = v[3]; return r; }
; DI void st_bf4(bf16_t* p, float a, float b, float c, float d) { uint2 v; v.x = pack2(a, b); v.y = pack2(c, d); *(uint2*)p = v; }
; DI void phase_gout(const Params& p, const Sub& s, char* lds_all, int layer, const bf16_t* A, const bf16_t* Bt) {
;     ...
;       [&](int row, int col) {
;         const bf16_t* x1b = (const bf16_t*)p.out;
;         float4 x4;
;         if (layer == 0) x4 = ldnt4(xrow(p, row) + col);
;         else ld_bf4(x1b + (size_t)row * D + col, x4.x, x4.y, x4.z, x4.w);
;         Ld2 r; r.a = x4; r.b = *(const float4*)(mod + (size_t)(row_bi(row) * 2 + layer) * 3072 + 2048 + col);
;         return r;
;       },
;       [&](int row, int col, f32x4 v, const Ld2& l2) {
;         const float4 x4 = l2.a, g4 = l2.b;
;         bf16_t* x1b = (bf16_t*)p.out;
;         bf16_t* x2b = (bf16_t*)(p.ws + W_SLOT3);
;         st_bf4((layer == 0 ? x1b : x2b) + (size_t)row * D + col, x4.x + g4.x * v[0], x4.y + g4.y * v[1], x4.z + g4.z * v[2], x4.w + g4.w * v[3]);
;       });
.LBB0_744:
	s_or_b64 exec, exec, s[0:1]
	v_and_b32_e32 v140, 15, v182
	v_bfe_u32 v141, v182, 4, 2
	v_bfe_u32 v143, v182, 6, 2
	v_lshrrev_b32_e32 v180, 8, v182
	v_lshl_add_u32 v181, v180, 6, v140
	v_and_b32_e32 v248, 1, v141
	v_lshrrev_b32_e32 v249, 1, v141
	v_lshlrev_b32_e32 v250, 12, v181
	v_lshl_add_u32 v250, v143, 7, v250
	v_lshl_add_u32 v250, v141, 4, v250
	v_lshlrev_b32_e32 v232, 7, v143
	v_lshl_add_u32 v232, v141, 4, v232
	v_lshlrev_b32_e32 v233, 11, v181
	v_lshl_add_u32 v233, v143, 6, v233
	v_lshl_add_u32 v233, v248, 5, v233
	v_lshl_add_u32 v233, v249, 4, v233
	s_lshr_b32 s0, s44, 13
	s_mul_i32 s0, s0, 0x6000
	s_add_u32 s0, s0, 0x2000
	s_lshl_b32 s1, s42, 2
	s_add_u32 s0, s0, s1
	s_add_u32 s2, s6, s0
	s_addc_u32 s3, s7, 0
	s_lshl_b32 s0, s44, 12
	s_add_u32 s4, s12, s0
	s_addc_u32 s5, s13, 0
	s_lshl_b32 s0, s42, 2
	s_add_u32 s4, s4, s0
	s_addc_u32 s5, s5, 0
	s_lshl_b32 s0, s44, 11
	s_add_u32 s40, s8, s0
	s_addc_u32 s41, s9, 0
	s_lshl_b32 s0, s42, 1
	s_add_u32 s40, s40, s0
	s_addc_u32 s41, s41, 0
	global_load_dwordx4 v[128:131], v232, s[2:3]
	global_load_dwordx4 v[132:135], v232, s[2:3] offset:64
	global_load_dwordx4 v[136:139], v232, s[2:3] offset:512
	global_load_dwordx4 v[144:147], v232, s[2:3] offset:576
	global_load_dwordx4 v[148:151], v250, s[4:5] nt
	global_load_dwordx4 v[152:155], v250, s[4:5] offset:64 nt
	global_load_dwordx4 v[156:159], v250, s[4:5] offset:512 nt
	global_load_dwordx4 v[160:163], v250, s[4:5] offset:576 nt
	s_add_u32 s4, s4, 0x10000
	s_addc_u32 s5, s5, 0
	global_load_dwordx4 v[164:167], v250, s[4:5] nt
	global_load_dwordx4 v[168:171], v250, s[4:5] offset:64 nt
	global_load_dwordx4 v[172:175], v250, s[4:5] offset:512 nt
	global_load_dwordx4 v[176:179], v250, s[4:5] offset:576 nt
	s_add_u32 s4, s4, 0x10000
	s_addc_u32 s5, s5, 0
	global_load_dwordx4 v[184:187], v250, s[4:5] nt
	global_load_dwordx4 v[188:191], v250, s[4:5] offset:64 nt
	global_load_dwordx4 v[192:195], v250, s[4:5] offset:512 nt
	global_load_dwordx4 v[196:199], v250, s[4:5] offset:576 nt
	s_add_u32 s4, s4, 0x10000
	s_addc_u32 s5, s5, 0
	global_load_dwordx4 v[200:203], v250, s[4:5] nt
	global_load_dwordx4 v[204:207], v250, s[4:5] offset:64 nt
	global_load_dwordx4 v[208:211], v250, s[4:5] offset:512 nt
	global_load_dwordx4 v[212:215], v250, s[4:5] offset:576 nt
	s_add_u32 s4, s4, 0x50000
	s_addc_u32 s5, s5, 0
	global_load_dwordx4 v[216:219], v250, s[4:5] nt
	global_load_dwordx4 v[220:223], v250, s[4:5] offset:64 nt
	global_load_dwordx4 v[224:227], v250, s[4:5] offset:512 nt
	global_load_dwordx4 v[228:231], v250, s[4:5] offset:576 nt
	s_waitcnt vmcnt(16)
	v_pk_fma_f32 v[148:149], v[128:129], v[108:109], v[148:149]
	v_pk_fma_f32 v[150:151], v[130:131], v[110:111], v[150:151]
	v_pk_fma_f32 v[152:153], v[132:133], v[112:113], v[152:153]
	v_pk_fma_f32 v[154:155], v[134:135], v[114:115], v[154:155]
	v_pk_fma_f32 v[156:157], v[136:137], v[124:125], v[156:157]
	v_pk_fma_f32 v[158:159], v[138:139], v[126:127], v[158:159]
	v_pk_fma_f32 v[160:161], v[144:145], v[120:121], v[160:161]
	v_pk_fma_f32 v[162:163], v[146:147], v[122:123], v[162:163]
	v_cvt_pk_bf16_f32 v148, v148, v149
	v_cvt_pk_bf16_f32 v149, v150, v151
	v_cvt_pk_bf16_f32 v150, v152, v153
	v_cvt_pk_bf16_f32 v151, v154, v155
	v_cvt_pk_bf16_f32 v156, v156, v157
	v_cvt_pk_bf16_f32 v157, v158, v159
	v_cvt_pk_bf16_f32 v158, v160, v161
	v_cvt_pk_bf16_f32 v159, v162, v163
	v_permlane16_swap_b32_e32 v148, v150
	v_permlane16_swap_b32_e32 v149, v151
	global_store_dwordx4 v233, v[148:151], s[40:41]
	v_permlane16_swap_b32_e32 v156, v158
	v_permlane16_swap_b32_e32 v157, v159
	global_store_dwordx4 v233, v[156:159], s[40:41] offset:256
	s_nop 1
	s_add_u32 s4, s4, 0x10000
	s_addc_u32 s5, s5, 0
	global_load_dwordx4 v[148:151], v250, s[4:5] nt
	global_load_dwordx4 v[152:155], v250, s[4:5] offset:64 nt
	global_load_dwordx4 v[156:159], v250, s[4:5] offset:512 nt
	global_load_dwordx4 v[160:163], v250, s[4:5] offset:576 nt
	s_waitcnt vmcnt(18)
	v_pk_fma_f32 v[164:165], v[128:129], v[104:105], v[164:165]
	v_pk_fma_f32 v[166:167], v[130:131], v[106:107], v[166:167]
	v_pk_fma_f32 v[168:169], v[132:133], v[100:101], v[168:169]
	v_pk_fma_f32 v[170:171], v[134:135], v[102:103], v[170:171]
	v_pk_fma_f32 v[172:173], v[136:137], v[116:117], v[172:173]
	v_pk_fma_f32 v[174:175], v[138:139], v[118:119], v[174:175]
	v_pk_fma_f32 v[176:177], v[144:145], v[96:97], v[176:177]
	v_pk_fma_f32 v[178:179], v[146:147], v[98:99], v[178:179]
	v_cvt_pk_bf16_f32 v164, v164, v165
	v_cvt_pk_bf16_f32 v165, v166, v167
	v_cvt_pk_bf16_f32 v166, v168, v169
	v_cvt_pk_bf16_f32 v167, v170, v171
	v_cvt_pk_bf16_f32 v172, v172, v173
	v_cvt_pk_bf16_f32 v173, v174, v175
	v_cvt_pk_bf16_f32 v174, v176, v177
	v_cvt_pk_bf16_f32 v175, v178, v179
	s_add_u32 s40, s40, 0x8000
	s_addc_u32 s41, s41, 0
	v_permlane16_swap_b32_e32 v164, v166
	v_permlane16_swap_b32_e32 v165, v167
	global_store_dwordx4 v233, v[164:167], s[40:41]
	v_permlane16_swap_b32_e32 v172, v174
	v_permlane16_swap_b32_e32 v173, v175
	global_store_dwordx4 v233, v[172:175], s[40:41] offset:256
	s_nop 1
	s_add_u32 s4, s4, 0x10000
	s_addc_u32 s5, s5, 0
	global_load_dwordx4 v[164:167], v250, s[4:5] nt
	global_load_dwordx4 v[168:171], v250, s[4:5] offset:64 nt
	global_load_dwordx4 v[172:175], v250, s[4:5] offset:512 nt
	global_load_dwordx4 v[176:179], v250, s[4:5] offset:576 nt
	s_waitcnt vmcnt(20)
; DI float4 ldnt4(const float* p) { const f32x4 v = __builtin_nontemporal_load((const f32x4*)p); float4 r; r.x = v[0]; r.y = v[1]; r.z = v[2]; r.w = v[3]; return r; }
; DI void st_bf4(bf16_t* p, float a, float b, float c, float d) { uint2 v; v.x = pack2(a, b); v.y = pack2(c, d); *(uint2*)p = v; }
; template <class FL, class FS>
; DI void gemm8_tile(char* shmc, const bf16_t* __restrict__ A, const bf16_t* __restrict__ Bt, const int K, const int brow, const int bcol, FL fl, FS fs) {
;     ...
;   asm volatile("s_waitcnt vmcnt(0)" ::: "memory");
;   __syncthreads();
; DI void phase_gout(const Params& p, const Sub& s, char* lds_all, int layer, const bf16_t* A, const bf16_t* Bt) {
;     ...
;       [&](int row, int col) {
;         const bf16_t* x1b = (const bf16_t*)p.out;
;         float4 x4;
;         if (layer == 0) x4 = ldnt4(xrow(p, row) + col);
;         else ld_bf4(x1b + (size_t)row * D + col, x4.x, x4.y, x4.z, x4.w);
;         Ld2 r; r.a = x4; r.b = *(const float4*)(mod + (size_t)(row_bi(row) * 2 + layer) * 3072 + 2048 + col);
;         return r;
;       },
;       [&](int row, int col, f32x4 v, const Ld2& l2) {
;         const float4 x4 = l2.a, g4 = l2.b;
;         bf16_t* x1b = (bf16_t*)p.out;
;         bf16_t* x2b = (bf16_t*)(p.ws + W_SLOT3);
;         st_bf4((layer == 0 ? x1b : x2b) + (size_t)row * D + col, x4.x + g4.x * v[0], x4.y + g4.y * v[1], x4.z + g4.z * v[2], x4.w + g4.w * v[3]);
;       });
	v_pk_fma_f32 v[184:185], v[128:129], v[80:81], v[184:185]
	v_pk_fma_f32 v[186:187], v[130:131], v[82:83], v[186:187]
	v_pk_fma_f32 v[188:189], v[132:133], v[76:77], v[188:189]
	v_pk_fma_f32 v[190:191], v[134:135], v[78:79], v[190:191]
	v_pk_fma_f32 v[192:193], v[136:137], v[92:93], v[192:193]
	v_pk_fma_f32 v[194:195], v[138:139], v[94:95], v[194:195]
	v_pk_fma_f32 v[196:197], v[144:145], v[88:89], v[196:197]
	v_pk_fma_f32 v[198:199], v[146:147], v[90:91], v[198:199]
	v_cvt_pk_bf16_f32 v184, v184, v185
	v_cvt_pk_bf16_f32 v185, v186, v187
	v_cvt_pk_bf16_f32 v186, v188, v189
	v_cvt_pk_bf16_f32 v187, v190, v191
	v_cvt_pk_bf16_f32 v192, v192, v193
	v_cvt_pk_bf16_f32 v193, v194, v195
	v_cvt_pk_bf16_f32 v194, v196, v197
	v_cvt_pk_bf16_f32 v195, v198, v199
	s_add_u32 s40, s40, 0x8000
	s_addc_u32 s41, s41, 0
	v_permlane16_swap_b32_e32 v184, v186
	v_permlane16_swap_b32_e32 v185, v187
	global_store_dwordx4 v233, v[184:187], s[40:41]
	v_permlane16_swap_b32_e32 v192, v194
	v_permlane16_swap_b32_e32 v193, v195
	global_store_dwordx4 v233, v[192:195], s[40:41] offset:256
	s_nop 1
	s_add_u32 s4, s4, 0x10000
	s_addc_u32 s5, s5, 0
	global_load_dwordx4 v[184:187], v250, s[4:5] nt
	global_load_dwordx4 v[188:191], v250, s[4:5] offset:64 nt
	global_load_dwordx4 v[192:195], v250, s[4:5] offset:512 nt
	global_load_dwordx4 v[196:199], v250, s[4:5] offset:576 nt
	s_waitcnt vmcnt(22)
	v_pk_fma_f32 v[200:201], v[128:129], v[72:73], v[200:201]
	v_pk_fma_f32 v[202:203], v[130:131], v[74:75], v[202:203]
	v_pk_fma_f32 v[204:205], v[132:133], v[68:69], v[204:205]
	v_pk_fma_f32 v[206:207], v[134:135], v[70:71], v[206:207]
	v_pk_fma_f32 v[208:209], v[136:137], v[84:85], v[208:209]
	v_pk_fma_f32 v[210:211], v[138:139], v[86:87], v[210:211]
	v_pk_fma_f32 v[212:213], v[144:145], v[64:65], v[212:213]
	v_pk_fma_f32 v[214:215], v[146:147], v[66:67], v[214:215]
	v_cvt_pk_bf16_f32 v200, v200, v201
	v_cvt_pk_bf16_f32 v201, v202, v203
	v_cvt_pk_bf16_f32 v202, v204, v205
	v_cvt_pk_bf16_f32 v203, v206, v207
	v_cvt_pk_bf16_f32 v208, v208, v209
	v_cvt_pk_bf16_f32 v209, v210, v211
	v_cvt_pk_bf16_f32 v210, v212, v213
	v_cvt_pk_bf16_f32 v211, v214, v215
	s_add_u32 s40, s40, 0x8000
	s_addc_u32 s41, s41, 0
	v_permlane16_swap_b32_e32 v200, v202
	v_permlane16_swap_b32_e32 v201, v203
	global_store_dwordx4 v233, v[200:203], s[40:41]
	v_permlane16_swap_b32_e32 v208, v210
	v_permlane16_swap_b32_e32 v209, v211
	global_store_dwordx4 v233, v[208:211], s[40:41] offset:256
	s_waitcnt vmcnt(20)
	v_pk_fma_f32 v[216:217], v[128:129], v[52:53], v[216:217]
	v_pk_fma_f32 v[218:219], v[130:131], v[54:55], v[218:219]
	v_pk_fma_f32 v[220:221], v[132:133], v[48:49], v[220:221]
	v_pk_fma_f32 v[222:223], v[134:135], v[50:51], v[222:223]
	v_pk_fma_f32 v[224:225], v[136:137], v[60:61], v[224:225]
	v_pk_fma_f32 v[226:227], v[138:139], v[62:63], v[226:227]
	v_pk_fma_f32 v[228:229], v[144:145], v[56:57], v[228:229]
	v_pk_fma_f32 v[230:231], v[146:147], v[58:59], v[230:231]
	v_cvt_pk_bf16_f32 v216, v216, v217
	v_cvt_pk_bf16_f32 v217, v218, v219
	v_cvt_pk_bf16_f32 v218, v220, v221
	v_cvt_pk_bf16_f32 v219, v222, v223
	v_cvt_pk_bf16_f32 v224, v224, v225
	v_cvt_pk_bf16_f32 v225, v226, v227
	v_cvt_pk_bf16_f32 v226, v228, v229
	v_cvt_pk_bf16_f32 v227, v230, v231
	s_add_u32 s40, s40, 0x28000
	s_addc_u32 s41, s41, 0
	v_permlane16_swap_b32_e32 v216, v218
	v_permlane16_swap_b32_e32 v217, v219
	global_store_dwordx4 v233, v[216:219], s[40:41]
	v_permlane16_swap_b32_e32 v224, v226
	v_permlane16_swap_b32_e32 v225, v227
	global_store_dwordx4 v233, v[224:227], s[40:41] offset:256
	s_waitcnt vmcnt(16)
	v_pk_fma_f32 v[148:149], v[128:129], v[40:41], v[148:149]
	v_pk_fma_f32 v[150:151], v[130:131], v[42:43], v[150:151]
	v_pk_fma_f32 v[152:153], v[132:133], v[36:37], v[152:153]
	v_pk_fma_f32 v[154:155], v[134:135], v[38:39], v[154:155]
	v_pk_fma_f32 v[156:157], v[136:137], v[44:45], v[156:157]
	v_pk_fma_f32 v[158:159], v[138:139], v[46:47], v[158:159]
	v_pk_fma_f32 v[160:161], v[144:145], v[32:33], v[160:161]
	v_pk_fma_f32 v[162:163], v[146:147], v[34:35], v[162:163]
	v_cvt_pk_bf16_f32 v148, v148, v149
	v_cvt_pk_bf16_f32 v149, v150, v151
	v_cvt_pk_bf16_f32 v150, v152, v153
	v_cvt_pk_bf16_f32 v151, v154, v155
	v_cvt_pk_bf16_f32 v156, v156, v157
	v_cvt_pk_bf16_f32 v157, v158, v159
	v_cvt_pk_bf16_f32 v158, v160, v161
	v_cvt_pk_bf16_f32 v159, v162, v163
	s_add_u32 s40, s40, 0x8000
	s_addc_u32 s41, s41, 0
	v_permlane16_swap_b32_e32 v148, v150
	v_permlane16_swap_b32_e32 v149, v151
	global_store_dwordx4 v233, v[148:151], s[40:41]
	v_permlane16_swap_b32_e32 v156, v158
	v_permlane16_swap_b32_e32 v157, v159
	global_store_dwordx4 v233, v[156:159], s[40:41] offset:256
	s_waitcnt vmcnt(12)
	v_pk_fma_f32 v[164:165], v[128:129], v[20:21], v[164:165]
	v_pk_fma_f32 v[166:167], v[130:131], v[22:23], v[166:167]
	v_pk_fma_f32 v[168:169], v[132:133], v[16:17], v[168:169]
	v_pk_fma_f32 v[170:171], v[134:135], v[18:19], v[170:171]
	v_pk_fma_f32 v[172:173], v[136:137], v[28:29], v[172:173]
	v_pk_fma_f32 v[174:175], v[138:139], v[30:31], v[174:175]
	v_pk_fma_f32 v[176:177], v[144:145], v[24:25], v[176:177]
	v_pk_fma_f32 v[178:179], v[146:147], v[26:27], v[178:179]
	v_cvt_pk_bf16_f32 v164, v164, v165
	v_cvt_pk_bf16_f32 v165, v166, v167
	v_cvt_pk_bf16_f32 v166, v168, v169
	v_cvt_pk_bf16_f32 v167, v170, v171
	v_cvt_pk_bf16_f32 v172, v172, v173
	v_cvt_pk_bf16_f32 v173, v174, v175
	v_cvt_pk_bf16_f32 v174, v176, v177
	v_cvt_pk_bf16_f32 v175, v178, v179
	s_add_u32 s40, s40, 0x8000
	s_addc_u32 s41, s41, 0
	v_permlane16_swap_b32_e32 v164, v166
	v_permlane16_swap_b32_e32 v165, v167
	global_store_dwordx4 v233, v[164:167], s[40:41]
	v_permlane16_swap_b32_e32 v172, v174
	v_permlane16_swap_b32_e32 v173, v175
	global_store_dwordx4 v233, v[172:175], s[40:41] offset:256
	s_waitcnt vmcnt(8)
	v_pk_fma_f32 v[184:185], v[128:129], v[8:9], v[184:185]
	v_pk_fma_f32 v[186:187], v[130:131], v[10:11], v[186:187]
	v_pk_fma_f32 v[188:189], v[132:133], v[4:5], v[188:189]
	v_pk_fma_f32 v[190:191], v[134:135], v[6:7], v[190:191]
	v_pk_fma_f32 v[192:193], v[136:137], v[12:13], v[192:193]
	v_pk_fma_f32 v[194:195], v[138:139], v[14:15], v[194:195]
	v_pk_fma_f32 v[196:197], v[144:145], v[0:1], v[196:197]
	v_pk_fma_f32 v[198:199], v[146:147], v[2:3], v[198:199]
	v_cvt_pk_bf16_f32 v184, v184, v185
	v_cvt_pk_bf16_f32 v185, v186, v187
	v_cvt_pk_bf16_f32 v186, v188, v189
	v_cvt_pk_bf16_f32 v187, v190, v191
	v_cvt_pk_bf16_f32 v192, v192, v193
	v_cvt_pk_bf16_f32 v193, v194, v195
	v_cvt_pk_bf16_f32 v194, v196, v197
	v_cvt_pk_bf16_f32 v195, v198, v199
	s_add_u32 s40, s40, 0x8000
	s_addc_u32 s41, s41, 0
	v_permlane16_swap_b32_e32 v184, v186
	v_permlane16_swap_b32_e32 v185, v187
	global_store_dwordx4 v233, v[184:187], s[40:41]
	v_permlane16_swap_b32_e32 v192, v194
	v_permlane16_swap_b32_e32 v193, v195
	global_store_dwordx4 v233, v[192:195], s[40:41] offset:256
	v_readlane_b32 s0, v251, 1
	s_add_i32 s56, s56, s0
	s_cmpk_lt_i32 s56, 0x400
	s_barrier
	s_cbranch_scc0 .LBB0_751

; DI float4 ldnt4(const float* p) { const f32x4 v = __builtin_nontemporal_load((const f32x4*)p); float4 r; r.x = v[0]; r.y = v[1]; r.z = v[2]; r.w = v[3]; return r; }
; DI void st_bf4(bf16_t* p, float a, float b, float c, float d) { uint2 v; v.x = pack2(a, b); v.y = pack2(c, d); *(uint2*)p = v; }
; DI void phase_gout(const Params& p, const Sub& s, char* lds_all, int layer, const bf16_t* A, const bf16_t* Bt) {
;     ...
;       [&](int row, int col) {
;         const bf16_t* x1b = (const bf16_t*)p.out;
;         float4 x4;
;         if (layer == 0) x4 = ldnt4(xrow(p, row) + col);
;         else ld_bf4(x1b + (size_t)row * D + col, x4.x, x4.y, x4.z, x4.w);
;         Ld2 r; r.a = x4; r.b = *(const float4*)(mod + (size_t)(row_bi(row) * 2 + layer) * 3072 + 2048 + col);
;         return r;
;       },
;       [&](int row, int col, f32x4 v, const Ld2& l2) {
;         const float4 x4 = l2.a, g4 = l2.b;
;         bf16_t* x1b = (bf16_t*)p.out;
;         bf16_t* x2b = (bf16_t*)(p.ws + W_SLOT3);
;         st_bf4((layer == 0 ? x1b : x2b) + (size_t)row * D + col, x4.x + g4.x * v[0], x4.y + g4.y * v[1], x4.z + g4.z * v[2], x4.w + g4.w * v[3]);
;       });
.LBB0_2088:
	s_or_b64 exec, exec, s[0:1]
	v_or_b32_e32 v128, s40, v143
	v_add_u32_e32 v130, v128, v145
	v_lshlrev_b32_e32 v128, 5, v141
	v_lshlrev_b32_e32 v129, 2, v142
	v_or3_b32 v136, v128, v129, s38
	v_ashrrev_i32_e32 v131, 31, v130
	v_lshlrev_b64 v[142:143], 11, v[130:131]
	v_ashrrev_i32_e32 v137, 31, v136
	v_add_u32_e32 v134, 0xffff0000, v130
	v_or_b32_e32 v162, 16, v130
	v_lshl_add_u64 v[132:133], s[4:5], 0, v[142:143]
	v_lshlrev_b64 v[128:129], 1, v[136:137]
	v_lshrrev_b32_e32 v134, 4, v134
	v_ashrrev_i32_e32 v163, 31, v162
	v_lshl_add_u64 v[132:133], v[132:133], 0, v[128:129]
	v_ashrrev_i32_e32 v131, 13, v130
	v_add_u32_e32 v134, 8, v134
	v_cmp_gt_i32_e32 vcc, s44, v130
	v_lshlrev_b64 v[192:193], 11, v[162:163]
	global_load_dwordx2 v[184:185], v[132:133], off
	global_load_dwordx2 v[186:187], v[132:133], off offset:32
	global_load_dwordx2 v[188:189], v[132:133], off offset:256
	global_load_dwordx2 v[190:191], v[132:133], off offset:288
	v_cndmask_b32_e32 v134, v134, v131, vcc
	v_lshl_add_u64 v[132:133], s[4:5], 0, v[192:193]
	v_lshl_or_b32 v138, v134, 1, 1
	v_lshl_add_u64 v[134:135], v[132:133], 0, v[128:129]
	v_mov_b64_e32 v[132:133], s[10:11]
	v_mad_i64_i32 v[138:139], s[0:1], v138, s53, v[132:133]
	v_add_u32_e32 v145, 0xffff0010, v130
	v_lshl_add_u64 v[158:159], v[138:139], 0, s[36:37]
	v_or_b32_e32 v138, 16, v136
	v_lshrrev_b32_e32 v145, 4, v145
	global_load_dwordx2 v[194:195], v[134:135], off
	global_load_dwordx2 v[196:197], v[134:135], off offset:32
	global_load_dwordx2 v[198:199], v[134:135], off offset:256
	global_load_dwordx2 v[200:201], v[134:135], off offset:288
	v_ashrrev_i32_e32 v139, 31, v138
	v_or_b32_e32 v134, 0x80, v136
	v_add_u32_e32 v145, 8, v145
	v_cmp_gt_i32_e32 vcc, s44, v162
	v_lshlrev_b64 v[140:141], 2, v[136:137]
	v_lshlrev_b64 v[138:139], 2, v[138:139]
	v_ashrrev_i32_e32 v135, 31, v134
	v_or_b32_e32 v136, 0x90, v136
	v_cndmask_b32_e32 v145, v145, v131, vcc
	v_lshl_add_u64 v[150:151], v[158:159], 0, v[140:141]
	v_lshl_add_u64 v[154:155], v[158:159], 0, v[138:139]
	v_lshlrev_b64 v[134:135], 2, v[134:135]
	v_ashrrev_i32_e32 v137, 31, v136
	v_lshl_or_b32 v145, v145, 1, 1
	v_lshl_add_u64 v[160:161], v[158:159], 0, v[134:135]
	global_load_dwordx4 v[150:153], v[150:151], off
	v_lshlrev_b64 v[136:137], 2, v[136:137]
	global_load_dwordx4 v[154:157], v[154:155], off
	v_mad_i64_i32 v[166:167], s[0:1], v145, s53, v[132:133]
	v_lshl_add_u64 v[164:165], v[158:159], 0, v[136:137]
	global_load_dwordx4 v[158:161], v[160:161], off
	v_lshl_add_u64 v[178:179], v[166:167], 0, s[36:37]
	global_load_dwordx4 v[162:165], v[164:165], off
	v_lshl_add_u64 v[166:167], v[178:179], 0, v[140:141]
	v_lshl_add_u64 v[170:171], v[178:179], 0, v[138:139]
	v_lshl_add_u64 v[174:175], v[178:179], 0, v[134:135]
	v_lshl_add_u64 v[178:179], v[178:179], 0, v[136:137]
	global_load_dwordx4 v[166:169], v[166:167], off
	v_lshl_add_u64 v[142:143], s[12:13], 0, v[142:143]
	global_load_dwordx4 v[170:173], v[170:171], off
	v_lshl_add_u64 v[142:143], v[142:143], 0, v[128:129]
	global_load_dwordx4 v[174:177], v[174:175], off
	v_readlane_b32 s2, v251, 1
	global_load_dwordx4 v[178:181], v[178:179], off
	v_readlane_b32 s3, v251, 2
	s_waitcnt vmcnt(15)
	v_lshlrev_b32_e32 v202, 16, v184
	v_and_b32_e32 v203, 0xffff0000, v184
	v_lshlrev_b32_e32 v184, 16, v185
	v_and_b32_e32 v185, 0xffff0000, v185
	s_waitcnt vmcnt(14)
	v_lshlrev_b32_e32 v204, 16, v186
	v_and_b32_e32 v205, 0xffff0000, v186
	v_lshlrev_b32_e32 v186, 16, v187
	v_and_b32_e32 v187, 0xffff0000, v187
	s_waitcnt vmcnt(13)
	v_lshlrev_b32_e32 v206, 16, v188
	v_and_b32_e32 v207, 0xffff0000, v188
	v_lshlrev_b32_e32 v188, 16, v189
	v_and_b32_e32 v189, 0xffff0000, v189
	s_waitcnt vmcnt(12)
	v_lshlrev_b32_e32 v208, 16, v190
	v_and_b32_e32 v209, 0xffff0000, v190
	v_lshlrev_b32_e32 v190, 16, v191
	v_and_b32_e32 v191, 0xffff0000, v191
	s_waitcnt vmcnt(11)
	v_lshlrev_b32_e32 v210, 16, v194
	v_and_b32_e32 v211, 0xffff0000, v194
	v_lshlrev_b32_e32 v194, 16, v195
	v_and_b32_e32 v195, 0xffff0000, v195
	s_waitcnt vmcnt(10)
	v_lshlrev_b32_e32 v212, 16, v196
	v_and_b32_e32 v213, 0xffff0000, v196
	v_lshlrev_b32_e32 v196, 16, v197
	v_and_b32_e32 v197, 0xffff0000, v197
	s_waitcnt vmcnt(8)
	v_lshlrev_b32_e32 v216, 16, v200
	v_and_b32_e32 v217, 0xffff0000, v200
	v_lshlrev_b32_e32 v200, 16, v201
	v_and_b32_e32 v201, 0xffff0000, v201
	v_lshlrev_b32_e32 v214, 16, v198
	v_and_b32_e32 v215, 0xffff0000, v198
	v_lshlrev_b32_e32 v198, 16, v199
	v_and_b32_e32 v199, 0xffff0000, v199
	s_waitcnt vmcnt(7)
	v_pk_fma_f32 v[112:113], v[112:113], v[150:151], v[202:203]
	v_pk_fma_f32 v[114:115], v[114:115], v[152:153], v[184:185]
	s_waitcnt vmcnt(6)
	v_pk_fma_f32 v[108:109], v[108:109], v[154:155], v[204:205]
	v_pk_fma_f32 v[110:111], v[110:111], v[156:157], v[186:187]
	v_cvt_pk_bf16_f32 v112, v112, v113
	v_cvt_pk_bf16_f32 v113, v114, v115
	v_cvt_pk_bf16_f32 v108, v108, v109
	v_cvt_pk_bf16_f32 v109, v110, v111
	s_waitcnt vmcnt(5)
	v_pk_fma_f32 v[110:111], v[124:125], v[158:159], v[206:207]
	v_pk_fma_f32 v[114:115], v[126:127], v[160:161], v[188:189]
	v_cvt_pk_bf16_f32 v110, v110, v111
	v_cvt_pk_bf16_f32 v111, v114, v115
	s_waitcnt vmcnt(4)
	v_pk_fma_f32 v[114:115], v[120:121], v[162:163], v[208:209]
	v_pk_fma_f32 v[120:121], v[122:123], v[164:165], v[190:191]
	v_cvt_pk_bf16_f32 v114, v114, v115
	v_cvt_pk_bf16_f32 v115, v120, v121
	v_lshl_add_u64 v[120:121], s[12:13], 0, v[192:193]
	s_waitcnt vmcnt(3)
	v_pk_fma_f32 v[104:105], v[104:105], v[166:167], v[210:211]
	v_pk_fma_f32 v[106:107], v[106:107], v[168:169], v[194:195]
	s_waitcnt vmcnt(2)
	v_pk_fma_f32 v[100:101], v[100:101], v[170:171], v[212:213]
	v_pk_fma_f32 v[102:103], v[102:103], v[172:173], v[196:197]
	s_waitcnt vmcnt(0)
; DI float4 ldnt4(const float* p) { const f32x4 v = __builtin_nontemporal_load((const f32x4*)p); float4 r; r.x = v[0]; r.y = v[1]; r.z = v[2]; r.w = v[3]; return r; }
; DI void st_bf4(bf16_t* p, float a, float b, float c, float d) { uint2 v; v.x = pack2(a, b); v.y = pack2(c, d); *(uint2*)p = v; }
; DI void phase_gout(const Params& p, const Sub& s, char* lds_all, int layer, const bf16_t* A, const bf16_t* Bt) {
;     ...
;       [&](int row, int col) {
;         const bf16_t* x1b = (const bf16_t*)p.out;
;         float4 x4;
;         if (layer == 0) x4 = ldnt4(xrow(p, row) + col);
;         else ld_bf4(x1b + (size_t)row * D + col, x4.x, x4.y, x4.z, x4.w);
;         Ld2 r; r.a = x4; r.b = *(const float4*)(mod + (size_t)(row_bi(row) * 2 + layer) * 3072 + 2048 + col);
;         return r;
;       },
;       [&](int row, int col, f32x4 v, const Ld2& l2) {
;         const float4 x4 = l2.a, g4 = l2.b;
;         bf16_t* x1b = (bf16_t*)p.out;
;         bf16_t* x2b = (bf16_t*)(p.ws + W_SLOT3);
;         st_bf4((layer == 0 ? x1b : x2b) + (size_t)row * D + col, x4.x + g4.x * v[0], x4.y + g4.y * v[1], x4.z + g4.z * v[2], x4.w + g4.w * v[3]);
;       });
	v_pk_fma_f32 v[96:97], v[96:97], v[178:179], v[216:217]
	v_pk_fma_f32 v[98:99], v[98:99], v[180:181], v[200:201]
	v_lshl_add_u64 v[120:121], v[120:121], 0, v[128:129]
	v_cvt_pk_bf16_f32 v104, v104, v105
	v_cvt_pk_bf16_f32 v105, v106, v107
	v_cvt_pk_bf16_f32 v100, v100, v101
	v_cvt_pk_bf16_f32 v101, v102, v103
	v_pk_fma_f32 v[102:103], v[116:117], v[174:175], v[214:215]
	v_pk_fma_f32 v[106:107], v[118:119], v[176:177], v[198:199]
	v_cvt_pk_bf16_f32 v96, v96, v97
	v_cvt_pk_bf16_f32 v97, v98, v99
	v_cvt_pk_bf16_f32 v102, v102, v103
	v_cvt_pk_bf16_f32 v103, v106, v107
	global_store_dwordx2 v[142:143], v[112:113], off
	global_store_dwordx2 v[142:143], v[108:109], off offset:32
	global_store_dwordx2 v[142:143], v[110:111], off offset:256
	global_store_dwordx2 v[142:143], v[114:115], off offset:288
	global_store_dwordx2 v[120:121], v[104:105], off
	global_store_dwordx2 v[120:121], v[100:101], off offset:32
	global_store_dwordx2 v[120:121], v[102:103], off offset:256
	global_store_dwordx2 v[120:121], v[96:97], off offset:288
	v_or_b32_e32 v96, 32, v130
	v_ashrrev_i32_e32 v97, 31, v96
	v_lshlrev_b64 v[142:143], 11, v[96:97]
	v_add_u32_e32 v97, 0xffff0020, v130
	v_lshrrev_b32_e32 v97, 4, v97
	v_add_u32_e32 v97, 8, v97
	v_cmp_gt_i32_e32 vcc, s44, v96
	v_or_b32_e32 v108, 48, v130
	v_ashrrev_i32_e32 v109, 31, v108
	v_cndmask_b32_e32 v96, v97, v131, vcc
	v_lshl_or_b32 v96, v96, 1, 1
	v_mad_i64_i32 v[96:97], s[0:1], v96, s53, v[132:133]
	v_lshl_add_u64 v[104:105], v[96:97], 0, s[36:37]
	v_lshl_add_u64 v[96:97], v[104:105], 0, v[140:141]
	v_lshl_add_u64 v[100:101], v[104:105], 0, v[138:139]
	v_lshl_add_u64 v[106:107], v[104:105], 0, v[134:135]
	v_lshl_add_u64 v[110:111], v[104:105], 0, v[136:137]
	v_add_u32_e32 v104, 0xffff0030, v130
	v_lshl_add_u64 v[98:99], s[4:5], 0, v[142:143]
	v_lshlrev_b64 v[158:159], 11, v[108:109]
	v_lshrrev_b32_e32 v109, 4, v104
	v_lshl_add_u64 v[98:99], v[98:99], 0, v[128:129]
	v_add_u32_e32 v109, 8, v109
	v_cmp_gt_i32_e32 vcc, s44, v108
	global_load_dwordx2 v[150:151], v[98:99], off
	global_load_dwordx2 v[152:153], v[98:99], off offset:32
	global_load_dwordx2 v[154:155], v[98:99], off offset:256
	global_load_dwordx2 v[156:157], v[98:99], off offset:288
	v_lshl_add_u64 v[98:99], s[4:5], 0, v[158:159]
	v_cndmask_b32_e32 v112, v109, v131, vcc
	v_lshl_add_u64 v[98:99], v[98:99], 0, v[128:129]
	v_lshl_or_b32 v112, v112, 1, 1
	global_load_dwordx2 v[160:161], v[98:99], off
	global_load_dwordx2 v[162:163], v[98:99], off offset:32
	global_load_dwordx2 v[164:165], v[98:99], off offset:256
	global_load_dwordx2 v[166:167], v[98:99], off offset:288
	v_mad_i64_i32 v[112:113], s[0:1], v112, s53, v[132:133]
	global_load_dwordx4 v[96:99], v[96:97], off
	v_lshl_add_u64 v[124:125], v[112:113], 0, s[36:37]
	global_load_dwordx4 v[100:103], v[100:101], off
	v_lshl_add_u64 v[112:113], v[124:125], 0, v[140:141]
	global_load_dwordx4 v[104:107], v[106:107], off
	v_lshl_add_u64 v[116:117], v[124:125], 0, v[138:139]
	global_load_dwordx4 v[108:111], v[110:111], off
	v_lshl_add_u64 v[120:121], v[124:125], 0, v[134:135]
	v_lshl_add_u64 v[124:125], v[124:125], 0, v[136:137]
	global_load_dwordx4 v[112:115], v[112:113], off
	v_lshl_add_u64 v[142:143], s[12:13], 0, v[142:143]
	global_load_dwordx4 v[116:119], v[116:117], off
	v_lshl_add_u64 v[142:143], v[142:143], 0, v[128:129]
	global_load_dwordx4 v[120:123], v[120:121], off
	s_waitcnt vmcnt(14)
	v_lshlrev_b32_e32 v168, 16, v150
	global_load_dwordx4 v[124:127], v[124:125], off
	v_and_b32_e32 v169, 0xffff0000, v150
	v_lshlrev_b32_e32 v150, 16, v151
	v_and_b32_e32 v151, 0xffff0000, v151
	s_waitcnt vmcnt(14)
	v_lshlrev_b32_e32 v170, 16, v152
	v_and_b32_e32 v171, 0xffff0000, v152
	v_lshlrev_b32_e32 v152, 16, v153
	v_and_b32_e32 v153, 0xffff0000, v153
	s_waitcnt vmcnt(13)
	v_lshlrev_b32_e32 v172, 16, v154
	v_and_b32_e32 v173, 0xffff0000, v154
	v_lshlrev_b32_e32 v154, 16, v155
	v_and_b32_e32 v155, 0xffff0000, v155
	s_waitcnt vmcnt(7)
	v_pk_fma_f32 v[80:81], v[80:81], v[96:97], v[168:169]
	v_pk_fma_f32 v[82:83], v[82:83], v[98:99], v[150:151]
	s_waitcnt vmcnt(6)
	v_pk_fma_f32 v[76:77], v[76:77], v[100:101], v[170:171]
	v_pk_fma_f32 v[78:79], v[78:79], v[102:103], v[152:153]
	v_lshlrev_b32_e32 v174, 16, v156
	v_and_b32_e32 v175, 0xffff0000, v156
	v_lshlrev_b32_e32 v156, 16, v157
	v_and_b32_e32 v157, 0xffff0000, v157
	v_cvt_pk_bf16_f32 v80, v80, v81
	v_cvt_pk_bf16_f32 v81, v82, v83
	v_cvt_pk_bf16_f32 v76, v76, v77
	v_cvt_pk_bf16_f32 v77, v78, v79
	s_waitcnt vmcnt(5)
	v_pk_fma_f32 v[78:79], v[92:93], v[104:105], v[172:173]
	v_pk_fma_f32 v[82:83], v[94:95], v[106:107], v[154:155]
	v_lshlrev_b32_e32 v176, 16, v160
	v_and_b32_e32 v177, 0xffff0000, v160
	v_lshlrev_b32_e32 v160, 16, v161
	v_and_b32_e32 v161, 0xffff0000, v161
	v_lshlrev_b32_e32 v178, 16, v162
	v_and_b32_e32 v179, 0xffff0000, v162
	v_lshlrev_b32_e32 v162, 16, v163
	v_and_b32_e32 v163, 0xffff0000, v163
	v_lshlrev_b32_e32 v184, 16, v166
	v_and_b32_e32 v185, 0xffff0000, v166
	v_lshlrev_b32_e32 v166, 16, v167
	v_and_b32_e32 v167, 0xffff0000, v167
	v_cvt_pk_bf16_f32 v78, v78, v79
	v_cvt_pk_bf16_f32 v79, v82, v83
	s_waitcnt vmcnt(4)
	v_pk_fma_f32 v[82:83], v[88:89], v[108:109], v[174:175]
	v_pk_fma_f32 v[88:89], v[90:91], v[110:111], v[156:157]
	v_lshlrev_b32_e32 v180, 16, v164
	v_and_b32_e32 v181, 0xffff0000, v164
	v_lshlrev_b32_e32 v164, 16, v165
	v_and_b32_e32 v165, 0xffff0000, v165
	v_cvt_pk_bf16_f32 v82, v82, v83
	v_cvt_pk_bf16_f32 v83, v88, v89
	v_lshl_add_u64 v[88:89], s[12:13], 0, v[158:159]
	s_waitcnt vmcnt(3)
	v_pk_fma_f32 v[72:73], v[72:73], v[112:113], v[176:177]
	v_pk_fma_f32 v[74:75], v[74:75], v[114:115], v[160:161]
	s_waitcnt vmcnt(2)
; DI float4 ldnt4(const float* p) { const f32x4 v = __builtin_nontemporal_load((const f32x4*)p); float4 r; r.x = v[0]; r.y = v[1]; r.z = v[2]; r.w = v[3]; return r; }
; DI void st_bf4(bf16_t* p, float a, float b, float c, float d) { uint2 v; v.x = pack2(a, b); v.y = pack2(c, d); *(uint2*)p = v; }
; DI void phase_gout(const Params& p, const Sub& s, char* lds_all, int layer, const bf16_t* A, const bf16_t* Bt) {
;     ...
;       [&](int row, int col) {
;         const bf16_t* x1b = (const bf16_t*)p.out;
;         float4 x4;
;         if (layer == 0) x4 = ldnt4(xrow(p, row) + col);
;         else ld_bf4(x1b + (size_t)row * D + col, x4.x, x4.y, x4.z, x4.w);
;         Ld2 r; r.a = x4; r.b = *(const float4*)(mod + (size_t)(row_bi(row) * 2 + layer) * 3072 + 2048 + col);
;         return r;
;       },
;       [&](int row, int col, f32x4 v, const Ld2& l2) {
;         const float4 x4 = l2.a, g4 = l2.b;
;         bf16_t* x1b = (bf16_t*)p.out;
;         bf16_t* x2b = (bf16_t*)(p.ws + W_SLOT3);
;         st_bf4((layer == 0 ? x1b : x2b) + (size_t)row * D + col, x4.x + g4.x * v[0], x4.y + g4.y * v[1], x4.z + g4.z * v[2], x4.w + g4.w * v[3]);
;       });
	v_pk_fma_f32 v[68:69], v[68:69], v[116:117], v[178:179]
	v_pk_fma_f32 v[70:71], v[70:71], v[118:119], v[162:163]
	v_lshl_add_u64 v[88:89], v[88:89], 0, v[128:129]
	v_cvt_pk_bf16_f32 v72, v72, v73
	v_cvt_pk_bf16_f32 v73, v74, v75
	v_cvt_pk_bf16_f32 v68, v68, v69
	v_cvt_pk_bf16_f32 v69, v70, v71
	s_waitcnt vmcnt(1)
	v_pk_fma_f32 v[70:71], v[84:85], v[120:121], v[180:181]
	v_pk_fma_f32 v[74:75], v[86:87], v[122:123], v[164:165]
	v_cvt_pk_bf16_f32 v70, v70, v71
	v_cvt_pk_bf16_f32 v71, v74, v75
	global_store_dwordx2 v[142:143], v[80:81], off
	global_store_dwordx2 v[142:143], v[76:77], off offset:32
	global_store_dwordx2 v[142:143], v[78:79], off offset:256
	global_store_dwordx2 v[142:143], v[82:83], off offset:288
	global_store_dwordx2 v[88:89], v[72:73], off
	global_store_dwordx2 v[88:89], v[68:69], off offset:32
	global_store_dwordx2 v[88:89], v[70:71], off offset:256
	v_add_u32_e32 v68, 0xffff0080, v130
	v_lshrrev_b32_e32 v68, 4, v68
	v_add_u32_e32 v68, 8, v68
	v_add_u32_e32 v76, 0x90, v130
	v_add_u32_e32 v74, 0xffff0090, v130
	v_ashrrev_i32_e32 v77, 31, v76
	v_lshrrev_b32_e32 v80, 4, v74
	v_lshlrev_b64 v[106:107], 11, v[76:77]
	v_ashrrev_i32_e32 v77, 13, v76
	v_add_u32_e32 v80, 8, v80
	s_waitcnt vmcnt(7)
	v_pk_fma_f32 v[64:65], v[64:65], v[124:125], v[184:185]
	v_pk_fma_f32 v[66:67], v[66:67], v[126:127], v[166:167]
	v_cvt_pk_bf16_f32 v64, v64, v65
	v_cvt_pk_bf16_f32 v65, v66, v67
	global_store_dwordx2 v[88:89], v[64:65], off offset:288
	v_add_u32_e32 v64, 0x80, v130
	v_ashrrev_i32_e32 v65, 31, v64
	v_lshlrev_b64 v[96:97], 11, v[64:65]
	v_ashrrev_i32_e32 v65, 13, v64
	v_cmp_gt_i32_e32 vcc, s44, v64
	v_lshl_add_u64 v[66:67], s[4:5], 0, v[96:97]
	v_lshl_add_u64 v[66:67], v[66:67], 0, v[128:129]
	v_cndmask_b32_e32 v64, v68, v65, vcc
	v_lshl_or_b32 v64, v64, 1, 1
	v_mad_i64_i32 v[64:65], s[0:1], v64, s53, v[132:133]
	v_cmp_gt_i32_e32 vcc, s44, v76
	global_load_dwordx2 v[98:99], v[66:67], off
	global_load_dwordx2 v[100:101], v[66:67], off offset:32
	global_load_dwordx2 v[102:103], v[66:67], off offset:256
	global_load_dwordx2 v[104:105], v[66:67], off offset:288
	v_lshl_add_u64 v[66:67], s[4:5], 0, v[106:107]
	v_lshl_add_u64 v[68:69], v[64:65], 0, s[36:37]
	v_cndmask_b32_e32 v80, v80, v77, vcc
	v_lshl_add_u64 v[66:67], v[66:67], 0, v[128:129]
	v_lshl_add_u64 v[64:65], v[68:69], 0, v[140:141]
	v_lshl_add_u64 v[70:71], v[68:69], 0, v[138:139]
	v_lshl_or_b32 v80, v80, 1, 1
	global_load_dwordx2 v[108:109], v[66:67], off
	global_load_dwordx2 v[110:111], v[66:67], off offset:32
	global_load_dwordx2 v[112:113], v[66:67], off offset:256
	global_load_dwordx2 v[114:115], v[66:67], off offset:288
	v_lshl_add_u64 v[72:73], v[68:69], 0, v[134:135]
	global_load_dwordx4 v[64:67], v[64:65], off
	v_lshl_add_u64 v[78:79], v[68:69], 0, v[136:137]
	global_load_dwordx4 v[68:71], v[70:71], off
	v_mad_i64_i32 v[80:81], s[0:1], v80, s53, v[132:133]
	global_load_dwordx4 v[72:75], v[72:73], off
	v_lshl_add_u64 v[92:93], v[80:81], 0, s[36:37]
	global_load_dwordx4 v[76:79], v[78:79], off
	v_lshl_add_u64 v[80:81], v[92:93], 0, v[140:141]
	v_lshl_add_u64 v[84:85], v[92:93], 0, v[138:139]
	v_lshl_add_u64 v[88:89], v[92:93], 0, v[134:135]
	v_lshl_add_u64 v[92:93], v[92:93], 0, v[136:137]
	global_load_dwordx4 v[80:83], v[80:81], off
	v_lshl_add_u64 v[96:97], s[12:13], 0, v[96:97]
	global_load_dwordx4 v[84:87], v[84:85], off
	v_lshl_add_u64 v[96:97], v[96:97], 0, v[128:129]
	global_load_dwordx4 v[88:91], v[88:89], off
	s_waitcnt vmcnt(14)
	v_lshlrev_b32_e32 v116, 16, v98
	global_load_dwordx4 v[92:95], v[92:93], off
	v_and_b32_e32 v117, 0xffff0000, v98
	v_lshlrev_b32_e32 v98, 16, v99
	v_and_b32_e32 v99, 0xffff0000, v99
	s_waitcnt vmcnt(14)
	v_lshlrev_b32_e32 v118, 16, v100
	v_and_b32_e32 v119, 0xffff0000, v100
	v_lshlrev_b32_e32 v100, 16, v101
	v_and_b32_e32 v101, 0xffff0000, v101
	s_waitcnt vmcnt(13)
	v_lshlrev_b32_e32 v120, 16, v102
	v_and_b32_e32 v121, 0xffff0000, v102
	v_lshlrev_b32_e32 v102, 16, v103
	v_and_b32_e32 v103, 0xffff0000, v103
	s_waitcnt vmcnt(12)
	v_lshlrev_b32_e32 v122, 16, v104
	v_and_b32_e32 v123, 0xffff0000, v104
	s_waitcnt vmcnt(7)
	v_pk_fma_f32 v[52:53], v[52:53], v[64:65], v[116:117]
	v_pk_fma_f32 v[54:55], v[54:55], v[66:67], v[98:99]
	s_waitcnt vmcnt(6)
	v_pk_fma_f32 v[48:49], v[48:49], v[68:69], v[118:119]
	v_pk_fma_f32 v[50:51], v[50:51], v[70:71], v[100:101]
	v_lshlrev_b32_e32 v104, 16, v105
	v_and_b32_e32 v105, 0xffff0000, v105
	v_cvt_pk_bf16_f32 v52, v52, v53
	v_cvt_pk_bf16_f32 v53, v54, v55
	v_cvt_pk_bf16_f32 v48, v48, v49
	v_cvt_pk_bf16_f32 v49, v50, v51
	s_waitcnt vmcnt(5)
	v_pk_fma_f32 v[50:51], v[60:61], v[72:73], v[120:121]
	v_pk_fma_f32 v[54:55], v[62:63], v[74:75], v[102:103]
	v_lshlrev_b32_e32 v124, 16, v108
	v_and_b32_e32 v125, 0xffff0000, v108
	v_lshlrev_b32_e32 v108, 16, v109
	v_and_b32_e32 v109, 0xffff0000, v109
	v_lshlrev_b32_e32 v126, 16, v110
	v_and_b32_e32 v127, 0xffff0000, v110
	v_lshlrev_b32_e32 v110, 16, v111
	v_and_b32_e32 v111, 0xffff0000, v111
	v_lshlrev_b32_e32 v150, 16, v114
	v_and_b32_e32 v151, 0xffff0000, v114
	v_lshlrev_b32_e32 v114, 16, v115
	v_and_b32_e32 v115, 0xffff0000, v115
	v_cvt_pk_bf16_f32 v50, v50, v51
	v_cvt_pk_bf16_f32 v51, v54, v55
	s_waitcnt vmcnt(4)
	v_pk_fma_f32 v[54:55], v[56:57], v[76:77], v[122:123]
	v_pk_fma_f32 v[56:57], v[58:59], v[78:79], v[104:105]
	v_lshlrev_b32_e32 v142, 16, v112
	v_and_b32_e32 v143, 0xffff0000, v112
	v_lshlrev_b32_e32 v112, 16, v113
	v_and_b32_e32 v113, 0xffff0000, v113
	v_cvt_pk_bf16_f32 v54, v54, v55
	v_cvt_pk_bf16_f32 v55, v56, v57
	v_lshl_add_u64 v[56:57], s[12:13], 0, v[106:107]
	s_waitcnt vmcnt(3)
	v_pk_fma_f32 v[40:41], v[40:41], v[80:81], v[124:125]
	v_pk_fma_f32 v[42:43], v[42:43], v[82:83], v[108:109]
	s_waitcnt vmcnt(2)
; DI float4 ldnt4(const float* p) { const f32x4 v = __builtin_nontemporal_load((const f32x4*)p); float4 r; r.x = v[0]; r.y = v[1]; r.z = v[2]; r.w = v[3]; return r; }
; DI void st_bf4(bf16_t* p, float a, float b, float c, float d) { uint2 v; v.x = pack2(a, b); v.y = pack2(c, d); *(uint2*)p = v; }
; template <class FL, class FS>
; DI void gemm8_tile(char* shmc, const bf16_t* __restrict__ A, const bf16_t* __restrict__ Bt, const int K, const int brow, const int bcol, FL fl, FS fs) {
;     ...
;   asm volatile("s_waitcnt vmcnt(0)" ::: "memory");
;   __syncthreads();
; DI void phase_gout(const Params& p, const Sub& s, char* lds_all, int layer, const bf16_t* A, const bf16_t* Bt) {
;     ...
;       [&](int row, int col) {
;         const bf16_t* x1b = (const bf16_t*)p.out;
;         float4 x4;
;         if (layer == 0) x4 = ldnt4(xrow(p, row) + col);
;         else ld_bf4(x1b + (size_t)row * D + col, x4.x, x4.y, x4.z, x4.w);
;         Ld2 r; r.a = x4; r.b = *(const float4*)(mod + (size_t)(row_bi(row) * 2 + layer) * 3072 + 2048 + col);
;         return r;
;       },
;       [&](int row, int col, f32x4 v, const Ld2& l2) {
;         const float4 x4 = l2.a, g4 = l2.b;
;         bf16_t* x1b = (bf16_t*)p.out;
;         bf16_t* x2b = (bf16_t*)(p.ws + W_SLOT3);
;         st_bf4((layer == 0 ? x1b : x2b) + (size_t)row * D + col, x4.x + g4.x * v[0], x4.y + g4.y * v[1], x4.z + g4.z * v[2], x4.w + g4.w * v[3]);
;       });
	v_pk_fma_f32 v[36:37], v[36:37], v[84:85], v[126:127]
	v_pk_fma_f32 v[38:39], v[38:39], v[86:87], v[110:111]
	v_lshl_add_u64 v[56:57], v[56:57], 0, v[128:129]
	v_cvt_pk_bf16_f32 v40, v40, v41
	v_cvt_pk_bf16_f32 v41, v42, v43
	v_cvt_pk_bf16_f32 v36, v36, v37
	v_cvt_pk_bf16_f32 v37, v38, v39
	s_waitcnt vmcnt(1)
	v_pk_fma_f32 v[38:39], v[44:45], v[88:89], v[142:143]
	v_pk_fma_f32 v[42:43], v[46:47], v[90:91], v[112:113]
	v_cvt_pk_bf16_f32 v38, v38, v39
	v_cvt_pk_bf16_f32 v39, v42, v43
	global_store_dwordx2 v[96:97], v[52:53], off
	global_store_dwordx2 v[96:97], v[48:49], off offset:32
	global_store_dwordx2 v[96:97], v[50:51], off offset:256
	global_store_dwordx2 v[96:97], v[54:55], off offset:288
	global_store_dwordx2 v[56:57], v[40:41], off
	global_store_dwordx2 v[56:57], v[36:37], off offset:32
	global_store_dwordx2 v[56:57], v[38:39], off offset:256
	v_add_u32_e32 v36, 0xffff00a0, v130
	v_lshrrev_b32_e32 v36, 4, v36
	v_add_u32_e32 v36, 8, v36
	v_add_u32_e32 v44, 0xb0, v130
	v_add_u32_e32 v42, 0xffff00b0, v130
	v_ashrrev_i32_e32 v45, 31, v44
	v_lshrrev_b32_e32 v48, 4, v42
	v_lshlrev_b64 v[74:75], 11, v[44:45]
	v_ashrrev_i32_e32 v45, 13, v44
	v_add_u32_e32 v48, 8, v48
	s_waitcnt vmcnt(7)
	v_pk_fma_f32 v[32:33], v[32:33], v[92:93], v[150:151]
	v_pk_fma_f32 v[34:35], v[34:35], v[94:95], v[114:115]
	v_cvt_pk_bf16_f32 v32, v32, v33
	v_cvt_pk_bf16_f32 v33, v34, v35
	global_store_dwordx2 v[56:57], v[32:33], off offset:288
	v_add_u32_e32 v32, 0xa0, v130
	v_ashrrev_i32_e32 v33, 31, v32
	v_lshlrev_b64 v[64:65], 11, v[32:33]
	v_ashrrev_i32_e32 v33, 13, v32
	v_cmp_gt_i32_e32 vcc, s44, v32
	v_lshl_add_u64 v[34:35], s[4:5], 0, v[64:65]
	v_lshl_add_u64 v[34:35], v[34:35], 0, v[128:129]
	v_cndmask_b32_e32 v32, v36, v33, vcc
	v_lshl_or_b32 v32, v32, 1, 1
	v_mad_i64_i32 v[32:33], s[0:1], v32, s53, v[132:133]
	v_cmp_gt_i32_e32 vcc, s44, v44
	global_load_dwordx2 v[66:67], v[34:35], off
	global_load_dwordx2 v[68:69], v[34:35], off offset:32
	global_load_dwordx2 v[70:71], v[34:35], off offset:256
	global_load_dwordx2 v[72:73], v[34:35], off offset:288
	v_lshl_add_u64 v[34:35], s[4:5], 0, v[74:75]
	v_lshl_add_u64 v[36:37], v[32:33], 0, s[36:37]
	v_cndmask_b32_e32 v48, v48, v45, vcc
	v_lshl_add_u64 v[34:35], v[34:35], 0, v[128:129]
	v_lshl_add_u64 v[32:33], v[36:37], 0, v[140:141]
	v_lshl_add_u64 v[38:39], v[36:37], 0, v[138:139]
	v_lshl_or_b32 v48, v48, 1, 1
	global_load_dwordx2 v[76:77], v[34:35], off
	global_load_dwordx2 v[78:79], v[34:35], off offset:32
	global_load_dwordx2 v[80:81], v[34:35], off offset:256
	global_load_dwordx2 v[82:83], v[34:35], off offset:288
	v_lshl_add_u64 v[40:41], v[36:37], 0, v[134:135]
	global_load_dwordx4 v[32:35], v[32:33], off
	v_lshl_add_u64 v[46:47], v[36:37], 0, v[136:137]
	global_load_dwordx4 v[36:39], v[38:39], off
	v_mad_i64_i32 v[48:49], s[0:1], v48, s53, v[132:133]
	global_load_dwordx4 v[40:43], v[40:41], off
	v_lshl_add_u64 v[60:61], v[48:49], 0, s[36:37]
	global_load_dwordx4 v[44:47], v[46:47], off
	v_lshl_add_u64 v[48:49], v[60:61], 0, v[140:141]
	v_lshl_add_u64 v[52:53], v[60:61], 0, v[138:139]
	v_lshl_add_u64 v[56:57], v[60:61], 0, v[134:135]
	v_lshl_add_u64 v[60:61], v[60:61], 0, v[136:137]
	global_load_dwordx4 v[48:51], v[48:49], off
	v_lshl_add_u64 v[64:65], s[12:13], 0, v[64:65]
	global_load_dwordx4 v[52:55], v[52:53], off
	v_lshl_add_u64 v[64:65], v[64:65], 0, v[128:129]
	global_load_dwordx4 v[56:59], v[56:57], off
	s_add_i32 s1, s56, s2
	global_load_dwordx4 v[60:63], v[60:61], off
	s_cmpk_lt_i32 s1, 0x400
	s_waitcnt vmcnt(15)
	v_lshlrev_b32_e32 v84, 16, v66
	v_and_b32_e32 v85, 0xffff0000, v66
	v_lshlrev_b32_e32 v66, 16, v67
	v_and_b32_e32 v67, 0xffff0000, v67
	s_waitcnt vmcnt(14)
	v_lshlrev_b32_e32 v86, 16, v68
	v_and_b32_e32 v87, 0xffff0000, v68
	v_lshlrev_b32_e32 v68, 16, v69
	v_and_b32_e32 v69, 0xffff0000, v69
	s_waitcnt vmcnt(13)
	v_lshlrev_b32_e32 v88, 16, v70
	v_and_b32_e32 v89, 0xffff0000, v70
	v_lshlrev_b32_e32 v70, 16, v71
	v_and_b32_e32 v71, 0xffff0000, v71
	s_waitcnt vmcnt(12)
	v_lshlrev_b32_e32 v90, 16, v72
	v_and_b32_e32 v91, 0xffff0000, v72
	v_lshlrev_b32_e32 v72, 16, v73
	s_waitcnt vmcnt(7)
	v_pk_fma_f32 v[20:21], v[20:21], v[32:33], v[84:85]
	v_pk_fma_f32 v[22:23], v[22:23], v[34:35], v[66:67]
	s_waitcnt vmcnt(6)
	v_pk_fma_f32 v[16:17], v[16:17], v[36:37], v[86:87]
	v_pk_fma_f32 v[18:19], v[18:19], v[38:39], v[68:69]
	v_and_b32_e32 v73, 0xffff0000, v73
	v_cvt_pk_bf16_f32 v20, v20, v21
	v_cvt_pk_bf16_f32 v21, v22, v23
	v_cvt_pk_bf16_f32 v16, v16, v17
	v_cvt_pk_bf16_f32 v17, v18, v19
	s_waitcnt vmcnt(5)
	v_pk_fma_f32 v[18:19], v[28:29], v[40:41], v[88:89]
	v_pk_fma_f32 v[22:23], v[30:31], v[42:43], v[70:71]
	v_lshlrev_b32_e32 v92, 16, v76
	v_and_b32_e32 v93, 0xffff0000, v76
	v_lshlrev_b32_e32 v76, 16, v77
	v_and_b32_e32 v77, 0xffff0000, v77
	v_lshlrev_b32_e32 v94, 16, v78
	v_and_b32_e32 v95, 0xffff0000, v78
	v_lshlrev_b32_e32 v78, 16, v79
	v_and_b32_e32 v79, 0xffff0000, v79
	v_lshlrev_b32_e32 v98, 16, v82
	v_and_b32_e32 v99, 0xffff0000, v82
	v_lshlrev_b32_e32 v82, 16, v83
	v_and_b32_e32 v83, 0xffff0000, v83
	v_cvt_pk_bf16_f32 v18, v18, v19
	v_cvt_pk_bf16_f32 v19, v22, v23
	s_waitcnt vmcnt(4)
	v_pk_fma_f32 v[22:23], v[24:25], v[44:45], v[90:91]
	v_pk_fma_f32 v[24:25], v[26:27], v[46:47], v[72:73]
	v_lshlrev_b32_e32 v96, 16, v80
	v_and_b32_e32 v97, 0xffff0000, v80
	v_lshlrev_b32_e32 v80, 16, v81
	v_and_b32_e32 v81, 0xffff0000, v81
	v_cvt_pk_bf16_f32 v22, v22, v23
	v_cvt_pk_bf16_f32 v23, v24, v25
	v_lshl_add_u64 v[24:25], s[12:13], 0, v[74:75]
	s_waitcnt vmcnt(3)
	v_pk_fma_f32 v[8:9], v[8:9], v[48:49], v[92:93]
	v_pk_fma_f32 v[10:11], v[10:11], v[50:51], v[76:77]
	s_waitcnt vmcnt(2)
	v_pk_fma_f32 v[4:5], v[4:5], v[52:53], v[94:95]
	v_pk_fma_f32 v[6:7], v[6:7], v[54:55], v[78:79]
	s_waitcnt vmcnt(0)
	v_pk_fma_f32 v[0:1], v[0:1], v[60:61], v[98:99]
	v_pk_fma_f32 v[2:3], v[2:3], v[62:63], v[82:83]
	v_lshl_add_u64 v[24:25], v[24:25], 0, v[128:129]
	v_cvt_pk_bf16_f32 v8, v8, v9
	v_cvt_pk_bf16_f32 v9, v10, v11
	v_cvt_pk_bf16_f32 v4, v4, v5
	v_cvt_pk_bf16_f32 v5, v6, v7
	v_pk_fma_f32 v[6:7], v[12:13], v[56:57], v[96:97]
	v_pk_fma_f32 v[10:11], v[14:15], v[58:59], v[80:81]
	v_cvt_pk_bf16_f32 v0, v0, v1
	v_cvt_pk_bf16_f32 v1, v2, v3
	v_cvt_pk_bf16_f32 v6, v6, v7
	v_cvt_pk_bf16_f32 v7, v10, v11
	global_store_dwordx2 v[64:65], v[20:21], off
	global_store_dwordx2 v[64:65], v[16:17], off offset:32
	global_store_dwordx2 v[64:65], v[18:19], off offset:256
	global_store_dwordx2 v[64:65], v[22:23], off offset:288
	global_store_dwordx2 v[24:25], v[8:9], off
	global_store_dwordx2 v[24:25], v[4:5], off offset:32
	global_store_dwordx2 v[24:25], v[6:7], off offset:256
	global_store_dwordx2 v[24:25], v[0:1], off offset:288
	s_barrier
	s_cbranch_scc0 .LBB0_2095
